# 4-phase loops with balanced LDS-DMA issue (2,4,4,6 pieces per load segment instead of 2,6,2,6; waits vmcnt(6)/(8)/(6))
# speedup vs baseline: 1.0028x; 1.0028x over previous
.LBB0_566:
	s_ashr_i32 s9, s8, 31
	v_cmp_lt_i64_e32 vcc, s[10:11], v[144:145]
	s_lshl_b64 s[10:11], s[8:9], 19
	s_add_u32 s10, s40, s10
	s_addc_u32 s11, s41, s11
	s_and_b64 s[12:13], vcc, exec
	s_cselect_b32 s9, s11, s17
	s_cselect_b32 s75, s10, s16
	s_ashr_i32 s7, s6, 31
	s_lshl_b64 s[12:13], s[6:7], 19
	s_add_u32 s12, s48, s12
	s_addc_u32 s13, s49, s13
	s_and_b64 s[18:19], vcc, exec
	s_cselect_b32 s7, s13, s35
	s_cselect_b32 s76, s12, s34
	s_add_u32 s16, s16, 0x40080
	s_addc_u32 s17, s17, 0
	s_add_u32 s77, s34, 0x100
	s_addc_u32 s78, s35, 0
	s_mov_b32 s79, -2
	ds_read_b128 v[154:157], v151
	ds_read_b128 v[158:161], v151 offset:1024
	ds_read_b128 v[162:165], v151 offset:2048
	ds_read_b128 v[166:169], v151 offset:3072
	s_add_u32 s18, s16, 0xfffc0080
	s_addc_u32 s19, s17, -1
	s_cmp_eq_u32 s79, 12
	s_cselect_b32 s19, s9, s19
	s_cselect_b32 s18, s75, s18
	s_cselect_b32 s35, s7, s78
	s_cselect_b32 s34, s76, s77
	v_lshl_add_u64 v[172:173], s[16:17], 0, v[140:141]
	s_add_i32 m0, s53, 0xc000
	ds_read_b128 v[176:179], v152
	ds_read_b128 v[180:183], v152 offset:1024
	ds_read_b128 v[184:187], v152 offset:2048
	ds_read_b128 v[188:191], v152 offset:3072
	ds_read_b128 v[192:195], v152 offset:4096
	ds_read_b128 v[196:199], v152 offset:5120
	ds_read_b128 v[200:203], v152 offset:6144
	ds_read_b128 v[204:207], v152 offset:7168
	global_load_lds_dwordx4 v[172:173], off
	v_lshl_add_u64 v[172:173], s[16:17], 0, v[142:143]
	s_add_i32 m0, s53, 0xe000
	s_nop 0
	global_load_lds_dwordx4 v[172:173], off
	ds_read_b128 v[208:211], v153
	ds_read_b128 v[212:215], v153 offset:1024
	ds_read_b128 v[216:219], v153 offset:2048
	ds_read_b128 v[220:223], v153 offset:3072
	s_waitcnt lgkmcnt(0)
	s_setprio 1
	s_barrier
	v_mfma_f32_16x16x32_bf16 v[126:129], v[154:157], v[176:179], 0
	v_mfma_f32_16x16x32_bf16 v[122:125], v[162:165], v[176:179], 0
	v_mfma_f32_16x16x32_bf16 v[110:113], v[154:157], v[184:187], 0
	v_mfma_f32_16x16x32_bf16 v[106:109], v[162:165], v[184:187], 0
	v_mfma_f32_16x16x32_bf16 v[94:97], v[154:157], v[192:195], 0
	v_mfma_f32_16x16x32_bf16 v[90:93], v[162:165], v[192:195], 0
	v_mfma_f32_16x16x32_bf16 v[78:81], v[154:157], v[200:203], 0
	v_mfma_f32_16x16x32_bf16 v[74:77], v[162:165], v[200:203], 0
	v_mfma_f32_16x16x32_bf16 v[126:129], v[158:161], v[180:183], v[126:129]
	v_mfma_f32_16x16x32_bf16 v[122:125], v[166:169], v[180:183], v[122:125]
	v_mfma_f32_16x16x32_bf16 v[110:113], v[158:161], v[188:191], v[110:113]
	v_mfma_f32_16x16x32_bf16 v[106:109], v[166:169], v[188:191], v[106:109]
	v_mfma_f32_16x16x32_bf16 v[94:97], v[158:161], v[196:199], v[94:97]
	v_mfma_f32_16x16x32_bf16 v[90:93], v[166:169], v[196:199], v[90:93]
	v_mfma_f32_16x16x32_bf16 v[78:81], v[158:161], v[204:207], v[78:81]
	v_mfma_f32_16x16x32_bf16 v[74:77], v[166:169], v[204:207], v[74:77]
	v_mfma_f32_16x16x32_bf16 v[118:121], v[208:211], v[176:179], 0
	v_mfma_f32_16x16x32_bf16 v[114:117], v[216:219], v[176:179], 0
	v_mfma_f32_16x16x32_bf16 v[102:105], v[208:211], v[184:187], 0
	v_mfma_f32_16x16x32_bf16 v[98:101], v[216:219], v[184:187], 0
	v_mfma_f32_16x16x32_bf16 v[86:89], v[208:211], v[192:195], 0
	v_mfma_f32_16x16x32_bf16 v[82:85], v[216:219], v[192:195], 0
	v_mfma_f32_16x16x32_bf16 v[70:73], v[208:211], v[200:203], 0
	v_mfma_f32_16x16x32_bf16 v[66:69], v[216:219], v[200:203], 0
	v_mfma_f32_16x16x32_bf16 v[118:121], v[212:215], v[180:183], v[118:121]
	v_mfma_f32_16x16x32_bf16 v[114:117], v[220:223], v[180:183], v[114:117]
	v_mfma_f32_16x16x32_bf16 v[102:105], v[212:215], v[188:191], v[102:105]
	v_mfma_f32_16x16x32_bf16 v[98:101], v[220:223], v[188:191], v[98:101]
	v_mfma_f32_16x16x32_bf16 v[86:89], v[212:215], v[196:199], v[86:89]
	v_mfma_f32_16x16x32_bf16 v[82:85], v[220:223], v[196:199], v[82:85]
	v_mfma_f32_16x16x32_bf16 v[70:73], v[212:215], v[204:207], v[70:73]
	v_mfma_f32_16x16x32_bf16 v[66:69], v[220:223], v[204:207], v[66:69]
	s_barrier
	s_setprio 0
	s_add_i32 s20, s72, s52
	v_lshl_add_u64 v[172:173], s[34:35], 0, v[134:135]
	s_mov_b32 m0, s20
	s_nop 0
	global_load_lds_dwordx4 v[172:173], off
	v_lshl_add_u64 v[224:225], s[34:35], 0, v[130:131]
	s_add_i32 m0, s20, 0x2000
	s_nop 0
	global_load_lds_dwordx4 v[224:225], off
	s_mov_b32 m0, s53
	v_lshl_add_u64 v[226:227], s[18:19], 0, v[136:137]
	ds_read_b128 v[176:179], v152 offset:16384
	ds_read_b128 v[180:183], v152 offset:17408
	ds_read_b128 v[184:187], v152 offset:18432
	ds_read_b128 v[188:191], v152 offset:19456
	ds_read_b128 v[192:195], v152 offset:20480
	ds_read_b128 v[196:199], v152 offset:21504
	ds_read_b128 v[200:203], v152 offset:22528
	ds_read_b128 v[204:207], v152 offset:23552
	global_load_lds_dwordx4 v[226:227], off
	v_lshl_add_u64 v[228:229], s[18:19], 0, v[132:133]
	s_mov_b32 m0, s54
	s_nop 0
	global_load_lds_dwordx4 v[228:229], off
	s_waitcnt vmcnt(6)
	s_waitcnt lgkmcnt(0)
	s_setprio 1
	s_barrier
	v_mfma_f32_16x16x32_bf16 v[62:65], v[154:157], v[176:179], 0
	v_mfma_f32_16x16x32_bf16 v[58:61], v[162:165], v[176:179], 0
	v_mfma_f32_16x16x32_bf16 v[46:49], v[154:157], v[184:187], 0
	v_mfma_f32_16x16x32_bf16 v[42:45], v[162:165], v[184:187], 0
	v_mfma_f32_16x16x32_bf16 v[30:33], v[154:157], v[192:195], 0
	v_mfma_f32_16x16x32_bf16 v[26:29], v[162:165], v[192:195], 0
	v_mfma_f32_16x16x32_bf16 v[14:17], v[154:157], v[200:203], 0
	v_mfma_f32_16x16x32_bf16 v[10:13], v[162:165], v[200:203], 0
	v_mfma_f32_16x16x32_bf16 v[62:65], v[158:161], v[180:183], v[62:65]
	v_mfma_f32_16x16x32_bf16 v[58:61], v[166:169], v[180:183], v[58:61]
	v_mfma_f32_16x16x32_bf16 v[46:49], v[158:161], v[188:191], v[46:49]
	v_mfma_f32_16x16x32_bf16 v[42:45], v[166:169], v[188:191], v[42:45]
	v_mfma_f32_16x16x32_bf16 v[30:33], v[158:161], v[196:199], v[30:33]
	v_mfma_f32_16x16x32_bf16 v[26:29], v[166:169], v[196:199], v[26:29]
	v_mfma_f32_16x16x32_bf16 v[14:17], v[158:161], v[204:207], v[14:17]
	v_mfma_f32_16x16x32_bf16 v[10:13], v[166:169], v[204:207], v[10:13]
	v_mfma_f32_16x16x32_bf16 v[54:57], v[208:211], v[176:179], 0
	v_mfma_f32_16x16x32_bf16 v[50:53], v[216:219], v[176:179], 0
	v_mfma_f32_16x16x32_bf16 v[38:41], v[208:211], v[184:187], 0
	v_mfma_f32_16x16x32_bf16 v[34:37], v[216:219], v[184:187], 0
	v_mfma_f32_16x16x32_bf16 v[22:25], v[208:211], v[192:195], 0
	v_mfma_f32_16x16x32_bf16 v[18:21], v[216:219], v[192:195], 0
	v_mfma_f32_16x16x32_bf16 v[6:9], v[208:211], v[200:203], 0
	v_mfma_f32_16x16x32_bf16 v[2:5], v[216:219], v[200:203], 0
	v_mfma_f32_16x16x32_bf16 v[54:57], v[212:215], v[180:183], v[54:57]
	v_mfma_f32_16x16x32_bf16 v[50:53], v[220:223], v[180:183], v[50:53]
	v_mfma_f32_16x16x32_bf16 v[38:41], v[212:215], v[188:191], v[38:41]
	v_mfma_f32_16x16x32_bf16 v[34:37], v[220:223], v[188:191], v[34:37]
	v_mfma_f32_16x16x32_bf16 v[22:25], v[212:215], v[196:199], v[22:25]
	v_mfma_f32_16x16x32_bf16 v[18:21], v[220:223], v[196:199], v[18:21]
	v_mfma_f32_16x16x32_bf16 v[6:9], v[212:215], v[204:207], v[6:9]
	v_mfma_f32_16x16x32_bf16 v[2:5], v[220:223], v[204:207], v[2:5]
	s_barrier
	s_setprio 0
	s_add_u32 s20, s34, 0x40000
	s_addc_u32 s21, s35, 0
	s_add_i32 s60, s73, s52
	v_lshl_add_u64 v[246:247], s[20:21], 0, v[134:135]
	s_mov_b32 m0, s60
	s_nop 0
	global_load_lds_dwordx4 v[246:247], off
	v_lshl_add_u64 v[246:247], s[20:21], 0, v[130:131]
	s_add_i32 m0, s60, 0x2000
	s_nop 0
	global_load_lds_dwordx4 v[246:247], off
	s_add_i32 s20, 0, 0x18000
	v_add_u32_e32 v166, s20, v150
	ds_read_b128 v[154:157], v166
	ds_read_b128 v[158:161], v166 offset:1024
	ds_read_b128 v[162:165], v166 offset:2048
	ds_read_b128 v[166:169], v166 offset:3072
	s_add_u32 s18, s18, 0x40000
	s_addc_u32 s19, s19, 0
	s_mov_b32 m0, s55
	v_lshl_add_u64 v[208:209], s[18:19], 0, v[136:137]
	ds_read_b128 v[176:179], v152 offset:32768
	ds_read_b128 v[180:183], v152 offset:33792
	ds_read_b128 v[184:187], v152 offset:34816
	ds_read_b128 v[188:191], v152 offset:35840
	ds_read_b128 v[192:195], v152 offset:36864
	ds_read_b128 v[196:199], v152 offset:37888
	ds_read_b128 v[200:203], v152 offset:38912
	ds_read_b128 v[204:207], v152 offset:39936
	global_load_lds_dwordx4 v[208:209], off
	v_lshl_add_u64 v[208:209], s[18:19], 0, v[132:133]
	s_mov_b32 m0, s56
	s_nop 0
	global_load_lds_dwordx4 v[208:209], off
	s_add_i32 s21, 0, 0x1c000
	v_add_u32_e32 v171, s21, v150
	ds_read_b128 v[208:211], v171
	ds_read_b128 v[212:215], v171 offset:1024
	ds_read_b128 v[216:219], v171 offset:2048
	ds_read_b128 v[220:223], v171 offset:3072
	s_waitcnt vmcnt(8)
	s_waitcnt lgkmcnt(0)
	s_setprio 1
	s_barrier
	v_mfma_f32_16x16x32_bf16 v[126:129], v[154:157], v[176:179], v[126:129]
	v_mfma_f32_16x16x32_bf16 v[122:125], v[162:165], v[176:179], v[122:125]
	v_mfma_f32_16x16x32_bf16 v[110:113], v[154:157], v[184:187], v[110:113]
	v_mfma_f32_16x16x32_bf16 v[106:109], v[162:165], v[184:187], v[106:109]
	v_mfma_f32_16x16x32_bf16 v[94:97], v[154:157], v[192:195], v[94:97]
	v_mfma_f32_16x16x32_bf16 v[90:93], v[162:165], v[192:195], v[90:93]
	v_mfma_f32_16x16x32_bf16 v[78:81], v[154:157], v[200:203], v[78:81]
	v_mfma_f32_16x16x32_bf16 v[74:77], v[162:165], v[200:203], v[74:77]
	v_mfma_f32_16x16x32_bf16 v[126:129], v[158:161], v[180:183], v[126:129]
	v_mfma_f32_16x16x32_bf16 v[122:125], v[166:169], v[180:183], v[122:125]
	v_mfma_f32_16x16x32_bf16 v[110:113], v[158:161], v[188:191], v[110:113]
	v_mfma_f32_16x16x32_bf16 v[106:109], v[166:169], v[188:191], v[106:109]
	v_mfma_f32_16x16x32_bf16 v[94:97], v[158:161], v[196:199], v[94:97]
	v_mfma_f32_16x16x32_bf16 v[90:93], v[166:169], v[196:199], v[90:93]
	v_mfma_f32_16x16x32_bf16 v[78:81], v[158:161], v[204:207], v[78:81]
	v_mfma_f32_16x16x32_bf16 v[74:77], v[166:169], v[204:207], v[74:77]
	v_mfma_f32_16x16x32_bf16 v[118:121], v[208:211], v[176:179], v[118:121]
	v_mfma_f32_16x16x32_bf16 v[114:117], v[216:219], v[176:179], v[114:117]
	v_mfma_f32_16x16x32_bf16 v[102:105], v[208:211], v[184:187], v[102:105]
	v_mfma_f32_16x16x32_bf16 v[98:101], v[216:219], v[184:187], v[98:101]
	v_mfma_f32_16x16x32_bf16 v[86:89], v[208:211], v[192:195], v[86:89]
	v_mfma_f32_16x16x32_bf16 v[82:85], v[216:219], v[192:195], v[82:85]
	v_mfma_f32_16x16x32_bf16 v[70:73], v[208:211], v[200:203], v[70:73]
	v_mfma_f32_16x16x32_bf16 v[66:69], v[216:219], v[200:203], v[66:69]
	v_mfma_f32_16x16x32_bf16 v[118:121], v[212:215], v[180:183], v[118:121]
	v_mfma_f32_16x16x32_bf16 v[114:117], v[220:223], v[180:183], v[114:117]
	v_mfma_f32_16x16x32_bf16 v[102:105], v[212:215], v[188:191], v[102:105]
	v_mfma_f32_16x16x32_bf16 v[98:101], v[220:223], v[188:191], v[98:101]
	v_mfma_f32_16x16x32_bf16 v[86:89], v[212:215], v[196:199], v[86:89]
	v_mfma_f32_16x16x32_bf16 v[82:85], v[220:223], v[196:199], v[82:85]
	v_mfma_f32_16x16x32_bf16 v[70:73], v[212:215], v[204:207], v[70:73]
	v_mfma_f32_16x16x32_bf16 v[66:69], v[220:223], v[204:207], v[66:69]
	s_barrier
	s_setprio 0
	s_add_i32 s18, s20, s52
	v_lshl_add_u64 v[172:173], v[172:173], 0, s[4:5]
	s_mov_b32 m0, s18
	s_nop 0
	global_load_lds_dwordx4 v[172:173], off
	v_lshl_add_u64 v[172:173], v[224:225], 0, s[4:5]
	s_add_i32 m0, s18, 0x2000
	s_nop 0
	global_load_lds_dwordx4 v[172:173], off
	s_mov_b32 m0, s68
	v_lshl_add_u64 v[172:173], v[226:227], 0, s[4:5]
	ds_read_b128 v[176:179], v152 offset:49152
	ds_read_b128 v[180:183], v152 offset:50176
	ds_read_b128 v[184:187], v152 offset:51200
	ds_read_b128 v[188:191], v152 offset:52224
	ds_read_b128 v[192:195], v152 offset:53248
	ds_read_b128 v[196:199], v152 offset:54272
	ds_read_b128 v[200:203], v152 offset:55296
	ds_read_b128 v[204:207], v152 offset:56320
	global_load_lds_dwordx4 v[172:173], off
	v_lshl_add_u64 v[172:173], v[228:229], 0, s[4:5]
	s_mov_b32 m0, s69
	s_nop 0
	global_load_lds_dwordx4 v[172:173], off
	s_add_u32 s18, s34, 0x40080
	s_addc_u32 s19, s35, 0
	s_add_i32 s20, s21, s52
	v_lshl_add_u64 v[248:249], s[18:19], 0, v[134:135]
	s_mov_b32 m0, s20
	s_nop 0
	global_load_lds_dwordx4 v[248:249], off
	v_lshl_add_u64 v[248:249], s[18:19], 0, v[130:131]
	s_add_i32 m0, s20, 0x2000
	s_nop 0
	global_load_lds_dwordx4 v[248:249], off
	s_waitcnt vmcnt(6)
	s_waitcnt lgkmcnt(0)
	s_setprio 1
	s_barrier
	v_mfma_f32_16x16x32_bf16 v[62:65], v[154:157], v[176:179], v[62:65]
	v_mfma_f32_16x16x32_bf16 v[58:61], v[162:165], v[176:179], v[58:61]
	v_mfma_f32_16x16x32_bf16 v[46:49], v[154:157], v[184:187], v[46:49]
	v_mfma_f32_16x16x32_bf16 v[42:45], v[162:165], v[184:187], v[42:45]
	v_mfma_f32_16x16x32_bf16 v[30:33], v[154:157], v[192:195], v[30:33]
	v_mfma_f32_16x16x32_bf16 v[26:29], v[162:165], v[192:195], v[26:29]
	v_mfma_f32_16x16x32_bf16 v[14:17], v[154:157], v[200:203], v[14:17]
	v_mfma_f32_16x16x32_bf16 v[10:13], v[162:165], v[200:203], v[10:13]
	v_mfma_f32_16x16x32_bf16 v[62:65], v[158:161], v[180:183], v[62:65]
	v_mfma_f32_16x16x32_bf16 v[58:61], v[166:169], v[180:183], v[58:61]
	v_mfma_f32_16x16x32_bf16 v[46:49], v[158:161], v[188:191], v[46:49]
	v_mfma_f32_16x16x32_bf16 v[42:45], v[166:169], v[188:191], v[42:45]
	v_mfma_f32_16x16x32_bf16 v[30:33], v[158:161], v[196:199], v[30:33]
	v_mfma_f32_16x16x32_bf16 v[26:29], v[166:169], v[196:199], v[26:29]
	v_mfma_f32_16x16x32_bf16 v[14:17], v[158:161], v[204:207], v[14:17]
	v_mfma_f32_16x16x32_bf16 v[10:13], v[166:169], v[204:207], v[10:13]
	v_mfma_f32_16x16x32_bf16 v[54:57], v[208:211], v[176:179], v[54:57]
	v_mfma_f32_16x16x32_bf16 v[50:53], v[216:219], v[176:179], v[50:53]
	v_mfma_f32_16x16x32_bf16 v[38:41], v[208:211], v[184:187], v[38:41]
	v_mfma_f32_16x16x32_bf16 v[34:37], v[216:219], v[184:187], v[34:37]
	v_mfma_f32_16x16x32_bf16 v[22:25], v[208:211], v[192:195], v[22:25]
	v_mfma_f32_16x16x32_bf16 v[18:21], v[216:219], v[192:195], v[18:21]
	v_mfma_f32_16x16x32_bf16 v[6:9], v[208:211], v[200:203], v[6:9]
	v_mfma_f32_16x16x32_bf16 v[2:5], v[216:219], v[200:203], v[2:5]
	v_mfma_f32_16x16x32_bf16 v[54:57], v[212:215], v[180:183], v[54:57]
	v_mfma_f32_16x16x32_bf16 v[50:53], v[220:223], v[180:183], v[50:53]
	v_mfma_f32_16x16x32_bf16 v[38:41], v[212:215], v[188:191], v[38:41]
	v_mfma_f32_16x16x32_bf16 v[34:37], v[220:223], v[188:191], v[34:37]
	v_mfma_f32_16x16x32_bf16 v[22:25], v[212:215], v[196:199], v[22:25]
	v_mfma_f32_16x16x32_bf16 v[18:21], v[220:223], v[196:199], v[18:21]
	v_mfma_f32_16x16x32_bf16 v[6:9], v[212:215], v[204:207], v[6:9]
	v_mfma_f32_16x16x32_bf16 v[2:5], v[220:223], v[204:207], v[2:5]
	s_barrier
	s_setprio 0
	s_add_i32 s79, s79, 2
	s_add_u32 s16, s16, 0x100
	s_addc_u32 s17, s17, 0
	s_add_u32 s77, s77, 0x100
	s_addc_u32 s78, s78, 0
	s_cmp_gt_u32 s79, 13
.LBB0_567:
	ds_read_b128 v[154:157], v151
	ds_read_b128 v[158:161], v151 offset:1024
	ds_read_b128 v[162:165], v151 offset:2048
	ds_read_b128 v[166:169], v151 offset:3072
	s_add_u32 s18, s16, 0xfffc0080
	s_addc_u32 s19, s17, -1
	s_cmp_eq_u32 s79, 12
	s_cselect_b32 s19, s9, s19
	s_cselect_b32 s18, s75, s18
	s_cselect_b32 s35, s7, s78
	s_cselect_b32 s34, s76, s77
	v_lshl_add_u64 v[172:173], s[16:17], 0, v[140:141]
	s_add_i32 m0, s53, 0xc000
	ds_read_b128 v[176:179], v152
	ds_read_b128 v[180:183], v152 offset:1024
	ds_read_b128 v[184:187], v152 offset:2048
	ds_read_b128 v[188:191], v152 offset:3072
	ds_read_b128 v[192:195], v152 offset:4096
	ds_read_b128 v[196:199], v152 offset:5120
	ds_read_b128 v[200:203], v152 offset:6144
	ds_read_b128 v[204:207], v152 offset:7168
	global_load_lds_dwordx4 v[172:173], off
	v_lshl_add_u64 v[172:173], s[16:17], 0, v[142:143]
	s_add_i32 m0, s53, 0xe000
	s_nop 0
	global_load_lds_dwordx4 v[172:173], off
	ds_read_b128 v[208:211], v153
	ds_read_b128 v[212:215], v153 offset:1024
	ds_read_b128 v[216:219], v153 offset:2048
	ds_read_b128 v[220:223], v153 offset:3072
	s_waitcnt lgkmcnt(0)
	s_setprio 1
	s_barrier
	v_mfma_f32_16x16x32_bf16 v[126:129], v[154:157], v[176:179], v[126:129]
	v_mfma_f32_16x16x32_bf16 v[122:125], v[162:165], v[176:179], v[122:125]
	v_mfma_f32_16x16x32_bf16 v[110:113], v[154:157], v[184:187], v[110:113]
	v_mfma_f32_16x16x32_bf16 v[106:109], v[162:165], v[184:187], v[106:109]
	v_mfma_f32_16x16x32_bf16 v[94:97], v[154:157], v[192:195], v[94:97]
	v_mfma_f32_16x16x32_bf16 v[90:93], v[162:165], v[192:195], v[90:93]
	v_mfma_f32_16x16x32_bf16 v[78:81], v[154:157], v[200:203], v[78:81]
	v_mfma_f32_16x16x32_bf16 v[74:77], v[162:165], v[200:203], v[74:77]
	v_mfma_f32_16x16x32_bf16 v[126:129], v[158:161], v[180:183], v[126:129]
	v_mfma_f32_16x16x32_bf16 v[122:125], v[166:169], v[180:183], v[122:125]
	v_mfma_f32_16x16x32_bf16 v[110:113], v[158:161], v[188:191], v[110:113]
	v_mfma_f32_16x16x32_bf16 v[106:109], v[166:169], v[188:191], v[106:109]
	v_mfma_f32_16x16x32_bf16 v[94:97], v[158:161], v[196:199], v[94:97]
	v_mfma_f32_16x16x32_bf16 v[90:93], v[166:169], v[196:199], v[90:93]
	v_mfma_f32_16x16x32_bf16 v[78:81], v[158:161], v[204:207], v[78:81]
	v_mfma_f32_16x16x32_bf16 v[74:77], v[166:169], v[204:207], v[74:77]
	v_mfma_f32_16x16x32_bf16 v[118:121], v[208:211], v[176:179], v[118:121]
	v_mfma_f32_16x16x32_bf16 v[114:117], v[216:219], v[176:179], v[114:117]
	v_mfma_f32_16x16x32_bf16 v[102:105], v[208:211], v[184:187], v[102:105]
	v_mfma_f32_16x16x32_bf16 v[98:101], v[216:219], v[184:187], v[98:101]
	v_mfma_f32_16x16x32_bf16 v[86:89], v[208:211], v[192:195], v[86:89]
	v_mfma_f32_16x16x32_bf16 v[82:85], v[216:219], v[192:195], v[82:85]
	v_mfma_f32_16x16x32_bf16 v[70:73], v[208:211], v[200:203], v[70:73]
	v_mfma_f32_16x16x32_bf16 v[66:69], v[216:219], v[200:203], v[66:69]
	v_mfma_f32_16x16x32_bf16 v[118:121], v[212:215], v[180:183], v[118:121]
	v_mfma_f32_16x16x32_bf16 v[114:117], v[220:223], v[180:183], v[114:117]
	v_mfma_f32_16x16x32_bf16 v[102:105], v[212:215], v[188:191], v[102:105]
	v_mfma_f32_16x16x32_bf16 v[98:101], v[220:223], v[188:191], v[98:101]
	v_mfma_f32_16x16x32_bf16 v[86:89], v[212:215], v[196:199], v[86:89]
	v_mfma_f32_16x16x32_bf16 v[82:85], v[220:223], v[196:199], v[82:85]
	v_mfma_f32_16x16x32_bf16 v[70:73], v[212:215], v[204:207], v[70:73]
	v_mfma_f32_16x16x32_bf16 v[66:69], v[220:223], v[204:207], v[66:69]
	s_barrier
	s_setprio 0
	s_add_i32 s20, s72, s52
	v_lshl_add_u64 v[172:173], s[34:35], 0, v[134:135]
	s_mov_b32 m0, s20
	s_nop 0
	global_load_lds_dwordx4 v[172:173], off
	v_lshl_add_u64 v[224:225], s[34:35], 0, v[130:131]
	s_add_i32 m0, s20, 0x2000
	s_nop 0
	global_load_lds_dwordx4 v[224:225], off
	s_mov_b32 m0, s53
	v_lshl_add_u64 v[226:227], s[18:19], 0, v[136:137]
	ds_read_b128 v[176:179], v152 offset:16384
	ds_read_b128 v[180:183], v152 offset:17408
	ds_read_b128 v[184:187], v152 offset:18432
	ds_read_b128 v[188:191], v152 offset:19456
	ds_read_b128 v[192:195], v152 offset:20480
	ds_read_b128 v[196:199], v152 offset:21504
	ds_read_b128 v[200:203], v152 offset:22528
	ds_read_b128 v[204:207], v152 offset:23552
	global_load_lds_dwordx4 v[226:227], off
	v_lshl_add_u64 v[228:229], s[18:19], 0, v[132:133]
	s_mov_b32 m0, s54
	s_nop 0
	global_load_lds_dwordx4 v[228:229], off
	s_waitcnt vmcnt(6)
	s_waitcnt lgkmcnt(0)
	s_setprio 1
	s_barrier
	v_mfma_f32_16x16x32_bf16 v[62:65], v[154:157], v[176:179], v[62:65]
	v_mfma_f32_16x16x32_bf16 v[58:61], v[162:165], v[176:179], v[58:61]
	v_mfma_f32_16x16x32_bf16 v[46:49], v[154:157], v[184:187], v[46:49]
	v_mfma_f32_16x16x32_bf16 v[42:45], v[162:165], v[184:187], v[42:45]
	v_mfma_f32_16x16x32_bf16 v[30:33], v[154:157], v[192:195], v[30:33]
	v_mfma_f32_16x16x32_bf16 v[26:29], v[162:165], v[192:195], v[26:29]
	v_mfma_f32_16x16x32_bf16 v[14:17], v[154:157], v[200:203], v[14:17]
	v_mfma_f32_16x16x32_bf16 v[10:13], v[162:165], v[200:203], v[10:13]
	v_mfma_f32_16x16x32_bf16 v[62:65], v[158:161], v[180:183], v[62:65]
	v_mfma_f32_16x16x32_bf16 v[58:61], v[166:169], v[180:183], v[58:61]
	v_mfma_f32_16x16x32_bf16 v[46:49], v[158:161], v[188:191], v[46:49]
	v_mfma_f32_16x16x32_bf16 v[42:45], v[166:169], v[188:191], v[42:45]
	v_mfma_f32_16x16x32_bf16 v[30:33], v[158:161], v[196:199], v[30:33]
	v_mfma_f32_16x16x32_bf16 v[26:29], v[166:169], v[196:199], v[26:29]
	v_mfma_f32_16x16x32_bf16 v[14:17], v[158:161], v[204:207], v[14:17]
	v_mfma_f32_16x16x32_bf16 v[10:13], v[166:169], v[204:207], v[10:13]
	v_mfma_f32_16x16x32_bf16 v[54:57], v[208:211], v[176:179], v[54:57]
	v_mfma_f32_16x16x32_bf16 v[50:53], v[216:219], v[176:179], v[50:53]
	v_mfma_f32_16x16x32_bf16 v[38:41], v[208:211], v[184:187], v[38:41]
	v_mfma_f32_16x16x32_bf16 v[34:37], v[216:219], v[184:187], v[34:37]
	v_mfma_f32_16x16x32_bf16 v[22:25], v[208:211], v[192:195], v[22:25]
	v_mfma_f32_16x16x32_bf16 v[18:21], v[216:219], v[192:195], v[18:21]
	v_mfma_f32_16x16x32_bf16 v[6:9], v[208:211], v[200:203], v[6:9]
	v_mfma_f32_16x16x32_bf16 v[2:5], v[216:219], v[200:203], v[2:5]
	v_mfma_f32_16x16x32_bf16 v[54:57], v[212:215], v[180:183], v[54:57]
	v_mfma_f32_16x16x32_bf16 v[50:53], v[220:223], v[180:183], v[50:53]
	v_mfma_f32_16x16x32_bf16 v[38:41], v[212:215], v[188:191], v[38:41]
	v_mfma_f32_16x16x32_bf16 v[34:37], v[220:223], v[188:191], v[34:37]
	v_mfma_f32_16x16x32_bf16 v[22:25], v[212:215], v[196:199], v[22:25]
	v_mfma_f32_16x16x32_bf16 v[18:21], v[220:223], v[196:199], v[18:21]
	v_mfma_f32_16x16x32_bf16 v[6:9], v[212:215], v[204:207], v[6:9]
	v_mfma_f32_16x16x32_bf16 v[2:5], v[220:223], v[204:207], v[2:5]
	s_barrier
	s_setprio 0
	s_add_u32 s20, s34, 0x40000
	s_addc_u32 s21, s35, 0
	s_add_i32 s60, s73, s52
	v_lshl_add_u64 v[246:247], s[20:21], 0, v[134:135]
	s_mov_b32 m0, s60
	s_nop 0
	global_load_lds_dwordx4 v[246:247], off
	v_lshl_add_u64 v[246:247], s[20:21], 0, v[130:131]
	s_add_i32 m0, s60, 0x2000
	s_nop 0
	global_load_lds_dwordx4 v[246:247], off
	s_add_i32 s20, 0, 0x18000
	v_add_u32_e32 v166, s20, v150
	ds_read_b128 v[154:157], v166
	ds_read_b128 v[158:161], v166 offset:1024
	ds_read_b128 v[162:165], v166 offset:2048
	ds_read_b128 v[166:169], v166 offset:3072
	s_add_u32 s18, s18, 0x40000
	s_addc_u32 s19, s19, 0
	s_mov_b32 m0, s55
	v_lshl_add_u64 v[208:209], s[18:19], 0, v[136:137]
	ds_read_b128 v[176:179], v152 offset:32768
	ds_read_b128 v[180:183], v152 offset:33792
	ds_read_b128 v[184:187], v152 offset:34816
	ds_read_b128 v[188:191], v152 offset:35840
	ds_read_b128 v[192:195], v152 offset:36864
	ds_read_b128 v[196:199], v152 offset:37888
	ds_read_b128 v[200:203], v152 offset:38912
	ds_read_b128 v[204:207], v152 offset:39936
	global_load_lds_dwordx4 v[208:209], off
	v_lshl_add_u64 v[208:209], s[18:19], 0, v[132:133]
	s_mov_b32 m0, s56
	s_nop 0
	global_load_lds_dwordx4 v[208:209], off
	s_add_i32 s21, 0, 0x1c000
	v_add_u32_e32 v171, s21, v150
	ds_read_b128 v[208:211], v171
	ds_read_b128 v[212:215], v171 offset:1024
	ds_read_b128 v[216:219], v171 offset:2048
	ds_read_b128 v[220:223], v171 offset:3072
	s_waitcnt vmcnt(8)
	s_waitcnt lgkmcnt(0)
	s_setprio 1
	s_barrier
	v_mfma_f32_16x16x32_bf16 v[126:129], v[154:157], v[176:179], v[126:129]
	v_mfma_f32_16x16x32_bf16 v[122:125], v[162:165], v[176:179], v[122:125]
	v_mfma_f32_16x16x32_bf16 v[110:113], v[154:157], v[184:187], v[110:113]
	v_mfma_f32_16x16x32_bf16 v[106:109], v[162:165], v[184:187], v[106:109]
	v_mfma_f32_16x16x32_bf16 v[94:97], v[154:157], v[192:195], v[94:97]
	v_mfma_f32_16x16x32_bf16 v[90:93], v[162:165], v[192:195], v[90:93]
	v_mfma_f32_16x16x32_bf16 v[78:81], v[154:157], v[200:203], v[78:81]
	v_mfma_f32_16x16x32_bf16 v[74:77], v[162:165], v[200:203], v[74:77]
	v_mfma_f32_16x16x32_bf16 v[126:129], v[158:161], v[180:183], v[126:129]
	v_mfma_f32_16x16x32_bf16 v[122:125], v[166:169], v[180:183], v[122:125]
	v_mfma_f32_16x16x32_bf16 v[110:113], v[158:161], v[188:191], v[110:113]
	v_mfma_f32_16x16x32_bf16 v[106:109], v[166:169], v[188:191], v[106:109]
	v_mfma_f32_16x16x32_bf16 v[94:97], v[158:161], v[196:199], v[94:97]
	v_mfma_f32_16x16x32_bf16 v[90:93], v[166:169], v[196:199], v[90:93]
	v_mfma_f32_16x16x32_bf16 v[78:81], v[158:161], v[204:207], v[78:81]
	v_mfma_f32_16x16x32_bf16 v[74:77], v[166:169], v[204:207], v[74:77]
	v_mfma_f32_16x16x32_bf16 v[118:121], v[208:211], v[176:179], v[118:121]
	v_mfma_f32_16x16x32_bf16 v[114:117], v[216:219], v[176:179], v[114:117]
	v_mfma_f32_16x16x32_bf16 v[102:105], v[208:211], v[184:187], v[102:105]
	v_mfma_f32_16x16x32_bf16 v[98:101], v[216:219], v[184:187], v[98:101]
	v_mfma_f32_16x16x32_bf16 v[86:89], v[208:211], v[192:195], v[86:89]
	v_mfma_f32_16x16x32_bf16 v[82:85], v[216:219], v[192:195], v[82:85]
	v_mfma_f32_16x16x32_bf16 v[70:73], v[208:211], v[200:203], v[70:73]
	v_mfma_f32_16x16x32_bf16 v[66:69], v[216:219], v[200:203], v[66:69]
	v_mfma_f32_16x16x32_bf16 v[118:121], v[212:215], v[180:183], v[118:121]
	v_mfma_f32_16x16x32_bf16 v[114:117], v[220:223], v[180:183], v[114:117]
	v_mfma_f32_16x16x32_bf16 v[102:105], v[212:215], v[188:191], v[102:105]
	v_mfma_f32_16x16x32_bf16 v[98:101], v[220:223], v[188:191], v[98:101]
	v_mfma_f32_16x16x32_bf16 v[86:89], v[212:215], v[196:199], v[86:89]
	v_mfma_f32_16x16x32_bf16 v[82:85], v[220:223], v[196:199], v[82:85]
	v_mfma_f32_16x16x32_bf16 v[70:73], v[212:215], v[204:207], v[70:73]
	v_mfma_f32_16x16x32_bf16 v[66:69], v[220:223], v[204:207], v[66:69]
	s_barrier
	s_setprio 0
	s_add_i32 s18, s20, s52
	v_lshl_add_u64 v[172:173], v[172:173], 0, s[4:5]
	s_mov_b32 m0, s18
	s_nop 0
	global_load_lds_dwordx4 v[172:173], off
	v_lshl_add_u64 v[172:173], v[224:225], 0, s[4:5]
	s_add_i32 m0, s18, 0x2000
	s_nop 0
	global_load_lds_dwordx4 v[172:173], off
	s_mov_b32 m0, s68
	v_lshl_add_u64 v[172:173], v[226:227], 0, s[4:5]
	ds_read_b128 v[176:179], v152 offset:49152
	ds_read_b128 v[180:183], v152 offset:50176
	ds_read_b128 v[184:187], v152 offset:51200
	ds_read_b128 v[188:191], v152 offset:52224
	ds_read_b128 v[192:195], v152 offset:53248
	ds_read_b128 v[196:199], v152 offset:54272
	ds_read_b128 v[200:203], v152 offset:55296
	ds_read_b128 v[204:207], v152 offset:56320
	global_load_lds_dwordx4 v[172:173], off
	v_lshl_add_u64 v[172:173], v[228:229], 0, s[4:5]
	s_mov_b32 m0, s69
	s_nop 0
	global_load_lds_dwordx4 v[172:173], off
	s_add_u32 s18, s34, 0x40080
	s_addc_u32 s19, s35, 0
	s_add_i32 s20, s21, s52
	v_lshl_add_u64 v[248:249], s[18:19], 0, v[134:135]
	s_mov_b32 m0, s20
	s_nop 0
	global_load_lds_dwordx4 v[248:249], off
	v_lshl_add_u64 v[248:249], s[18:19], 0, v[130:131]
	s_add_i32 m0, s20, 0x2000
	s_nop 0
	global_load_lds_dwordx4 v[248:249], off
	s_waitcnt vmcnt(6)
	s_waitcnt lgkmcnt(0)
	s_setprio 1
	s_barrier
	v_mfma_f32_16x16x32_bf16 v[62:65], v[154:157], v[176:179], v[62:65]
	v_mfma_f32_16x16x32_bf16 v[58:61], v[162:165], v[176:179], v[58:61]
	v_mfma_f32_16x16x32_bf16 v[46:49], v[154:157], v[184:187], v[46:49]
	v_mfma_f32_16x16x32_bf16 v[42:45], v[162:165], v[184:187], v[42:45]
	v_mfma_f32_16x16x32_bf16 v[30:33], v[154:157], v[192:195], v[30:33]
	v_mfma_f32_16x16x32_bf16 v[26:29], v[162:165], v[192:195], v[26:29]
	v_mfma_f32_16x16x32_bf16 v[14:17], v[154:157], v[200:203], v[14:17]
	v_mfma_f32_16x16x32_bf16 v[10:13], v[162:165], v[200:203], v[10:13]
	v_mfma_f32_16x16x32_bf16 v[62:65], v[158:161], v[180:183], v[62:65]
	v_mfma_f32_16x16x32_bf16 v[58:61], v[166:169], v[180:183], v[58:61]
	v_mfma_f32_16x16x32_bf16 v[46:49], v[158:161], v[188:191], v[46:49]
	v_mfma_f32_16x16x32_bf16 v[42:45], v[166:169], v[188:191], v[42:45]
	v_mfma_f32_16x16x32_bf16 v[30:33], v[158:161], v[196:199], v[30:33]
	v_mfma_f32_16x16x32_bf16 v[26:29], v[166:169], v[196:199], v[26:29]
	v_mfma_f32_16x16x32_bf16 v[14:17], v[158:161], v[204:207], v[14:17]
	v_mfma_f32_16x16x32_bf16 v[10:13], v[166:169], v[204:207], v[10:13]
	v_mfma_f32_16x16x32_bf16 v[54:57], v[208:211], v[176:179], v[54:57]
	v_mfma_f32_16x16x32_bf16 v[50:53], v[216:219], v[176:179], v[50:53]
	v_mfma_f32_16x16x32_bf16 v[38:41], v[208:211], v[184:187], v[38:41]
	v_mfma_f32_16x16x32_bf16 v[34:37], v[216:219], v[184:187], v[34:37]
	v_mfma_f32_16x16x32_bf16 v[22:25], v[208:211], v[192:195], v[22:25]
	v_mfma_f32_16x16x32_bf16 v[18:21], v[216:219], v[192:195], v[18:21]
	v_mfma_f32_16x16x32_bf16 v[6:9], v[208:211], v[200:203], v[6:9]
	v_mfma_f32_16x16x32_bf16 v[2:5], v[216:219], v[200:203], v[2:5]
	v_mfma_f32_16x16x32_bf16 v[54:57], v[212:215], v[180:183], v[54:57]
	v_mfma_f32_16x16x32_bf16 v[50:53], v[220:223], v[180:183], v[50:53]
	v_mfma_f32_16x16x32_bf16 v[38:41], v[212:215], v[188:191], v[38:41]
	v_mfma_f32_16x16x32_bf16 v[34:37], v[220:223], v[188:191], v[34:37]
	v_mfma_f32_16x16x32_bf16 v[22:25], v[212:215], v[196:199], v[22:25]
	v_mfma_f32_16x16x32_bf16 v[18:21], v[220:223], v[196:199], v[18:21]
	v_mfma_f32_16x16x32_bf16 v[6:9], v[212:215], v[204:207], v[6:9]
	v_mfma_f32_16x16x32_bf16 v[2:5], v[220:223], v[204:207], v[2:5]
	s_barrier
	s_setprio 0
	s_add_i32 s79, s79, 2
	s_add_u32 s16, s16, 0x100
	s_addc_u32 s17, s17, 0
	s_add_u32 s77, s77, 0x100
	s_addc_u32 s78, s78, 0
	s_cmp_gt_u32 s79, 13
	s_cbranch_scc0 .LBB0_567
	v_mul_f32_e32 v154, 0xbfb8aa3b, v126
	v_mul_f32_e32 v155, 0xbfb8aa3b, v127
	v_exp_f32_e32 v154, v154
	v_exp_f32_e32 v155, v155
	s_and_b64 vcc, exec, s[2:3]
	s_mov_b64 s[34:35], s[12:13]
	v_add_f32_e32 v154, 1.0, v154
	v_add_f32_e32 v155, 1.0, v155
	v_rcp_f32_e32 v156, v154
	v_rcp_f32_e32 v157, v155
	v_mul_f32_e32 v155, 0xbfb8aa3b, v128
	v_exp_f32_e32 v155, v155
	v_lshl_add_u32 v154, s14, 8, v149
	v_pk_mul_f32 v[126:127], v[126:127], v[156:157]
	v_mul_f32_e32 v156, 0xbfb8aa3b, v129
	v_exp_f32_e32 v156, v156
	v_pk_mul_f32 v[118:119], v[126:127], v[118:119]
	v_add_f32_e32 v126, 1.0, v155
	v_mul_f32_e32 v155, 0xbfb8aa3b, v122
	v_add_f32_e32 v127, 1.0, v156
	v_rcp_f32_e32 v126, v126
	v_rcp_f32_e32 v127, v127
	v_exp_f32_e32 v155, v155
	v_mul_f32_e32 v156, 0xbfb8aa3b, v123
	v_exp_f32_e32 v156, v156
	v_pk_mul_f32 v[126:127], v[128:129], v[126:127]
	v_add_f32_e32 v128, 1.0, v155
	v_mul_f32_e32 v155, 0xbfb8aa3b, v124
	v_add_f32_e32 v129, 1.0, v156
	v_exp_f32_e32 v155, v155
	v_mul_f32_e32 v156, 0xbfb8aa3b, v125
	v_exp_f32_e32 v157, v156
	v_rcp_f32_e32 v128, v128
	v_add_f32_e32 v155, 1.0, v155
	v_rcp_f32_e32 v129, v129
	v_rcp_f32_e32 v156, v155
	v_add_f32_e32 v155, 1.0, v157
	v_rcp_f32_e32 v157, v155
	v_pk_mul_f32 v[122:123], v[122:123], v[128:129]
	s_lshl_b32 s14, s15, 7
	v_pk_mul_f32 v[122:123], v[122:123], v[114:115]
	v_pk_mul_f32 v[114:115], v[124:125], v[156:157]
	s_ashr_i32 s15, s14, 31
	v_pk_mul_f32 v[124:125], v[114:115], v[116:117]
	v_mov_b64_e32 v[114:115], s[0:1]
	v_mad_i64_i32 v[116:117], s[16:17], v154, s74, v[114:115]
	s_lshl_b64 s[14:15], s[14:15], 1
	v_lshl_add_u64 v[116:117], v[116:117], 0, s[14:15]
	v_pk_mul_f32 v[120:121], v[126:127], v[120:121]
	v_lshl_add_u64 v[126:127], v[116:117], 0, v[138:139]
	v_cvt_pk_bf16_f32 v116, v118, v119
	v_mul_f32_e32 v118, 0xbfb8aa3b, v110
	v_exp_f32_e32 v119, v118
	v_mul_f32_e32 v118, 0xbfb8aa3b, v111
	v_cvt_pk_bf16_f32 v117, v120, v121
	v_exp_f32_e32 v121, v118
	v_add_f32_e32 v119, 1.0, v119
	v_rcp_f32_e32 v120, v119
	v_cvt_pk_bf16_f32 v118, v122, v123
	v_add_f32_e32 v119, 1.0, v121
	v_rcp_f32_e32 v121, v119
	v_cvt_pk_bf16_f32 v119, v124, v125
	global_store_dwordx4 v[126:127], v[116:119], off nt
	v_pk_mul_f32 v[110:111], v[110:111], v[120:121]
	s_nop 0
	v_mul_f32_e32 v116, 0xbfb8aa3b, v112
	v_mul_f32_e32 v117, 0xbfb8aa3b, v113
	v_exp_f32_e32 v116, v116
	v_exp_f32_e32 v117, v117
	v_pk_mul_f32 v[102:103], v[110:111], v[102:103]
	v_or_b32_e32 v118, 16, v154
	v_add_f32_e32 v110, 1.0, v116
	v_add_f32_e32 v111, 1.0, v117
	v_mul_f32_e32 v116, 0xbfb8aa3b, v106
	v_mul_f32_e32 v117, 0xbfb8aa3b, v107
	v_rcp_f32_e32 v110, v110
	v_rcp_f32_e32 v111, v111
	v_exp_f32_e32 v116, v116
	v_exp_f32_e32 v117, v117
	v_pk_mul_f32 v[110:111], v[112:113], v[110:111]
	v_add_f32_e32 v112, 1.0, v116
	v_add_f32_e32 v113, 1.0, v117
	v_mul_f32_e32 v116, 0xbfb8aa3b, v108
	v_mul_f32_e32 v117, 0xbfb8aa3b, v109
	v_exp_f32_e32 v116, v116
	v_exp_f32_e32 v117, v117
	v_rcp_f32_e32 v112, v112
	v_rcp_f32_e32 v113, v113
	v_add_f32_e32 v116, 1.0, v116
	v_add_f32_e32 v117, 1.0, v117
	v_rcp_f32_e32 v116, v116
	v_rcp_f32_e32 v117, v117
	v_pk_mul_f32 v[106:107], v[106:107], v[112:113]
	v_pk_mul_f32 v[104:105], v[110:111], v[104:105]
	v_pk_mul_f32 v[106:107], v[106:107], v[98:99]
	v_pk_mul_f32 v[98:99], v[108:109], v[116:117]
	s_nop 0
	v_pk_mul_f32 v[108:109], v[98:99], v[100:101]
	v_mad_i64_i32 v[98:99], s[16:17], v118, s74, v[114:115]
	v_mul_f32_e32 v100, 0xbfb8aa3b, v94
	v_lshl_add_u64 v[98:99], v[98:99], 0, s[14:15]
	v_exp_f32_e32 v101, v100
	v_mul_f32_e32 v100, 0xbfb8aa3b, v95
	v_lshl_add_u64 v[110:111], v[98:99], 0, v[138:139]
	v_cvt_pk_bf16_f32 v98, v102, v103
	v_exp_f32_e32 v103, v100
	v_add_f32_e32 v101, 1.0, v101
	v_rcp_f32_e32 v102, v101
	v_cvt_pk_bf16_f32 v99, v104, v105
	v_add_f32_e32 v101, 1.0, v103
	v_cvt_pk_bf16_f32 v100, v106, v107
	v_rcp_f32_e32 v103, v101
	v_cvt_pk_bf16_f32 v101, v108, v109
	global_store_dwordx4 v[110:111], v[98:101], off nt
	v_pk_mul_f32 v[94:95], v[94:95], v[102:103]
	s_nop 0
	v_mul_f32_e32 v98, 0xbfb8aa3b, v96
	v_mul_f32_e32 v99, 0xbfb8aa3b, v97
	v_exp_f32_e32 v98, v98
	v_exp_f32_e32 v99, v99
	v_pk_mul_f32 v[86:87], v[94:95], v[86:87]
	v_or_b32_e32 v100, 32, v154
	v_add_f32_e32 v94, 1.0, v98
	v_add_f32_e32 v95, 1.0, v99
	v_mul_f32_e32 v98, 0xbfb8aa3b, v90
	v_mul_f32_e32 v99, 0xbfb8aa3b, v91
	v_rcp_f32_e32 v94, v94
	v_rcp_f32_e32 v95, v95
	v_exp_f32_e32 v98, v98
	v_exp_f32_e32 v99, v99
	v_pk_mul_f32 v[94:95], v[96:97], v[94:95]
	v_add_f32_e32 v96, 1.0, v98
	v_add_f32_e32 v97, 1.0, v99
	v_mul_f32_e32 v98, 0xbfb8aa3b, v92
	v_mul_f32_e32 v99, 0xbfb8aa3b, v93
	v_exp_f32_e32 v98, v98
	v_exp_f32_e32 v99, v99
	v_rcp_f32_e32 v96, v96
	v_rcp_f32_e32 v97, v97
	v_add_f32_e32 v98, 1.0, v98
	v_add_f32_e32 v99, 1.0, v99
	v_rcp_f32_e32 v98, v98
	v_rcp_f32_e32 v99, v99
	v_pk_mul_f32 v[90:91], v[90:91], v[96:97]
	v_pk_mul_f32 v[88:89], v[94:95], v[88:89]
	v_pk_mul_f32 v[90:91], v[90:91], v[82:83]
	v_pk_mul_f32 v[82:83], v[92:93], v[98:99]
	s_nop 0
	v_pk_mul_f32 v[92:93], v[82:83], v[84:85]
	v_mad_i64_i32 v[82:83], s[16:17], v100, s74, v[114:115]
	v_mul_f32_e32 v84, 0xbfb8aa3b, v78
	v_lshl_add_u64 v[82:83], v[82:83], 0, s[14:15]
	v_exp_f32_e32 v85, v84
	v_mul_f32_e32 v84, 0xbfb8aa3b, v79
	v_lshl_add_u64 v[94:95], v[82:83], 0, v[138:139]
	v_cvt_pk_bf16_f32 v82, v86, v87
	v_exp_f32_e32 v87, v84
	v_add_f32_e32 v85, 1.0, v85
	v_rcp_f32_e32 v86, v85
	v_cvt_pk_bf16_f32 v83, v88, v89
	v_add_f32_e32 v85, 1.0, v87
	v_cvt_pk_bf16_f32 v84, v90, v91
	v_rcp_f32_e32 v87, v85
	v_cvt_pk_bf16_f32 v85, v92, v93
	global_store_dwordx4 v[94:95], v[82:85], off nt
	v_pk_mul_f32 v[78:79], v[78:79], v[86:87]
	s_nop 0
	v_mul_f32_e32 v82, 0xbfb8aa3b, v80
	v_mul_f32_e32 v83, 0xbfb8aa3b, v81
	v_exp_f32_e32 v82, v82
	v_exp_f32_e32 v83, v83
	v_pk_mul_f32 v[70:71], v[78:79], v[70:71]
	v_or_b32_e32 v84, 48, v154
	v_add_f32_e32 v78, 1.0, v82
	v_add_f32_e32 v79, 1.0, v83
	v_mul_f32_e32 v82, 0xbfb8aa3b, v74
	v_mul_f32_e32 v83, 0xbfb8aa3b, v75
	v_rcp_f32_e32 v78, v78
	v_rcp_f32_e32 v79, v79
	v_exp_f32_e32 v82, v82
	v_exp_f32_e32 v83, v83
	v_pk_mul_f32 v[78:79], v[80:81], v[78:79]
	v_add_f32_e32 v80, 1.0, v82
	v_add_f32_e32 v81, 1.0, v83
	v_mul_f32_e32 v82, 0xbfb8aa3b, v76
	v_mul_f32_e32 v83, 0xbfb8aa3b, v77
	v_exp_f32_e32 v82, v82
	v_exp_f32_e32 v83, v83
	v_rcp_f32_e32 v80, v80
	v_rcp_f32_e32 v81, v81
	v_add_f32_e32 v82, 1.0, v82
	v_add_f32_e32 v83, 1.0, v83
	v_rcp_f32_e32 v82, v82
	v_rcp_f32_e32 v83, v83
	v_pk_mul_f32 v[74:75], v[74:75], v[80:81]
	v_pk_mul_f32 v[72:73], v[78:79], v[72:73]
	v_pk_mul_f32 v[74:75], v[74:75], v[66:67]
	v_pk_mul_f32 v[66:67], v[76:77], v[82:83]
	s_nop 0
	v_pk_mul_f32 v[76:77], v[66:67], v[68:69]
	v_mad_i64_i32 v[66:67], s[16:17], v84, s74, v[114:115]
	v_mul_f32_e32 v68, 0xbfb8aa3b, v62
	v_lshl_add_u64 v[66:67], v[66:67], 0, s[14:15]
	v_exp_f32_e32 v69, v68
	v_mul_f32_e32 v68, 0xbfb8aa3b, v63
	v_lshl_add_u64 v[78:79], v[66:67], 0, v[138:139]
	v_cvt_pk_bf16_f32 v66, v70, v71
	v_exp_f32_e32 v71, v68
	v_add_f32_e32 v69, 1.0, v69
	v_rcp_f32_e32 v70, v69
	v_cvt_pk_bf16_f32 v67, v72, v73
	v_add_f32_e32 v69, 1.0, v71
	v_cvt_pk_bf16_f32 v68, v74, v75
	v_rcp_f32_e32 v71, v69
	v_cvt_pk_bf16_f32 v69, v76, v77
	global_store_dwordx4 v[78:79], v[66:69], off nt
	v_pk_mul_f32 v[62:63], v[62:63], v[70:71]
	s_nop 0
	v_mul_f32_e32 v66, 0xbfb8aa3b, v64
	v_mul_f32_e32 v67, 0xbfb8aa3b, v65
	v_exp_f32_e32 v66, v66
	v_exp_f32_e32 v67, v67
	v_pk_mul_f32 v[54:55], v[62:63], v[54:55]
	v_add_u32_e32 v68, 0x80, v154
	v_add_f32_e32 v62, 1.0, v66
	v_add_f32_e32 v63, 1.0, v67
	v_mul_f32_e32 v66, 0xbfb8aa3b, v58
	v_mul_f32_e32 v67, 0xbfb8aa3b, v59
	v_rcp_f32_e32 v62, v62
	v_rcp_f32_e32 v63, v63
	v_exp_f32_e32 v66, v66
	v_exp_f32_e32 v67, v67
	v_pk_mul_f32 v[62:63], v[64:65], v[62:63]
	v_add_f32_e32 v64, 1.0, v66
	v_add_f32_e32 v65, 1.0, v67
	v_mul_f32_e32 v66, 0xbfb8aa3b, v60
	v_mul_f32_e32 v67, 0xbfb8aa3b, v61
	v_exp_f32_e32 v66, v66
	v_exp_f32_e32 v67, v67
	v_rcp_f32_e32 v64, v64
	v_rcp_f32_e32 v65, v65
	v_add_f32_e32 v66, 1.0, v66
	v_add_f32_e32 v67, 1.0, v67
	v_rcp_f32_e32 v66, v66
	v_rcp_f32_e32 v67, v67
	v_pk_mul_f32 v[58:59], v[58:59], v[64:65]
	v_pk_mul_f32 v[56:57], v[62:63], v[56:57]
	v_pk_mul_f32 v[58:59], v[58:59], v[50:51]
	v_pk_mul_f32 v[50:51], v[60:61], v[66:67]
	s_nop 0
	v_pk_mul_f32 v[60:61], v[50:51], v[52:53]
	v_mad_i64_i32 v[50:51], s[16:17], v68, s74, v[114:115]
	v_mul_f32_e32 v52, 0xbfb8aa3b, v46
	v_lshl_add_u64 v[50:51], v[50:51], 0, s[14:15]
	v_exp_f32_e32 v53, v52
	v_mul_f32_e32 v52, 0xbfb8aa3b, v47
	v_lshl_add_u64 v[62:63], v[50:51], 0, v[138:139]
	v_cvt_pk_bf16_f32 v50, v54, v55
	v_exp_f32_e32 v55, v52
	v_add_f32_e32 v53, 1.0, v53
	v_rcp_f32_e32 v54, v53
	v_cvt_pk_bf16_f32 v51, v56, v57
	v_add_f32_e32 v53, 1.0, v55
	v_cvt_pk_bf16_f32 v52, v58, v59
	v_rcp_f32_e32 v55, v53
	v_cvt_pk_bf16_f32 v53, v60, v61
	global_store_dwordx4 v[62:63], v[50:53], off nt
	v_pk_mul_f32 v[46:47], v[46:47], v[54:55]
	s_nop 0
	v_mul_f32_e32 v50, 0xbfb8aa3b, v48
	v_mul_f32_e32 v51, 0xbfb8aa3b, v49
	v_exp_f32_e32 v50, v50
	v_exp_f32_e32 v51, v51
	v_pk_mul_f32 v[38:39], v[46:47], v[38:39]
	v_add_u32_e32 v52, 0x90, v154
	v_add_f32_e32 v46, 1.0, v50
	v_add_f32_e32 v47, 1.0, v51
	v_mul_f32_e32 v50, 0xbfb8aa3b, v42
	v_mul_f32_e32 v51, 0xbfb8aa3b, v43
	v_rcp_f32_e32 v46, v46
	v_rcp_f32_e32 v47, v47
	v_exp_f32_e32 v50, v50
	v_exp_f32_e32 v51, v51
	v_pk_mul_f32 v[46:47], v[48:49], v[46:47]
	v_add_f32_e32 v48, 1.0, v50
	v_add_f32_e32 v49, 1.0, v51
	v_mul_f32_e32 v50, 0xbfb8aa3b, v44
	v_mul_f32_e32 v51, 0xbfb8aa3b, v45
	v_exp_f32_e32 v50, v50
	v_exp_f32_e32 v51, v51
	v_rcp_f32_e32 v48, v48
	v_rcp_f32_e32 v49, v49
	v_add_f32_e32 v50, 1.0, v50
	v_add_f32_e32 v51, 1.0, v51
	v_rcp_f32_e32 v50, v50
	v_rcp_f32_e32 v51, v51
	v_pk_mul_f32 v[42:43], v[42:43], v[48:49]
	v_pk_mul_f32 v[40:41], v[46:47], v[40:41]
	v_pk_mul_f32 v[42:43], v[42:43], v[34:35]
	v_pk_mul_f32 v[34:35], v[44:45], v[50:51]
	s_nop 0
	v_pk_mul_f32 v[44:45], v[34:35], v[36:37]
	v_mad_i64_i32 v[34:35], s[16:17], v52, s74, v[114:115]
	v_mul_f32_e32 v36, 0xbfb8aa3b, v30
	v_lshl_add_u64 v[34:35], v[34:35], 0, s[14:15]
	v_exp_f32_e32 v37, v36
	v_mul_f32_e32 v36, 0xbfb8aa3b, v31
	v_lshl_add_u64 v[46:47], v[34:35], 0, v[138:139]
	v_cvt_pk_bf16_f32 v34, v38, v39
	v_exp_f32_e32 v39, v36
	v_add_f32_e32 v37, 1.0, v37
	v_rcp_f32_e32 v38, v37
	v_cvt_pk_bf16_f32 v35, v40, v41
	v_add_f32_e32 v37, 1.0, v39
	v_cvt_pk_bf16_f32 v36, v42, v43
	v_rcp_f32_e32 v39, v37
	v_cvt_pk_bf16_f32 v37, v44, v45
	global_store_dwordx4 v[46:47], v[34:37], off nt
	v_pk_mul_f32 v[30:31], v[30:31], v[38:39]
	s_nop 0
	v_mul_f32_e32 v34, 0xbfb8aa3b, v32
	v_mul_f32_e32 v35, 0xbfb8aa3b, v33
	v_exp_f32_e32 v34, v34
	v_exp_f32_e32 v35, v35
	v_pk_mul_f32 v[22:23], v[30:31], v[22:23]
	v_add_u32_e32 v36, 0xa0, v154
	v_add_f32_e32 v30, 1.0, v34
	v_add_f32_e32 v31, 1.0, v35
	v_mul_f32_e32 v34, 0xbfb8aa3b, v26
	v_mul_f32_e32 v35, 0xbfb8aa3b, v27
	v_rcp_f32_e32 v30, v30
	v_rcp_f32_e32 v31, v31
	v_exp_f32_e32 v34, v34
	v_exp_f32_e32 v35, v35
	v_pk_mul_f32 v[30:31], v[32:33], v[30:31]
	v_add_f32_e32 v32, 1.0, v34
	v_add_f32_e32 v33, 1.0, v35
	v_mul_f32_e32 v34, 0xbfb8aa3b, v28
	v_mul_f32_e32 v35, 0xbfb8aa3b, v29
	v_exp_f32_e32 v34, v34
	v_exp_f32_e32 v35, v35
	v_rcp_f32_e32 v32, v32
	v_rcp_f32_e32 v33, v33
	v_add_f32_e32 v34, 1.0, v34
	v_add_f32_e32 v35, 1.0, v35
	v_rcp_f32_e32 v34, v34
	v_rcp_f32_e32 v35, v35
	v_pk_mul_f32 v[26:27], v[26:27], v[32:33]
	v_pk_mul_f32 v[24:25], v[30:31], v[24:25]
	v_pk_mul_f32 v[26:27], v[26:27], v[18:19]
	v_pk_mul_f32 v[18:19], v[28:29], v[34:35]
	s_nop 0
	v_pk_mul_f32 v[28:29], v[18:19], v[20:21]
	v_mad_i64_i32 v[18:19], s[16:17], v36, s74, v[114:115]
	v_mul_f32_e32 v20, 0xbfb8aa3b, v14
	v_lshl_add_u64 v[18:19], v[18:19], 0, s[14:15]
	v_exp_f32_e32 v21, v20
	v_mul_f32_e32 v20, 0xbfb8aa3b, v15
	v_lshl_add_u64 v[30:31], v[18:19], 0, v[138:139]
	v_cvt_pk_bf16_f32 v18, v22, v23
	v_exp_f32_e32 v23, v20
	v_add_f32_e32 v21, 1.0, v21
	v_rcp_f32_e32 v22, v21
	v_cvt_pk_bf16_f32 v19, v24, v25
	v_add_f32_e32 v21, 1.0, v23
	v_cvt_pk_bf16_f32 v20, v26, v27
	v_rcp_f32_e32 v23, v21
	v_cvt_pk_bf16_f32 v21, v28, v29
	global_store_dwordx4 v[30:31], v[18:21], off nt
	v_pk_mul_f32 v[14:15], v[14:15], v[22:23]
	s_nop 0
	v_mul_f32_e32 v18, 0xbfb8aa3b, v16
	v_mul_f32_e32 v19, 0xbfb8aa3b, v17
	v_exp_f32_e32 v18, v18
	v_exp_f32_e32 v19, v19
	v_pk_mul_f32 v[6:7], v[14:15], v[6:7]
	v_add_u32_e32 v20, 0xb0, v154
	v_add_f32_e32 v14, 1.0, v18
	v_add_f32_e32 v15, 1.0, v19
	v_mul_f32_e32 v18, 0xbfb8aa3b, v10
	v_mul_f32_e32 v19, 0xbfb8aa3b, v11
	v_rcp_f32_e32 v14, v14
	v_rcp_f32_e32 v15, v15
	v_exp_f32_e32 v18, v18
	v_exp_f32_e32 v19, v19
	v_pk_mul_f32 v[14:15], v[16:17], v[14:15]
	v_add_f32_e32 v16, 1.0, v18
	v_add_f32_e32 v17, 1.0, v19
	v_mul_f32_e32 v18, 0xbfb8aa3b, v12
	v_mul_f32_e32 v19, 0xbfb8aa3b, v13
	v_exp_f32_e32 v18, v18
	v_exp_f32_e32 v19, v19
	v_rcp_f32_e32 v16, v16
	v_rcp_f32_e32 v17, v17
	v_add_f32_e32 v18, 1.0, v18
	v_add_f32_e32 v19, 1.0, v19
	v_rcp_f32_e32 v18, v18
	v_rcp_f32_e32 v19, v19
	v_pk_mul_f32 v[10:11], v[10:11], v[16:17]
	v_pk_mul_f32 v[8:9], v[14:15], v[8:9]
	v_pk_mul_f32 v[10:11], v[10:11], v[2:3]
	v_pk_mul_f32 v[2:3], v[12:13], v[18:19]
	s_nop 0
	v_pk_mul_f32 v[12:13], v[2:3], v[4:5]
	v_mad_i64_i32 v[2:3], s[16:17], v20, s74, v[114:115]
	v_lshl_add_u64 v[2:3], v[2:3], 0, s[14:15]
	v_lshl_add_u64 v[14:15], v[2:3], 0, v[138:139]
	v_cvt_pk_bf16_f32 v2, v6, v7
	v_cvt_pk_bf16_f32 v3, v8, v9
	v_cvt_pk_bf16_f32 v4, v10, v11
	v_cvt_pk_bf16_f32 v5, v12, v13
	s_mov_b32 s15, s6
	s_mov_b32 s14, s8
	s_mov_b64 s[16:17], s[10:11]
	global_store_dwordx4 v[14:15], v[2:5], off nt
	s_cbranch_vccz .LBB0_564
	s_waitcnt vmcnt(0)
	s_cmpk_gt_u32 s33, 0xff
	s_cbranch_scc1 .LBB0_571
	s_barrier

.LBB0_1374:
	s_ashr_i32 s41, s40, 31
	s_xor_b64 s[50:51], s[18:19], -1
	s_lshl_b64 s[20:21], s[40:41], 19
	s_add_u32 s48, s65, s20
	s_addc_u32 s49, s66, s21
	s_and_b64 s[20:21], s[18:19], exec
	s_cselect_b32 s3, s49, s35
	s_cselect_b32 s5, s48, s34
	s_ashr_i32 s39, s38, 31
	s_lshl_b64 s[20:21], s[38:39], 19
	s_add_u32 s52, s67, s20
	s_addc_u32 s53, s68, s21
	s_and_b64 s[18:19], s[18:19], exec
	s_cselect_b32 s39, s53, s55
	s_cselect_b32 s41, s52, s54
	s_add_u32 s34, s34, 0x40080
	s_addc_u32 s35, s35, 0
	s_add_u32 s56, s54, 0x100
	s_addc_u32 s57, s55, 0
	s_mov_b32 vcc_lo, -2
	s_waitcnt vmcnt(0)
	ds_read_b128 v[10:13], v225
	ds_read_b128 v[14:17], v225 offset:1024
	ds_read_b128 v[26:29], v225 offset:2048
	ds_read_b128 v[30:33], v225 offset:3072
	s_add_u32 s18, s34, 0xfffc0080
	s_addc_u32 s19, s35, -1
	s_cmp_eq_u32 vcc_lo, 12
	s_cselect_b32 s19, s3, s19
	s_cselect_b32 s18, s5, s18
	s_cselect_b32 s55, s39, s57
	s_cselect_b32 s54, s41, s56
	v_lshl_add_u64 v[202:203], s[34:35], 0, v[178:179]
	s_add_i32 m0, s72, 0xc000
	ds_read_b128 v[34:37], v226
	ds_read_b128 v[38:41], v226 offset:1024
	ds_read_b128 v[50:53], v226 offset:2048
	ds_read_b128 v[54:57], v226 offset:3072
	ds_read_b128 v[186:189], v226 offset:4096
	ds_read_b128 v[190:193], v226 offset:5120
	ds_read_b128 v[194:197], v226 offset:6144
	ds_read_b128 v[198:201], v226 offset:7168
	global_load_lds_dwordx4 v[202:203], off
	v_lshl_add_u64 v[202:203], s[34:35], 0, v[180:181]
	s_add_i32 m0, s72, 0xe000
	s_nop 0
	global_load_lds_dwordx4 v[202:203], off
	ds_read_b128 v[202:205], v227
	ds_read_b128 v[206:209], v227 offset:1024
	ds_read_b128 v[210:213], v227 offset:2048
	ds_read_b128 v[214:217], v227 offset:3072
	s_waitcnt lgkmcnt(0)
	s_setprio 1
	s_barrier
	v_mfma_f32_16x16x32_bf16 v[158:161], v[10:13], v[34:37], 0
	v_mfma_f32_16x16x32_bf16 v[154:157], v[26:29], v[34:37], 0
	v_mfma_f32_16x16x32_bf16 v[142:145], v[10:13], v[50:53], 0
	v_mfma_f32_16x16x32_bf16 v[138:141], v[26:29], v[50:53], 0
	v_mfma_f32_16x16x32_bf16 v[126:129], v[10:13], v[186:189], 0
	v_mfma_f32_16x16x32_bf16 v[122:125], v[26:29], v[186:189], 0
	v_mfma_f32_16x16x32_bf16 v[110:113], v[10:13], v[194:197], 0
	v_mfma_f32_16x16x32_bf16 v[106:109], v[26:29], v[194:197], 0
	v_mfma_f32_16x16x32_bf16 v[158:161], v[14:17], v[38:41], v[158:161]
	v_mfma_f32_16x16x32_bf16 v[154:157], v[30:33], v[38:41], v[154:157]
	v_mfma_f32_16x16x32_bf16 v[142:145], v[14:17], v[54:57], v[142:145]
	v_mfma_f32_16x16x32_bf16 v[138:141], v[30:33], v[54:57], v[138:141]
	v_mfma_f32_16x16x32_bf16 v[126:129], v[14:17], v[190:193], v[126:129]
	v_mfma_f32_16x16x32_bf16 v[122:125], v[30:33], v[190:193], v[122:125]
	v_mfma_f32_16x16x32_bf16 v[110:113], v[14:17], v[198:201], v[110:113]
	v_mfma_f32_16x16x32_bf16 v[106:109], v[30:33], v[198:201], v[106:109]
	v_mfma_f32_16x16x32_bf16 v[150:153], v[202:205], v[34:37], 0
	v_mfma_f32_16x16x32_bf16 v[34:37], v[210:213], v[34:37], 0
	v_mfma_f32_16x16x32_bf16 v[150:153], v[206:209], v[38:41], v[150:153]
	v_mfma_f32_16x16x32_bf16 v[34:37], v[214:217], v[38:41], v[34:37]
	v_mfma_f32_16x16x32_bf16 v[38:41], v[202:205], v[50:53], 0
	v_mfma_f32_16x16x32_bf16 v[50:53], v[210:213], v[50:53], 0
	v_mfma_f32_16x16x32_bf16 v[114:117], v[210:213], v[186:189], 0
	v_mfma_f32_16x16x32_bf16 v[102:105], v[202:205], v[194:197], 0
	v_mfma_f32_16x16x32_bf16 v[98:101], v[210:213], v[194:197], 0
	v_mfma_f32_16x16x32_bf16 v[38:41], v[206:209], v[54:57], v[38:41]
	v_mfma_f32_16x16x32_bf16 v[50:53], v[214:217], v[54:57], v[50:53]
	v_mfma_f32_16x16x32_bf16 v[54:57], v[202:205], v[186:189], 0
	v_mfma_f32_16x16x32_bf16 v[114:117], v[214:217], v[190:193], v[114:117]
	v_mfma_f32_16x16x32_bf16 v[102:105], v[206:209], v[198:201], v[102:105]
	v_mfma_f32_16x16x32_bf16 v[98:101], v[214:217], v[198:201], v[98:101]
	v_mfma_f32_16x16x32_bf16 v[54:57], v[206:209], v[190:193], v[54:57]
	s_barrier
	s_setprio 0
	s_add_i32 s20, s33, s71
	v_lshl_add_u64 v[222:223], s[54:55], 0, v[164:165]
	s_mov_b32 m0, s20
	s_nop 0
	global_load_lds_dwordx4 v[222:223], off
	v_lshl_add_u64 v[238:239], s[54:55], 0, v[168:169]
	s_add_i32 m0, s20, 0x2000
	s_nop 0
	global_load_lds_dwordx4 v[238:239], off
	s_mov_b32 m0, s72
	v_lshl_add_u64 v[240:241], s[18:19], 0, v[162:163]
	ds_read_b128 v[118:121], v226 offset:16384
	ds_read_b128 v[130:133], v226 offset:17408
	ds_read_b128 v[134:137], v226 offset:18432
	ds_read_b128 v[146:149], v226 offset:19456
	ds_read_b128 v[186:189], v226 offset:20480
	ds_read_b128 v[190:193], v226 offset:21504
	ds_read_b128 v[194:197], v226 offset:22528
	ds_read_b128 v[198:201], v226 offset:23552
	global_load_lds_dwordx4 v[240:241], off
	v_lshl_add_u64 v[242:243], s[18:19], 0, v[166:167]
	s_mov_b32 m0, s73
	s_nop 0
	global_load_lds_dwordx4 v[242:243], off
	s_waitcnt vmcnt(6)
	s_waitcnt lgkmcnt(0)
	s_setprio 1
	s_barrier
	v_mfma_f32_16x16x32_bf16 v[94:97], v[10:13], v[118:121], 0
	v_mfma_f32_16x16x32_bf16 v[90:93], v[26:29], v[118:121], 0
	v_mfma_f32_16x16x32_bf16 v[78:81], v[10:13], v[134:137], 0
	v_mfma_f32_16x16x32_bf16 v[74:77], v[26:29], v[134:137], 0
	v_mfma_f32_16x16x32_bf16 v[62:65], v[10:13], v[186:189], 0
	v_mfma_f32_16x16x32_bf16 v[58:61], v[26:29], v[186:189], 0
	v_mfma_f32_16x16x32_bf16 v[10:13], v[10:13], v[194:197], 0
	v_mfma_f32_16x16x32_bf16 v[94:97], v[14:17], v[130:133], v[94:97]
	v_mfma_f32_16x16x32_bf16 v[90:93], v[30:33], v[130:133], v[90:93]
	v_mfma_f32_16x16x32_bf16 v[78:81], v[14:17], v[146:149], v[78:81]
	v_mfma_f32_16x16x32_bf16 v[74:77], v[30:33], v[146:149], v[74:77]
	v_mfma_f32_16x16x32_bf16 v[62:65], v[14:17], v[190:193], v[62:65]
	v_mfma_f32_16x16x32_bf16 v[58:61], v[30:33], v[190:193], v[58:61]
	v_mfma_f32_16x16x32_bf16 v[10:13], v[14:17], v[198:201], v[10:13]
	v_mfma_f32_16x16x32_bf16 v[14:17], v[26:29], v[194:197], 0
	v_mfma_f32_16x16x32_bf16 v[14:17], v[30:33], v[198:201], v[14:17]
	v_mfma_f32_16x16x32_bf16 v[18:21], v[202:205], v[118:121], 0
	v_mfma_f32_16x16x32_bf16 v[26:29], v[206:209], v[130:133], v[18:21]
	v_mfma_f32_16x16x32_bf16 v[18:21], v[210:213], v[118:121], 0
	v_mfma_f32_16x16x32_bf16 v[30:33], v[214:217], v[130:133], v[18:21]
	v_mfma_f32_16x16x32_bf16 v[18:21], v[202:205], v[134:137], 0
	v_mfma_f32_16x16x32_bf16 v[70:73], v[206:209], v[146:149], v[18:21]
	v_mfma_f32_16x16x32_bf16 v[18:21], v[210:213], v[134:137], 0
	v_mfma_f32_16x16x32_bf16 v[66:69], v[214:217], v[146:149], v[18:21]
	v_mfma_f32_16x16x32_bf16 v[18:21], v[202:205], v[186:189], 0
	v_mfma_f32_16x16x32_bf16 v[46:49], v[206:209], v[190:193], v[18:21]
	v_mfma_f32_16x16x32_bf16 v[18:21], v[210:213], v[186:189], 0
	v_mfma_f32_16x16x32_bf16 v[6:9], v[202:205], v[194:197], 0
	v_mfma_f32_16x16x32_bf16 v[2:5], v[210:213], v[194:197], 0
	v_mfma_f32_16x16x32_bf16 v[42:45], v[214:217], v[190:193], v[18:21]
	v_mfma_f32_16x16x32_bf16 v[6:9], v[206:209], v[198:201], v[6:9]
	v_mfma_f32_16x16x32_bf16 v[2:5], v[214:217], v[198:201], v[2:5]
	s_barrier
	s_setprio 0
	s_add_u32 s20, s54, 0x40000
	s_addc_u32 s21, s55, 0
	s_add_i32 s60, s64, s71
	v_lshl_add_u64 v[246:247], s[20:21], 0, v[164:165]
	s_mov_b32 m0, s60
	s_nop 0
	global_load_lds_dwordx4 v[246:247], off
	v_lshl_add_u64 v[246:247], s[20:21], 0, v[168:169]
	s_add_i32 m0, s60, 0x2000
	s_nop 0
	global_load_lds_dwordx4 v[246:247], off
	s_add_i32 s20, 0, 0x18000
	v_add_u32_e32 v86, s20, v175
	ds_read_b128 v[18:21], v86
	ds_read_b128 v[22:25], v86 offset:1024
	ds_read_b128 v[82:85], v86 offset:2048
	ds_read_b128 v[86:89], v86 offset:3072
	s_add_u32 s18, s18, 0x40000
	s_addc_u32 s19, s19, 0
	s_mov_b32 m0, s74
	v_lshl_add_u64 v[134:135], s[18:19], 0, v[162:163]
	ds_read_b128 v[118:121], v226 offset:32768
	ds_read_b128 v[130:133], v226 offset:33792
	ds_read_b128 v[186:189], v226 offset:34816
	ds_read_b128 v[190:193], v226 offset:35840
	ds_read_b128 v[194:197], v226 offset:36864
	ds_read_b128 v[198:201], v226 offset:37888
	ds_read_b128 v[202:205], v226 offset:38912
	ds_read_b128 v[206:209], v226 offset:39936
	global_load_lds_dwordx4 v[134:135], off
	v_lshl_add_u64 v[134:135], s[18:19], 0, v[166:167]
	s_mov_b32 m0, s75
	s_nop 0
	global_load_lds_dwordx4 v[134:135], off
	s_add_i32 s21, 0, 0x1c000
	v_add_u32_e32 v244, s21, v175
	ds_read_b128 v[210:213], v244
	ds_read_b128 v[214:217], v244 offset:1024
	ds_read_b128 v[218:221], v244 offset:2048
	ds_read_b128 v[234:237], v244 offset:3072
	s_waitcnt vmcnt(8)
	s_waitcnt lgkmcnt(0)
	s_setprio 1
	s_barrier
	v_mfma_f32_16x16x32_bf16 v[134:137], v[18:21], v[118:121], v[158:161]
	v_mfma_f32_16x16x32_bf16 v[158:161], v[22:25], v[130:133], v[134:137]
	v_mfma_f32_16x16x32_bf16 v[134:137], v[82:85], v[118:121], v[154:157]
	v_mfma_f32_16x16x32_bf16 v[154:157], v[86:89], v[130:133], v[134:137]
	v_mfma_f32_16x16x32_bf16 v[134:137], v[18:21], v[186:189], v[142:145]
	v_mfma_f32_16x16x32_bf16 v[142:145], v[22:25], v[190:193], v[134:137]
	v_mfma_f32_16x16x32_bf16 v[134:137], v[82:85], v[186:189], v[138:141]
	v_mfma_f32_16x16x32_bf16 v[126:129], v[18:21], v[194:197], v[126:129]
	v_mfma_f32_16x16x32_bf16 v[122:125], v[82:85], v[194:197], v[122:125]
	v_mfma_f32_16x16x32_bf16 v[110:113], v[18:21], v[202:205], v[110:113]
	v_mfma_f32_16x16x32_bf16 v[106:109], v[82:85], v[202:205], v[106:109]
	v_mfma_f32_16x16x32_bf16 v[138:141], v[86:89], v[190:193], v[134:137]
	v_mfma_f32_16x16x32_bf16 v[126:129], v[22:25], v[198:201], v[126:129]
	v_mfma_f32_16x16x32_bf16 v[122:125], v[86:89], v[198:201], v[122:125]
	v_mfma_f32_16x16x32_bf16 v[110:113], v[22:25], v[206:209], v[110:113]
	v_mfma_f32_16x16x32_bf16 v[106:109], v[86:89], v[206:209], v[106:109]
	v_mfma_f32_16x16x32_bf16 v[34:37], v[218:221], v[118:121], v[34:37]
	v_mfma_f32_16x16x32_bf16 v[134:137], v[210:213], v[118:121], v[150:153]
	v_mfma_f32_16x16x32_bf16 v[146:149], v[234:237], v[130:133], v[34:37]
	v_mfma_f32_16x16x32_bf16 v[34:37], v[210:213], v[186:189], v[38:41]
	v_mfma_f32_16x16x32_bf16 v[150:153], v[214:217], v[130:133], v[134:137]
	v_mfma_f32_16x16x32_bf16 v[134:137], v[214:217], v[190:193], v[34:37]
	v_mfma_f32_16x16x32_bf16 v[34:37], v[218:221], v[186:189], v[50:53]
	v_mfma_f32_16x16x32_bf16 v[130:133], v[234:237], v[190:193], v[34:37]
	v_mfma_f32_16x16x32_bf16 v[34:37], v[210:213], v[194:197], v[54:57]
	v_mfma_f32_16x16x32_bf16 v[118:121], v[214:217], v[198:201], v[34:37]
	v_mfma_f32_16x16x32_bf16 v[34:37], v[218:221], v[194:197], v[114:117]
	v_mfma_f32_16x16x32_bf16 v[114:117], v[234:237], v[198:201], v[34:37]
	v_mfma_f32_16x16x32_bf16 v[34:37], v[210:213], v[202:205], v[102:105]
	v_mfma_f32_16x16x32_bf16 v[102:105], v[214:217], v[206:209], v[34:37]
	v_mfma_f32_16x16x32_bf16 v[34:37], v[218:221], v[202:205], v[98:101]
	v_mfma_f32_16x16x32_bf16 v[98:101], v[234:237], v[206:209], v[34:37]
	s_barrier
	s_setprio 0
	s_add_i32 s18, s20, s71
	v_lshl_add_u64 v[248:249], v[222:223], 0, s[24:25]
	s_mov_b32 m0, s18
	s_nop 0
	global_load_lds_dwordx4 v[248:249], off
	v_lshl_add_u64 v[248:249], v[238:239], 0, s[24:25]
	s_add_i32 m0, s18, 0x2000
	s_nop 0
	global_load_lds_dwordx4 v[248:249], off
	s_mov_b32 m0, s95
	v_lshl_add_u64 v[202:203], v[240:241], 0, s[24:25]
	s_nop 2
	ds_read_b128 v[34:37], v226 offset:49152
	ds_read_b128 v[38:41], v226 offset:50176
	ds_read_b128 v[50:53], v226 offset:51200
	ds_read_b128 v[54:57], v226 offset:52224
	ds_read_b128 v[186:189], v226 offset:53248
	ds_read_b128 v[190:193], v226 offset:54272
	ds_read_b128 v[194:197], v226 offset:55296
	ds_read_b128 v[198:201], v226 offset:56320
	global_load_lds_dwordx4 v[202:203], off
	v_lshl_add_u64 v[202:203], v[242:243], 0, s[24:25]
	s_mov_b32 m0, s96
	s_nop 0
	global_load_lds_dwordx4 v[202:203], off
	s_add_u32 s18, s54, 0x40080
	s_addc_u32 s19, s55, 0
	s_add_i32 s20, s21, s71
	v_lshl_add_u64 v[250:251], s[18:19], 0, v[164:165]
	s_mov_b32 m0, s20
	s_nop 0
	global_load_lds_dwordx4 v[250:251], off
	v_lshl_add_u64 v[250:251], s[18:19], 0, v[168:169]
	s_add_i32 m0, s20, 0x2000
	s_nop 0
	global_load_lds_dwordx4 v[250:251], off
	s_waitcnt vmcnt(6)
	s_waitcnt lgkmcnt(0)
	s_setprio 1
	s_barrier
	v_mfma_f32_16x16x32_bf16 v[94:97], v[18:21], v[34:37], v[94:97]
	v_mfma_f32_16x16x32_bf16 v[78:81], v[18:21], v[50:53], v[78:81]
	v_mfma_f32_16x16x32_bf16 v[62:65], v[18:21], v[186:189], v[62:65]
	v_mfma_f32_16x16x32_bf16 v[10:13], v[18:21], v[194:197], v[10:13]
	v_mfma_f32_16x16x32_bf16 v[94:97], v[22:25], v[38:41], v[94:97]
	v_mfma_f32_16x16x32_bf16 v[90:93], v[82:85], v[34:37], v[90:93]
	v_mfma_f32_16x16x32_bf16 v[78:81], v[22:25], v[54:57], v[78:81]
	v_mfma_f32_16x16x32_bf16 v[74:77], v[82:85], v[50:53], v[74:77]
	v_mfma_f32_16x16x32_bf16 v[62:65], v[22:25], v[190:193], v[62:65]
	v_mfma_f32_16x16x32_bf16 v[58:61], v[82:85], v[186:189], v[58:61]
	v_mfma_f32_16x16x32_bf16 v[22:25], v[22:25], v[198:201], v[10:13]
	v_mfma_f32_16x16x32_bf16 v[10:13], v[82:85], v[194:197], v[14:17]
	v_mfma_f32_16x16x32_bf16 v[90:93], v[86:89], v[38:41], v[90:93]
	v_mfma_f32_16x16x32_bf16 v[74:77], v[86:89], v[54:57], v[74:77]
	v_mfma_f32_16x16x32_bf16 v[58:61], v[86:89], v[190:193], v[58:61]
	v_mfma_f32_16x16x32_bf16 v[18:21], v[86:89], v[198:201], v[10:13]
	v_mfma_f32_16x16x32_bf16 v[10:13], v[210:213], v[34:37], v[26:29]
	v_mfma_f32_16x16x32_bf16 v[86:89], v[214:217], v[38:41], v[10:13]
	v_mfma_f32_16x16x32_bf16 v[10:13], v[218:221], v[34:37], v[30:33]
	v_mfma_f32_16x16x32_bf16 v[82:85], v[234:237], v[38:41], v[10:13]
	v_mfma_f32_16x16x32_bf16 v[10:13], v[210:213], v[50:53], v[70:73]
	v_mfma_f32_16x16x32_bf16 v[70:73], v[214:217], v[54:57], v[10:13]
	v_mfma_f32_16x16x32_bf16 v[10:13], v[218:221], v[50:53], v[66:69]
	v_mfma_f32_16x16x32_bf16 v[66:69], v[234:237], v[54:57], v[10:13]
	v_mfma_f32_16x16x32_bf16 v[10:13], v[210:213], v[186:189], v[46:49]
	v_mfma_f32_16x16x32_bf16 v[46:49], v[214:217], v[190:193], v[10:13]
	v_mfma_f32_16x16x32_bf16 v[10:13], v[218:221], v[186:189], v[42:45]
	v_mfma_f32_16x16x32_bf16 v[6:9], v[210:213], v[194:197], v[6:9]
	v_mfma_f32_16x16x32_bf16 v[2:5], v[218:221], v[194:197], v[2:5]
	v_mfma_f32_16x16x32_bf16 v[42:45], v[234:237], v[190:193], v[10:13]
	v_mfma_f32_16x16x32_bf16 v[6:9], v[214:217], v[198:201], v[6:9]
	v_mfma_f32_16x16x32_bf16 v[2:5], v[234:237], v[198:201], v[2:5]
	s_barrier
	s_setprio 0
	s_add_i32 vcc_lo, vcc_lo, 2
	s_add_u32 s34, s34, 0x100
	s_addc_u32 s35, s35, 0
	s_add_u32 s56, s56, 0x100
	s_addc_u32 s57, s57, 0
	s_cmp_gt_u32 vcc_lo, 13
.LBB0_1375:
	ds_read_b128 v[10:13], v225
	ds_read_b128 v[14:17], v225 offset:1024
	ds_read_b128 v[26:29], v225 offset:2048
	ds_read_b128 v[30:33], v225 offset:3072
	s_add_u32 s18, s34, 0xfffc0080
	s_addc_u32 s19, s35, -1
	s_cmp_eq_u32 vcc_lo, 12
	s_cselect_b32 s19, s3, s19
	s_cselect_b32 s18, s5, s18
	s_cselect_b32 s55, s39, s57
	s_cselect_b32 s54, s41, s56
	v_lshl_add_u64 v[202:203], s[34:35], 0, v[178:179]
	s_add_i32 m0, s72, 0xc000
	ds_read_b128 v[34:37], v226
	ds_read_b128 v[38:41], v226 offset:1024
	ds_read_b128 v[50:53], v226 offset:2048
	ds_read_b128 v[54:57], v226 offset:3072
	ds_read_b128 v[186:189], v226 offset:4096
	ds_read_b128 v[190:193], v226 offset:5120
	ds_read_b128 v[194:197], v226 offset:6144
	ds_read_b128 v[198:201], v226 offset:7168
	global_load_lds_dwordx4 v[202:203], off
	v_lshl_add_u64 v[202:203], s[34:35], 0, v[180:181]
	s_add_i32 m0, s72, 0xe000
	s_nop 0
	global_load_lds_dwordx4 v[202:203], off
	ds_read_b128 v[202:205], v227
	ds_read_b128 v[206:209], v227 offset:1024
	ds_read_b128 v[210:213], v227 offset:2048
	ds_read_b128 v[214:217], v227 offset:3072
	s_waitcnt lgkmcnt(0)
	s_setprio 1
	s_barrier
	v_mfma_f32_16x16x32_bf16 v[158:161], v[10:13], v[34:37], v[158:161]
	v_mfma_f32_16x16x32_bf16 v[154:157], v[26:29], v[34:37], v[154:157]
	v_mfma_f32_16x16x32_bf16 v[142:145], v[10:13], v[50:53], v[142:145]
	v_mfma_f32_16x16x32_bf16 v[138:141], v[26:29], v[50:53], v[138:141]
	v_mfma_f32_16x16x32_bf16 v[126:129], v[10:13], v[186:189], v[126:129]
	v_mfma_f32_16x16x32_bf16 v[122:125], v[26:29], v[186:189], v[122:125]
	v_mfma_f32_16x16x32_bf16 v[110:113], v[10:13], v[194:197], v[110:113]
	v_mfma_f32_16x16x32_bf16 v[106:109], v[26:29], v[194:197], v[106:109]
	v_mfma_f32_16x16x32_bf16 v[158:161], v[14:17], v[38:41], v[158:161]
	v_mfma_f32_16x16x32_bf16 v[154:157], v[30:33], v[38:41], v[154:157]
	v_mfma_f32_16x16x32_bf16 v[142:145], v[14:17], v[54:57], v[142:145]
	v_mfma_f32_16x16x32_bf16 v[138:141], v[30:33], v[54:57], v[138:141]
	v_mfma_f32_16x16x32_bf16 v[126:129], v[14:17], v[190:193], v[126:129]
	v_mfma_f32_16x16x32_bf16 v[122:125], v[30:33], v[190:193], v[122:125]
	v_mfma_f32_16x16x32_bf16 v[110:113], v[14:17], v[198:201], v[110:113]
	v_mfma_f32_16x16x32_bf16 v[106:109], v[30:33], v[198:201], v[106:109]
	v_mfma_f32_16x16x32_bf16 v[150:153], v[202:205], v[34:37], v[150:153]
	v_mfma_f32_16x16x32_bf16 v[34:37], v[210:213], v[34:37], v[146:149]
	v_mfma_f32_16x16x32_bf16 v[150:153], v[206:209], v[38:41], v[150:153]
	v_mfma_f32_16x16x32_bf16 v[34:37], v[214:217], v[38:41], v[34:37]
	v_mfma_f32_16x16x32_bf16 v[38:41], v[202:205], v[50:53], v[134:137]
	v_mfma_f32_16x16x32_bf16 v[50:53], v[210:213], v[50:53], v[130:133]
	v_mfma_f32_16x16x32_bf16 v[114:117], v[210:213], v[186:189], v[114:117]
	v_mfma_f32_16x16x32_bf16 v[102:105], v[202:205], v[194:197], v[102:105]
	v_mfma_f32_16x16x32_bf16 v[98:101], v[210:213], v[194:197], v[98:101]
	v_mfma_f32_16x16x32_bf16 v[38:41], v[206:209], v[54:57], v[38:41]
	v_mfma_f32_16x16x32_bf16 v[50:53], v[214:217], v[54:57], v[50:53]
	v_mfma_f32_16x16x32_bf16 v[54:57], v[202:205], v[186:189], v[118:121]
	v_mfma_f32_16x16x32_bf16 v[114:117], v[214:217], v[190:193], v[114:117]
	v_mfma_f32_16x16x32_bf16 v[102:105], v[206:209], v[198:201], v[102:105]
	v_mfma_f32_16x16x32_bf16 v[98:101], v[214:217], v[198:201], v[98:101]
	v_mfma_f32_16x16x32_bf16 v[54:57], v[206:209], v[190:193], v[54:57]
	s_barrier
	s_setprio 0
	s_add_i32 s20, s33, s71
	v_lshl_add_u64 v[222:223], s[54:55], 0, v[164:165]
	s_mov_b32 m0, s20
	s_nop 0
	global_load_lds_dwordx4 v[222:223], off
	v_lshl_add_u64 v[238:239], s[54:55], 0, v[168:169]
	s_add_i32 m0, s20, 0x2000
	s_nop 0
	global_load_lds_dwordx4 v[238:239], off
	s_mov_b32 m0, s72
	v_lshl_add_u64 v[240:241], s[18:19], 0, v[162:163]
	ds_read_b128 v[118:121], v226 offset:16384
	ds_read_b128 v[130:133], v226 offset:17408
	ds_read_b128 v[134:137], v226 offset:18432
	ds_read_b128 v[146:149], v226 offset:19456
	ds_read_b128 v[186:189], v226 offset:20480
	ds_read_b128 v[190:193], v226 offset:21504
	ds_read_b128 v[194:197], v226 offset:22528
	ds_read_b128 v[198:201], v226 offset:23552
	global_load_lds_dwordx4 v[240:241], off
	v_lshl_add_u64 v[242:243], s[18:19], 0, v[166:167]
	s_mov_b32 m0, s73
	s_nop 0
	global_load_lds_dwordx4 v[242:243], off
	s_waitcnt vmcnt(6)
	s_waitcnt lgkmcnt(0)
	s_setprio 1
	s_barrier
	v_mfma_f32_16x16x32_bf16 v[94:97], v[10:13], v[118:121], v[94:97]
	v_mfma_f32_16x16x32_bf16 v[90:93], v[26:29], v[118:121], v[90:93]
	v_mfma_f32_16x16x32_bf16 v[78:81], v[10:13], v[134:137], v[78:81]
	v_mfma_f32_16x16x32_bf16 v[74:77], v[26:29], v[134:137], v[74:77]
	v_mfma_f32_16x16x32_bf16 v[62:65], v[10:13], v[186:189], v[62:65]
	v_mfma_f32_16x16x32_bf16 v[58:61], v[26:29], v[186:189], v[58:61]
	v_mfma_f32_16x16x32_bf16 v[10:13], v[10:13], v[194:197], v[22:25]
	v_mfma_f32_16x16x32_bf16 v[94:97], v[14:17], v[130:133], v[94:97]
	v_mfma_f32_16x16x32_bf16 v[90:93], v[30:33], v[130:133], v[90:93]
	v_mfma_f32_16x16x32_bf16 v[78:81], v[14:17], v[146:149], v[78:81]
	v_mfma_f32_16x16x32_bf16 v[74:77], v[30:33], v[146:149], v[74:77]
	v_mfma_f32_16x16x32_bf16 v[62:65], v[14:17], v[190:193], v[62:65]
	v_mfma_f32_16x16x32_bf16 v[58:61], v[30:33], v[190:193], v[58:61]
	v_mfma_f32_16x16x32_bf16 v[10:13], v[14:17], v[198:201], v[10:13]
	v_mfma_f32_16x16x32_bf16 v[14:17], v[26:29], v[194:197], v[18:21]
	v_mfma_f32_16x16x32_bf16 v[14:17], v[30:33], v[198:201], v[14:17]
	v_mfma_f32_16x16x32_bf16 v[18:21], v[202:205], v[118:121], v[86:89]
	v_mfma_f32_16x16x32_bf16 v[26:29], v[206:209], v[130:133], v[18:21]
	v_mfma_f32_16x16x32_bf16 v[18:21], v[210:213], v[118:121], v[82:85]
	v_mfma_f32_16x16x32_bf16 v[30:33], v[214:217], v[130:133], v[18:21]
	v_mfma_f32_16x16x32_bf16 v[18:21], v[202:205], v[134:137], v[70:73]
	v_mfma_f32_16x16x32_bf16 v[70:73], v[206:209], v[146:149], v[18:21]
	v_mfma_f32_16x16x32_bf16 v[18:21], v[210:213], v[134:137], v[66:69]
	v_mfma_f32_16x16x32_bf16 v[66:69], v[214:217], v[146:149], v[18:21]
	v_mfma_f32_16x16x32_bf16 v[18:21], v[202:205], v[186:189], v[46:49]
	v_mfma_f32_16x16x32_bf16 v[46:49], v[206:209], v[190:193], v[18:21]
	v_mfma_f32_16x16x32_bf16 v[18:21], v[210:213], v[186:189], v[42:45]
	v_mfma_f32_16x16x32_bf16 v[6:9], v[202:205], v[194:197], v[6:9]
	v_mfma_f32_16x16x32_bf16 v[2:5], v[210:213], v[194:197], v[2:5]
	v_mfma_f32_16x16x32_bf16 v[42:45], v[214:217], v[190:193], v[18:21]
	v_mfma_f32_16x16x32_bf16 v[6:9], v[206:209], v[198:201], v[6:9]
	v_mfma_f32_16x16x32_bf16 v[2:5], v[214:217], v[198:201], v[2:5]
	s_barrier
	s_setprio 0
	s_add_u32 s20, s54, 0x40000
	s_addc_u32 s21, s55, 0
	s_add_i32 s60, s64, s71
	v_lshl_add_u64 v[246:247], s[20:21], 0, v[164:165]
	s_mov_b32 m0, s60
	s_nop 0
	global_load_lds_dwordx4 v[246:247], off
	v_lshl_add_u64 v[246:247], s[20:21], 0, v[168:169]
	s_add_i32 m0, s60, 0x2000
	s_nop 0
	global_load_lds_dwordx4 v[246:247], off
	s_add_i32 s20, 0, 0x18000
	v_add_u32_e32 v86, s20, v175
	ds_read_b128 v[18:21], v86
	ds_read_b128 v[22:25], v86 offset:1024
	ds_read_b128 v[82:85], v86 offset:2048
	ds_read_b128 v[86:89], v86 offset:3072
	s_add_u32 s18, s18, 0x40000
	s_addc_u32 s19, s19, 0
	s_mov_b32 m0, s74
	v_lshl_add_u64 v[134:135], s[18:19], 0, v[162:163]
	ds_read_b128 v[118:121], v226 offset:32768
	ds_read_b128 v[130:133], v226 offset:33792
	ds_read_b128 v[186:189], v226 offset:34816
	ds_read_b128 v[190:193], v226 offset:35840
	ds_read_b128 v[194:197], v226 offset:36864
	ds_read_b128 v[198:201], v226 offset:37888
	ds_read_b128 v[202:205], v226 offset:38912
	ds_read_b128 v[206:209], v226 offset:39936
	global_load_lds_dwordx4 v[134:135], off
	v_lshl_add_u64 v[134:135], s[18:19], 0, v[166:167]
	s_mov_b32 m0, s75
	s_nop 0
	global_load_lds_dwordx4 v[134:135], off
	s_add_i32 s21, 0, 0x1c000
	v_add_u32_e32 v244, s21, v175
	ds_read_b128 v[210:213], v244
	ds_read_b128 v[214:217], v244 offset:1024
	ds_read_b128 v[218:221], v244 offset:2048
	ds_read_b128 v[234:237], v244 offset:3072
	s_waitcnt vmcnt(8)
	s_waitcnt lgkmcnt(0)
	s_setprio 1
	s_barrier
	v_mfma_f32_16x16x32_bf16 v[134:137], v[18:21], v[118:121], v[158:161]
	v_mfma_f32_16x16x32_bf16 v[158:161], v[22:25], v[130:133], v[134:137]
	v_mfma_f32_16x16x32_bf16 v[134:137], v[82:85], v[118:121], v[154:157]
	v_mfma_f32_16x16x32_bf16 v[154:157], v[86:89], v[130:133], v[134:137]
	v_mfma_f32_16x16x32_bf16 v[134:137], v[18:21], v[186:189], v[142:145]
	v_mfma_f32_16x16x32_bf16 v[142:145], v[22:25], v[190:193], v[134:137]
	v_mfma_f32_16x16x32_bf16 v[134:137], v[82:85], v[186:189], v[138:141]
	v_mfma_f32_16x16x32_bf16 v[126:129], v[18:21], v[194:197], v[126:129]
	v_mfma_f32_16x16x32_bf16 v[122:125], v[82:85], v[194:197], v[122:125]
	v_mfma_f32_16x16x32_bf16 v[110:113], v[18:21], v[202:205], v[110:113]
	v_mfma_f32_16x16x32_bf16 v[106:109], v[82:85], v[202:205], v[106:109]
	v_mfma_f32_16x16x32_bf16 v[138:141], v[86:89], v[190:193], v[134:137]
	v_mfma_f32_16x16x32_bf16 v[126:129], v[22:25], v[198:201], v[126:129]
	v_mfma_f32_16x16x32_bf16 v[122:125], v[86:89], v[198:201], v[122:125]
	v_mfma_f32_16x16x32_bf16 v[110:113], v[22:25], v[206:209], v[110:113]
	v_mfma_f32_16x16x32_bf16 v[106:109], v[86:89], v[206:209], v[106:109]
	v_mfma_f32_16x16x32_bf16 v[34:37], v[218:221], v[118:121], v[34:37]
	v_mfma_f32_16x16x32_bf16 v[134:137], v[210:213], v[118:121], v[150:153]
	v_mfma_f32_16x16x32_bf16 v[146:149], v[234:237], v[130:133], v[34:37]
	v_mfma_f32_16x16x32_bf16 v[34:37], v[210:213], v[186:189], v[38:41]
	v_mfma_f32_16x16x32_bf16 v[150:153], v[214:217], v[130:133], v[134:137]
	v_mfma_f32_16x16x32_bf16 v[134:137], v[214:217], v[190:193], v[34:37]
	v_mfma_f32_16x16x32_bf16 v[34:37], v[218:221], v[186:189], v[50:53]
	v_mfma_f32_16x16x32_bf16 v[130:133], v[234:237], v[190:193], v[34:37]
	v_mfma_f32_16x16x32_bf16 v[34:37], v[210:213], v[194:197], v[54:57]
	v_mfma_f32_16x16x32_bf16 v[118:121], v[214:217], v[198:201], v[34:37]
	v_mfma_f32_16x16x32_bf16 v[34:37], v[218:221], v[194:197], v[114:117]
	v_mfma_f32_16x16x32_bf16 v[114:117], v[234:237], v[198:201], v[34:37]
	v_mfma_f32_16x16x32_bf16 v[34:37], v[210:213], v[202:205], v[102:105]
	v_mfma_f32_16x16x32_bf16 v[102:105], v[214:217], v[206:209], v[34:37]
	v_mfma_f32_16x16x32_bf16 v[34:37], v[218:221], v[202:205], v[98:101]
	v_mfma_f32_16x16x32_bf16 v[98:101], v[234:237], v[206:209], v[34:37]
	s_barrier
	s_setprio 0
	s_add_i32 s18, s20, s71
	v_lshl_add_u64 v[248:249], v[222:223], 0, s[24:25]
	s_mov_b32 m0, s18
	s_nop 0
	global_load_lds_dwordx4 v[248:249], off
	v_lshl_add_u64 v[248:249], v[238:239], 0, s[24:25]
	s_add_i32 m0, s18, 0x2000
	s_nop 0
	global_load_lds_dwordx4 v[248:249], off
	s_mov_b32 m0, s95
	v_lshl_add_u64 v[202:203], v[240:241], 0, s[24:25]
	s_nop 2
	ds_read_b128 v[34:37], v226 offset:49152
	ds_read_b128 v[38:41], v226 offset:50176
	ds_read_b128 v[50:53], v226 offset:51200
	ds_read_b128 v[54:57], v226 offset:52224
	ds_read_b128 v[186:189], v226 offset:53248
	ds_read_b128 v[190:193], v226 offset:54272
	ds_read_b128 v[194:197], v226 offset:55296
	ds_read_b128 v[198:201], v226 offset:56320
	global_load_lds_dwordx4 v[202:203], off
	v_lshl_add_u64 v[202:203], v[242:243], 0, s[24:25]
	s_mov_b32 m0, s96
	s_nop 0
	global_load_lds_dwordx4 v[202:203], off
	s_add_u32 s18, s54, 0x40080
	s_addc_u32 s19, s55, 0
	s_add_i32 s20, s21, s71
	v_lshl_add_u64 v[250:251], s[18:19], 0, v[164:165]
	s_mov_b32 m0, s20
	s_nop 0
	global_load_lds_dwordx4 v[250:251], off
	v_lshl_add_u64 v[250:251], s[18:19], 0, v[168:169]
	s_add_i32 m0, s20, 0x2000
	s_nop 0
	global_load_lds_dwordx4 v[250:251], off
	s_waitcnt vmcnt(6)
	s_waitcnt lgkmcnt(0)
	s_setprio 1
	s_barrier
	v_mfma_f32_16x16x32_bf16 v[94:97], v[18:21], v[34:37], v[94:97]
	v_mfma_f32_16x16x32_bf16 v[78:81], v[18:21], v[50:53], v[78:81]
	v_mfma_f32_16x16x32_bf16 v[62:65], v[18:21], v[186:189], v[62:65]
	v_mfma_f32_16x16x32_bf16 v[10:13], v[18:21], v[194:197], v[10:13]
	v_mfma_f32_16x16x32_bf16 v[94:97], v[22:25], v[38:41], v[94:97]
	v_mfma_f32_16x16x32_bf16 v[90:93], v[82:85], v[34:37], v[90:93]
	v_mfma_f32_16x16x32_bf16 v[78:81], v[22:25], v[54:57], v[78:81]
	v_mfma_f32_16x16x32_bf16 v[74:77], v[82:85], v[50:53], v[74:77]
	v_mfma_f32_16x16x32_bf16 v[62:65], v[22:25], v[190:193], v[62:65]
	v_mfma_f32_16x16x32_bf16 v[58:61], v[82:85], v[186:189], v[58:61]
	v_mfma_f32_16x16x32_bf16 v[22:25], v[22:25], v[198:201], v[10:13]
	v_mfma_f32_16x16x32_bf16 v[10:13], v[82:85], v[194:197], v[14:17]
	v_mfma_f32_16x16x32_bf16 v[90:93], v[86:89], v[38:41], v[90:93]
	v_mfma_f32_16x16x32_bf16 v[74:77], v[86:89], v[54:57], v[74:77]
	v_mfma_f32_16x16x32_bf16 v[58:61], v[86:89], v[190:193], v[58:61]
	v_mfma_f32_16x16x32_bf16 v[18:21], v[86:89], v[198:201], v[10:13]
	v_mfma_f32_16x16x32_bf16 v[10:13], v[210:213], v[34:37], v[26:29]
	v_mfma_f32_16x16x32_bf16 v[86:89], v[214:217], v[38:41], v[10:13]
	v_mfma_f32_16x16x32_bf16 v[10:13], v[218:221], v[34:37], v[30:33]
	v_mfma_f32_16x16x32_bf16 v[82:85], v[234:237], v[38:41], v[10:13]
	v_mfma_f32_16x16x32_bf16 v[10:13], v[210:213], v[50:53], v[70:73]
	v_mfma_f32_16x16x32_bf16 v[70:73], v[214:217], v[54:57], v[10:13]
	v_mfma_f32_16x16x32_bf16 v[10:13], v[218:221], v[50:53], v[66:69]
	v_mfma_f32_16x16x32_bf16 v[66:69], v[234:237], v[54:57], v[10:13]
	v_mfma_f32_16x16x32_bf16 v[10:13], v[210:213], v[186:189], v[46:49]
	v_mfma_f32_16x16x32_bf16 v[46:49], v[214:217], v[190:193], v[10:13]
	v_mfma_f32_16x16x32_bf16 v[10:13], v[218:221], v[186:189], v[42:45]
	v_mfma_f32_16x16x32_bf16 v[6:9], v[210:213], v[194:197], v[6:9]
	v_mfma_f32_16x16x32_bf16 v[2:5], v[218:221], v[194:197], v[2:5]
	v_mfma_f32_16x16x32_bf16 v[42:45], v[234:237], v[190:193], v[10:13]
	v_mfma_f32_16x16x32_bf16 v[6:9], v[214:217], v[198:201], v[6:9]
	v_mfma_f32_16x16x32_bf16 v[2:5], v[234:237], v[198:201], v[2:5]
	s_barrier
	s_setprio 0
	s_add_i32 vcc_lo, vcc_lo, 2
	s_add_u32 s34, s34, 0x100
	s_addc_u32 s35, s35, 0
	s_add_u32 s56, s56, 0x100
	s_addc_u32 s57, s57, 0
	s_cmp_gt_u32 vcc_lo, 13
	s_cbranch_scc0 .LBB0_1375
	s_min_i32 s3, s4, 0x80
	s_ashr_i32 s5, s3, 3
	s_lshl_b32 s3, s2, 8
	s_mul_hi_i32 s19, s5, 0x6000
	s_mulk_i32 s5, 0x6000
	v_or_b32_e32 v186, s3, v224
	s_add_u32 s18, s77, s5
	s_addc_u32 s19, s78, s19
	v_ashrrev_i32_e32 v187, 31, v186
	v_lshl_add_u64 v[10:11], v[186:187], 2, s[18:19]
	global_load_dwordx4 v[50:53], v[10:11], off offset:16
	global_load_dwordx4 v[54:57], v[10:11], off
	global_load_dwordx4 v[26:29], v[10:11], off offset:528
	global_load_dwordx4 v[30:33], v[10:11], off offset:512
	s_add_i32 s5, s2, -2
	s_cmp_gt_u32 s5, 3
	s_cbranch_scc1 .LBB0_1378
	v_lshl_add_u64 v[14:15], v[186:187], 2, s[6:7]
	global_load_dwordx4 v[38:41], v[14:15], off offset:-2048
	global_load_dwordx4 v[34:37], v[14:15], off offset:-2032
	global_load_dwordx4 v[10:13], v[14:15], off offset:-1536
	s_nop 0
	global_load_dwordx4 v[14:17], v[14:15], off offset:-1520

.LBB0_2625:
	v_add_u32_e32 v142, s57, v161
	ds_read_b128 v[130:133], v142
	ds_read_b128 v[134:137], v142 offset:1024
	ds_read_b128 v[138:141], v142 offset:2048
	ds_read_b128 v[142:145], v142 offset:3072
	s_add_u32 s18, s38, 0xfffc0080
	s_addc_u32 s19, s39, -1
	s_cmp_eq_u32 s72, 4
	s_cselect_b32 s19, s25, s19
	s_cselect_b32 s18, s68, s18
	s_cselect_b32 s43, s17, s71
	s_cselect_b32 s42, s69, s70
	v_lshl_add_u64 v[204:205], s[38:39], 0, v[164:165]
	s_add_i32 m0, s50, 0xc000
	ds_read_b128 v[146:149], v171
	ds_read_b128 v[176:179], v171 offset:1024
	ds_read_b128 v[180:183], v171 offset:2048
	ds_read_b128 v[184:187], v171 offset:3072
	ds_read_b128 v[188:191], v171 offset:4096
	ds_read_b128 v[192:195], v171 offset:5120
	ds_read_b128 v[196:199], v171 offset:6144
	ds_read_b128 v[200:203], v171 offset:7168
	global_load_lds_dwordx4 v[204:205], off
	v_lshl_add_u64 v[204:205], s[38:39], 0, v[166:167]
	s_add_i32 m0, s50, 0xe000
	s_nop 0
	global_load_lds_dwordx4 v[204:205], off
	v_add_u32_e32 v158, s60, v161
	ds_read_b128 v[204:207], v158
	ds_read_b128 v[208:211], v158 offset:1024
	ds_read_b128 v[212:215], v158 offset:2048
	ds_read_b128 v[216:219], v158 offset:3072
	s_waitcnt lgkmcnt(0)
	s_setprio 1
	s_barrier
	v_mfma_f32_16x16x32_bf16 v[126:129], v[130:133], v[146:149], v[126:129]
	v_mfma_f32_16x16x32_bf16 v[122:125], v[138:141], v[146:149], v[122:125]
	v_mfma_f32_16x16x32_bf16 v[118:121], v[130:133], v[180:183], v[118:121]
	v_mfma_f32_16x16x32_bf16 v[114:117], v[138:141], v[180:183], v[114:117]
	v_mfma_f32_16x16x32_bf16 v[110:113], v[130:133], v[188:191], v[110:113]
	v_mfma_f32_16x16x32_bf16 v[106:109], v[138:141], v[188:191], v[106:109]
	v_mfma_f32_16x16x32_bf16 v[102:105], v[130:133], v[196:199], v[102:105]
	v_mfma_f32_16x16x32_bf16 v[98:101], v[138:141], v[196:199], v[98:101]
	v_mfma_f32_16x16x32_bf16 v[126:129], v[134:137], v[176:179], v[126:129]
	v_mfma_f32_16x16x32_bf16 v[122:125], v[142:145], v[176:179], v[122:125]
	v_mfma_f32_16x16x32_bf16 v[118:121], v[134:137], v[184:187], v[118:121]
	v_mfma_f32_16x16x32_bf16 v[114:117], v[142:145], v[184:187], v[114:117]
	v_mfma_f32_16x16x32_bf16 v[110:113], v[134:137], v[192:195], v[110:113]
	v_mfma_f32_16x16x32_bf16 v[106:109], v[142:145], v[192:195], v[106:109]
	v_mfma_f32_16x16x32_bf16 v[102:105], v[134:137], v[200:203], v[102:105]
	v_mfma_f32_16x16x32_bf16 v[98:101], v[142:145], v[200:203], v[98:101]
	v_mfma_f32_16x16x32_bf16 v[94:97], v[204:207], v[146:149], v[94:97]
	v_mfma_f32_16x16x32_bf16 v[90:93], v[212:215], v[146:149], v[90:93]
	v_mfma_f32_16x16x32_bf16 v[86:89], v[204:207], v[180:183], v[86:89]
	v_mfma_f32_16x16x32_bf16 v[82:85], v[212:215], v[180:183], v[82:85]
	v_mfma_f32_16x16x32_bf16 v[78:81], v[204:207], v[188:191], v[78:81]
	v_mfma_f32_16x16x32_bf16 v[74:77], v[212:215], v[188:191], v[74:77]
	v_mfma_f32_16x16x32_bf16 v[70:73], v[204:207], v[196:199], v[70:73]
	v_mfma_f32_16x16x32_bf16 v[66:69], v[212:215], v[196:199], v[66:69]
	v_mfma_f32_16x16x32_bf16 v[94:97], v[208:211], v[176:179], v[94:97]
	v_mfma_f32_16x16x32_bf16 v[90:93], v[216:219], v[176:179], v[90:93]
	v_mfma_f32_16x16x32_bf16 v[86:89], v[208:211], v[184:187], v[86:89]
	v_mfma_f32_16x16x32_bf16 v[82:85], v[216:219], v[184:187], v[82:85]
	v_mfma_f32_16x16x32_bf16 v[78:81], v[208:211], v[192:195], v[78:81]
	v_mfma_f32_16x16x32_bf16 v[74:77], v[216:219], v[192:195], v[74:77]
	v_mfma_f32_16x16x32_bf16 v[70:73], v[208:211], v[200:203], v[70:73]
	v_mfma_f32_16x16x32_bf16 v[66:69], v[216:219], v[200:203], v[66:69]
	s_barrier
	s_setprio 0
	s_add_i32 s20, s57, s48
	v_lshl_add_u64 v[220:221], s[42:43], 0, v[152:153]
	s_mov_b32 m0, s20
	s_nop 0
	global_load_lds_dwordx4 v[220:221], off
	v_lshl_add_u64 v[222:223], s[42:43], 0, v[156:157]
	s_add_i32 m0, s20, 0x2000
	s_nop 0
	global_load_lds_dwordx4 v[222:223], off
	s_mov_b32 m0, s50
	v_lshl_add_u64 v[224:225], s[18:19], 0, v[150:151]
	ds_read_b128 v[146:149], v171 offset:16384
	ds_read_b128 v[176:179], v171 offset:17408
	ds_read_b128 v[180:183], v171 offset:18432
	ds_read_b128 v[184:187], v171 offset:19456
	ds_read_b128 v[188:191], v171 offset:20480
	ds_read_b128 v[192:195], v171 offset:21504
	ds_read_b128 v[196:199], v171 offset:22528
	ds_read_b128 v[200:203], v171 offset:23552
	global_load_lds_dwordx4 v[224:225], off
	v_lshl_add_u64 v[226:227], s[18:19], 0, v[154:155]
	s_mov_b32 m0, s51
	s_nop 0
	global_load_lds_dwordx4 v[226:227], off
	s_waitcnt vmcnt(6)
	s_waitcnt lgkmcnt(0)
	s_setprio 1
	s_barrier
	v_mfma_f32_16x16x32_bf16 v[62:65], v[130:133], v[146:149], v[62:65]
	v_mfma_f32_16x16x32_bf16 v[58:61], v[138:141], v[146:149], v[58:61]
	v_mfma_f32_16x16x32_bf16 v[54:57], v[130:133], v[180:183], v[54:57]
	v_mfma_f32_16x16x32_bf16 v[50:53], v[138:141], v[180:183], v[50:53]
	v_mfma_f32_16x16x32_bf16 v[46:49], v[130:133], v[188:191], v[46:49]
	v_mfma_f32_16x16x32_bf16 v[42:45], v[138:141], v[188:191], v[42:45]
	v_mfma_f32_16x16x32_bf16 v[38:41], v[130:133], v[196:199], v[38:41]
	v_mfma_f32_16x16x32_bf16 v[34:37], v[138:141], v[196:199], v[34:37]
	v_mfma_f32_16x16x32_bf16 v[62:65], v[134:137], v[176:179], v[62:65]
	v_mfma_f32_16x16x32_bf16 v[58:61], v[142:145], v[176:179], v[58:61]
	v_mfma_f32_16x16x32_bf16 v[54:57], v[134:137], v[184:187], v[54:57]
	v_mfma_f32_16x16x32_bf16 v[50:53], v[142:145], v[184:187], v[50:53]
	v_mfma_f32_16x16x32_bf16 v[46:49], v[134:137], v[192:195], v[46:49]
	v_mfma_f32_16x16x32_bf16 v[42:45], v[142:145], v[192:195], v[42:45]
	v_mfma_f32_16x16x32_bf16 v[38:41], v[134:137], v[200:203], v[38:41]
	v_mfma_f32_16x16x32_bf16 v[34:37], v[142:145], v[200:203], v[34:37]
	v_mfma_f32_16x16x32_bf16 v[30:33], v[204:207], v[146:149], v[30:33]
	v_mfma_f32_16x16x32_bf16 v[26:29], v[212:215], v[146:149], v[26:29]
	v_mfma_f32_16x16x32_bf16 v[22:25], v[204:207], v[180:183], v[22:25]
	v_mfma_f32_16x16x32_bf16 v[18:21], v[212:215], v[180:183], v[18:21]
	v_mfma_f32_16x16x32_bf16 v[14:17], v[204:207], v[188:191], v[14:17]
	v_mfma_f32_16x16x32_bf16 v[10:13], v[212:215], v[188:191], v[10:13]
	v_mfma_f32_16x16x32_bf16 v[6:9], v[204:207], v[196:199], v[6:9]
	v_mfma_f32_16x16x32_bf16 v[2:5], v[212:215], v[196:199], v[2:5]
	v_mfma_f32_16x16x32_bf16 v[30:33], v[208:211], v[176:179], v[30:33]
	v_mfma_f32_16x16x32_bf16 v[26:29], v[216:219], v[176:179], v[26:29]
	v_mfma_f32_16x16x32_bf16 v[22:25], v[208:211], v[184:187], v[22:25]
	v_mfma_f32_16x16x32_bf16 v[18:21], v[216:219], v[184:187], v[18:21]
	v_mfma_f32_16x16x32_bf16 v[14:17], v[208:211], v[192:195], v[14:17]
	v_mfma_f32_16x16x32_bf16 v[10:13], v[216:219], v[192:195], v[10:13]
	v_mfma_f32_16x16x32_bf16 v[6:9], v[208:211], v[200:203], v[6:9]
	v_mfma_f32_16x16x32_bf16 v[2:5], v[216:219], v[200:203], v[2:5]
	s_barrier
	s_setprio 0
	s_add_u32 s20, s42, 0x40000
	s_addc_u32 s21, s43, 0
	s_add_i32 s73, s60, s48
	v_lshl_add_u64 v[246:247], s[20:21], 0, v[152:153]
	s_mov_b32 m0, s73
	s_nop 0
	global_load_lds_dwordx4 v[246:247], off
	v_lshl_add_u64 v[246:247], s[20:21], 0, v[156:157]
	s_add_i32 m0, s73, 0x2000
	s_nop 0
	global_load_lds_dwordx4 v[246:247], off
	s_add_i32 s20, 0, 0x18000
	v_add_u32_e32 v142, s20, v161
	ds_read_b128 v[130:133], v142
	ds_read_b128 v[134:137], v142 offset:1024
	ds_read_b128 v[138:141], v142 offset:2048
	ds_read_b128 v[142:145], v142 offset:3072
	s_add_u32 s18, s18, 0x40000
	s_addc_u32 s19, s19, 0
	s_mov_b32 m0, s52
	v_lshl_add_u64 v[204:205], s[18:19], 0, v[150:151]
	ds_read_b128 v[146:149], v171 offset:32768
	ds_read_b128 v[176:179], v171 offset:33792
	ds_read_b128 v[180:183], v171 offset:34816
	ds_read_b128 v[184:187], v171 offset:35840
	ds_read_b128 v[188:191], v171 offset:36864
	ds_read_b128 v[192:195], v171 offset:37888
	ds_read_b128 v[196:199], v171 offset:38912
	ds_read_b128 v[200:203], v171 offset:39936
	global_load_lds_dwordx4 v[204:205], off
	v_lshl_add_u64 v[204:205], s[18:19], 0, v[154:155]
	s_mov_b32 m0, s53
	s_nop 0
	global_load_lds_dwordx4 v[204:205], off
	s_add_i32 s21, 0, 0x1c000
	v_add_u32_e32 v158, s21, v161
	ds_read_b128 v[204:207], v158
	ds_read_b128 v[208:211], v158 offset:1024
	ds_read_b128 v[212:215], v158 offset:2048
	ds_read_b128 v[216:219], v158 offset:3072
	s_waitcnt vmcnt(8)
	s_waitcnt lgkmcnt(0)
	s_setprio 1
	s_barrier
	v_mfma_f32_16x16x32_bf16 v[126:129], v[130:133], v[146:149], v[126:129]
	v_mfma_f32_16x16x32_bf16 v[122:125], v[138:141], v[146:149], v[122:125]
	v_mfma_f32_16x16x32_bf16 v[118:121], v[130:133], v[180:183], v[118:121]
	v_mfma_f32_16x16x32_bf16 v[114:117], v[138:141], v[180:183], v[114:117]
	v_mfma_f32_16x16x32_bf16 v[110:113], v[130:133], v[188:191], v[110:113]
	v_mfma_f32_16x16x32_bf16 v[106:109], v[138:141], v[188:191], v[106:109]
	v_mfma_f32_16x16x32_bf16 v[102:105], v[130:133], v[196:199], v[102:105]
	v_mfma_f32_16x16x32_bf16 v[98:101], v[138:141], v[196:199], v[98:101]
	v_mfma_f32_16x16x32_bf16 v[126:129], v[134:137], v[176:179], v[126:129]
	v_mfma_f32_16x16x32_bf16 v[122:125], v[142:145], v[176:179], v[122:125]
	v_mfma_f32_16x16x32_bf16 v[118:121], v[134:137], v[184:187], v[118:121]
	v_mfma_f32_16x16x32_bf16 v[114:117], v[142:145], v[184:187], v[114:117]
	v_mfma_f32_16x16x32_bf16 v[110:113], v[134:137], v[192:195], v[110:113]
	v_mfma_f32_16x16x32_bf16 v[106:109], v[142:145], v[192:195], v[106:109]
	v_mfma_f32_16x16x32_bf16 v[102:105], v[134:137], v[200:203], v[102:105]
	v_mfma_f32_16x16x32_bf16 v[98:101], v[142:145], v[200:203], v[98:101]
	v_mfma_f32_16x16x32_bf16 v[94:97], v[204:207], v[146:149], v[94:97]
	v_mfma_f32_16x16x32_bf16 v[90:93], v[212:215], v[146:149], v[90:93]
	v_mfma_f32_16x16x32_bf16 v[86:89], v[204:207], v[180:183], v[86:89]
	v_mfma_f32_16x16x32_bf16 v[82:85], v[212:215], v[180:183], v[82:85]
	v_mfma_f32_16x16x32_bf16 v[78:81], v[204:207], v[188:191], v[78:81]
	v_mfma_f32_16x16x32_bf16 v[74:77], v[212:215], v[188:191], v[74:77]
	v_mfma_f32_16x16x32_bf16 v[70:73], v[204:207], v[196:199], v[70:73]
	v_mfma_f32_16x16x32_bf16 v[66:69], v[212:215], v[196:199], v[66:69]
	v_mfma_f32_16x16x32_bf16 v[94:97], v[208:211], v[176:179], v[94:97]
	v_mfma_f32_16x16x32_bf16 v[90:93], v[216:219], v[176:179], v[90:93]
	v_mfma_f32_16x16x32_bf16 v[86:89], v[208:211], v[184:187], v[86:89]
	v_mfma_f32_16x16x32_bf16 v[82:85], v[216:219], v[184:187], v[82:85]
	v_mfma_f32_16x16x32_bf16 v[78:81], v[208:211], v[192:195], v[78:81]
	v_mfma_f32_16x16x32_bf16 v[74:77], v[216:219], v[192:195], v[74:77]
	v_mfma_f32_16x16x32_bf16 v[70:73], v[208:211], v[200:203], v[70:73]
	v_mfma_f32_16x16x32_bf16 v[66:69], v[216:219], v[200:203], v[66:69]
	s_barrier
	s_setprio 0
	s_add_i32 s18, s20, s48
	v_lshl_add_u64 v[220:221], v[220:221], 0, s[6:7]
	s_mov_b32 m0, s18
	s_nop 0
	global_load_lds_dwordx4 v[220:221], off
	v_lshl_add_u64 v[220:221], v[222:223], 0, s[6:7]
	s_add_i32 m0, s18, 0x2000
	s_nop 0
	global_load_lds_dwordx4 v[220:221], off
	s_mov_b32 m0, s55
	v_lshl_add_u64 v[220:221], v[224:225], 0, s[6:7]
	ds_read_b128 v[146:149], v171 offset:49152
	ds_read_b128 v[176:179], v171 offset:50176
	ds_read_b128 v[180:183], v171 offset:51200
	ds_read_b128 v[184:187], v171 offset:52224
	ds_read_b128 v[188:191], v171 offset:53248
	ds_read_b128 v[192:195], v171 offset:54272
	ds_read_b128 v[196:199], v171 offset:55296
	ds_read_b128 v[200:203], v171 offset:56320
	global_load_lds_dwordx4 v[220:221], off
	v_lshl_add_u64 v[220:221], v[226:227], 0, s[6:7]
	s_mov_b32 m0, s56
	s_nop 0
	global_load_lds_dwordx4 v[220:221], off
	s_add_u32 s18, s42, 0x40080
	s_addc_u32 s19, s43, 0
	s_add_i32 s20, s21, s48
	v_lshl_add_u64 v[248:249], s[18:19], 0, v[152:153]
	s_mov_b32 m0, s20
	s_nop 0
	global_load_lds_dwordx4 v[248:249], off
	v_lshl_add_u64 v[248:249], s[18:19], 0, v[156:157]
	s_add_i32 m0, s20, 0x2000
	s_nop 0
	global_load_lds_dwordx4 v[248:249], off
	s_waitcnt vmcnt(6)
	s_waitcnt lgkmcnt(0)
	s_setprio 1
	s_barrier
	v_mfma_f32_16x16x32_bf16 v[62:65], v[130:133], v[146:149], v[62:65]
	v_mfma_f32_16x16x32_bf16 v[58:61], v[138:141], v[146:149], v[58:61]
	v_mfma_f32_16x16x32_bf16 v[54:57], v[130:133], v[180:183], v[54:57]
	v_mfma_f32_16x16x32_bf16 v[50:53], v[138:141], v[180:183], v[50:53]
	v_mfma_f32_16x16x32_bf16 v[46:49], v[130:133], v[188:191], v[46:49]
	v_mfma_f32_16x16x32_bf16 v[42:45], v[138:141], v[188:191], v[42:45]
	v_mfma_f32_16x16x32_bf16 v[38:41], v[130:133], v[196:199], v[38:41]
	v_mfma_f32_16x16x32_bf16 v[34:37], v[138:141], v[196:199], v[34:37]
	v_mfma_f32_16x16x32_bf16 v[62:65], v[134:137], v[176:179], v[62:65]
	v_mfma_f32_16x16x32_bf16 v[58:61], v[142:145], v[176:179], v[58:61]
	v_mfma_f32_16x16x32_bf16 v[54:57], v[134:137], v[184:187], v[54:57]
	v_mfma_f32_16x16x32_bf16 v[50:53], v[142:145], v[184:187], v[50:53]
	v_mfma_f32_16x16x32_bf16 v[46:49], v[134:137], v[192:195], v[46:49]
	v_mfma_f32_16x16x32_bf16 v[42:45], v[142:145], v[192:195], v[42:45]
	v_mfma_f32_16x16x32_bf16 v[38:41], v[134:137], v[200:203], v[38:41]
	v_mfma_f32_16x16x32_bf16 v[34:37], v[142:145], v[200:203], v[34:37]
	v_mfma_f32_16x16x32_bf16 v[30:33], v[204:207], v[146:149], v[30:33]
	v_mfma_f32_16x16x32_bf16 v[26:29], v[212:215], v[146:149], v[26:29]
	v_mfma_f32_16x16x32_bf16 v[22:25], v[204:207], v[180:183], v[22:25]
	v_mfma_f32_16x16x32_bf16 v[18:21], v[212:215], v[180:183], v[18:21]
	v_mfma_f32_16x16x32_bf16 v[14:17], v[204:207], v[188:191], v[14:17]
	v_mfma_f32_16x16x32_bf16 v[10:13], v[212:215], v[188:191], v[10:13]
	v_mfma_f32_16x16x32_bf16 v[6:9], v[204:207], v[196:199], v[6:9]
	v_mfma_f32_16x16x32_bf16 v[2:5], v[212:215], v[196:199], v[2:5]
	v_mfma_f32_16x16x32_bf16 v[30:33], v[208:211], v[176:179], v[30:33]
	v_mfma_f32_16x16x32_bf16 v[26:29], v[216:219], v[176:179], v[26:29]
	v_mfma_f32_16x16x32_bf16 v[22:25], v[208:211], v[184:187], v[22:25]
	v_mfma_f32_16x16x32_bf16 v[18:21], v[216:219], v[184:187], v[18:21]
	v_mfma_f32_16x16x32_bf16 v[14:17], v[208:211], v[192:195], v[14:17]
	v_mfma_f32_16x16x32_bf16 v[10:13], v[216:219], v[192:195], v[10:13]
	v_mfma_f32_16x16x32_bf16 v[6:9], v[208:211], v[200:203], v[6:9]
	v_mfma_f32_16x16x32_bf16 v[2:5], v[216:219], v[200:203], v[2:5]
	s_barrier
	s_setprio 0
	s_add_i32 s72, s72, 2
	s_add_u32 s38, s38, 0x100
	s_addc_u32 s39, s39, 0
	s_add_u32 s70, s70, 0x100
	s_addc_u32 s71, s71, 0
	s_cmp_gt_u32 s72, 5
	s_cbranch_scc0 .LBB0_2625
	s_cmp_lg_u32 s41, 1
	v_lshl_add_u32 v182, s40, 8, v1
	s_cselect_b64 s[38:39], -1, 0
	s_lshl_b32 s40, s67, 8
	v_or_b32_e32 v180, 16, v182
	v_or_b32_e32 v178, 32, v182
	v_or_b32_e32 v176, 48, v182
	s_ashr_i32 s41, s40, 31
	s_mov_b64 s[18:19], -1
	s_and_b64 vcc, exec, s[38:39]
	v_ashrrev_i32_e32 v183, 31, v182
	v_lshlrev_b32_e32 v158, 1, v160
	v_ashrrev_i32_e32 v181, 31, v180
	v_ashrrev_i32_e32 v179, 31, v178
	v_ashrrev_i32_e32 v177, 31, v176
	s_cbranch_vccnz .LBB0_2629
	s_andn2_b64 vcc, exec, s[18:19]
	s_cbranch_vccz .LBB0_2630

.LBB0_2844:
	s_ashr_i32 s37, s36, 31
	v_cmp_lt_i64_e32 vcc, s[18:19], v[192:193]
	s_lshl_b64 s[18:19], s[36:37], 19
	s_add_u32 s38, s48, s18
	s_addc_u32 s39, s49, s19
	s_and_b64 s[18:19], vcc, exec
	s_cselect_b32 s37, s39, s45
	s_cselect_b32 s43, s38, s44
	s_ashr_i32 s35, s34, 31
	s_lshl_b64 s[18:19], s[34:35], 19
	s_add_u32 s40, s50, s18
	s_addc_u32 s41, s51, s19
	s_and_b64 s[18:19], vcc, exec
	s_cselect_b32 s35, s41, s47
	s_cselect_b32 s70, s40, s46
	s_add_u32 s44, s44, 0x40080
	s_addc_u32 s45, s45, 0
	s_add_u32 s71, s46, 0x100
	s_addc_u32 s72, s47, 0
	s_mov_b32 s73, -2
	s_waitcnt lgkmcnt(0)
	s_waitcnt vmcnt(0)
	ds_read_b128 v[98:101], v173
	ds_read_b128 v[102:105], v173 offset:1024
	ds_read_b128 v[106:109], v173 offset:2048
	ds_read_b128 v[110:113], v173 offset:3072
	s_add_u32 s18, s44, 0xfffc0080
	s_addc_u32 s19, s45, -1
	s_cmp_eq_u32 s73, 12
	s_cselect_b32 s19, s37, s19
	s_cselect_b32 s18, s43, s18
	s_cselect_b32 s47, s35, s72
	s_cselect_b32 s46, s70, s71
	v_lshl_add_u64 v[204:205], s[44:45], 0, v[188:189]
	s_add_i32 m0, s53, 0xc000
	ds_read_b128 v[146:149], v185
	ds_read_b128 v[150:153], v185 offset:1024
	ds_read_b128 v[154:157], v185 offset:2048
	ds_read_b128 v[158:161], v185 offset:3072
	ds_read_b128 v[162:165], v185 offset:4096
	ds_read_b128 v[166:169], v185 offset:5120
	ds_read_b128 v[196:199], v185 offset:6144
	ds_read_b128 v[200:203], v185 offset:7168
	global_load_lds_dwordx4 v[204:205], off
	v_lshl_add_u64 v[204:205], s[44:45], 0, v[190:191]
	s_add_i32 m0, s53, 0xe000
	s_nop 0
	global_load_lds_dwordx4 v[204:205], off
	ds_read_b128 v[204:207], v222
	ds_read_b128 v[208:211], v222 offset:1024
	ds_read_b128 v[212:215], v222 offset:2048
	ds_read_b128 v[216:219], v222 offset:3072
	s_waitcnt lgkmcnt(0)
	s_setprio 1
	s_barrier
	v_mfma_f32_16x16x32_bf16 v[142:145], v[98:101], v[146:149], 0
	v_mfma_f32_16x16x32_bf16 v[138:141], v[106:109], v[146:149], 0
	v_mfma_f32_16x16x32_bf16 v[126:129], v[98:101], v[154:157], 0
	v_mfma_f32_16x16x32_bf16 v[122:125], v[106:109], v[154:157], 0
	v_mfma_f32_16x16x32_bf16 v[94:97], v[98:101], v[162:165], 0
	v_mfma_f32_16x16x32_bf16 v[90:93], v[106:109], v[162:165], 0
	v_mfma_f32_16x16x32_bf16 v[78:81], v[98:101], v[196:199], 0
	v_mfma_f32_16x16x32_bf16 v[74:77], v[106:109], v[196:199], 0
	v_mfma_f32_16x16x32_bf16 v[142:145], v[102:105], v[150:153], v[142:145]
	v_mfma_f32_16x16x32_bf16 v[138:141], v[110:113], v[150:153], v[138:141]
	v_mfma_f32_16x16x32_bf16 v[126:129], v[102:105], v[158:161], v[126:129]
	v_mfma_f32_16x16x32_bf16 v[122:125], v[110:113], v[158:161], v[122:125]
	v_mfma_f32_16x16x32_bf16 v[94:97], v[102:105], v[166:169], v[94:97]
	v_mfma_f32_16x16x32_bf16 v[90:93], v[110:113], v[166:169], v[90:93]
	v_mfma_f32_16x16x32_bf16 v[78:81], v[102:105], v[200:203], v[78:81]
	v_mfma_f32_16x16x32_bf16 v[74:77], v[110:113], v[200:203], v[74:77]
	v_mfma_f32_16x16x32_bf16 v[134:137], v[204:207], v[146:149], 0
	v_mfma_f32_16x16x32_bf16 v[130:133], v[212:215], v[146:149], 0
	v_mfma_f32_16x16x32_bf16 v[118:121], v[204:207], v[154:157], 0
	v_mfma_f32_16x16x32_bf16 v[114:117], v[212:215], v[154:157], 0
	v_mfma_f32_16x16x32_bf16 v[86:89], v[204:207], v[162:165], 0
	v_mfma_f32_16x16x32_bf16 v[82:85], v[212:215], v[162:165], 0
	v_mfma_f32_16x16x32_bf16 v[70:73], v[204:207], v[196:199], 0
	v_mfma_f32_16x16x32_bf16 v[66:69], v[212:215], v[196:199], 0
	v_mfma_f32_16x16x32_bf16 v[134:137], v[208:211], v[150:153], v[134:137]
	v_mfma_f32_16x16x32_bf16 v[130:133], v[216:219], v[150:153], v[130:133]
	v_mfma_f32_16x16x32_bf16 v[118:121], v[208:211], v[158:161], v[118:121]
	v_mfma_f32_16x16x32_bf16 v[114:117], v[216:219], v[158:161], v[114:117]
	v_mfma_f32_16x16x32_bf16 v[86:89], v[208:211], v[166:169], v[86:89]
	v_mfma_f32_16x16x32_bf16 v[82:85], v[216:219], v[166:169], v[82:85]
	v_mfma_f32_16x16x32_bf16 v[70:73], v[208:211], v[200:203], v[70:73]
	v_mfma_f32_16x16x32_bf16 v[66:69], v[216:219], v[200:203], v[66:69]
	s_barrier
	s_setprio 0
	s_add_i32 s20, s65, s52
	v_lshl_add_u64 v[220:221], s[46:47], 0, v[176:177]
	s_mov_b32 m0, s20
	s_nop 0
	global_load_lds_dwordx4 v[220:221], off
	v_lshl_add_u64 v[224:225], s[46:47], 0, v[180:181]
	s_add_i32 m0, s20, 0x2000
	s_nop 0
	global_load_lds_dwordx4 v[224:225], off
	s_mov_b32 m0, s53
	v_lshl_add_u64 v[226:227], s[18:19], 0, v[174:175]
	ds_read_b128 v[146:149], v185 offset:16384
	ds_read_b128 v[150:153], v185 offset:17408
	ds_read_b128 v[154:157], v185 offset:18432
	ds_read_b128 v[158:161], v185 offset:19456
	ds_read_b128 v[162:165], v185 offset:20480
	ds_read_b128 v[166:169], v185 offset:21504
	ds_read_b128 v[196:199], v185 offset:22528
	ds_read_b128 v[200:203], v185 offset:23552
	global_load_lds_dwordx4 v[226:227], off
	v_lshl_add_u64 v[228:229], s[18:19], 0, v[178:179]
	s_mov_b32 m0, s54
	s_nop 0
	global_load_lds_dwordx4 v[228:229], off
	s_waitcnt vmcnt(6)
	s_waitcnt lgkmcnt(0)
	s_setprio 1
	s_barrier
	v_mfma_f32_16x16x32_bf16 v[62:65], v[98:101], v[146:149], 0
	v_mfma_f32_16x16x32_bf16 v[58:61], v[106:109], v[146:149], 0
	v_mfma_f32_16x16x32_bf16 v[46:49], v[98:101], v[154:157], 0
	v_mfma_f32_16x16x32_bf16 v[42:45], v[106:109], v[154:157], 0
	v_mfma_f32_16x16x32_bf16 v[30:33], v[98:101], v[162:165], 0
	v_mfma_f32_16x16x32_bf16 v[26:29], v[106:109], v[162:165], 0
	v_mfma_f32_16x16x32_bf16 v[14:17], v[98:101], v[196:199], 0
	v_mfma_f32_16x16x32_bf16 v[10:13], v[106:109], v[196:199], 0
	v_mfma_f32_16x16x32_bf16 v[62:65], v[102:105], v[150:153], v[62:65]
	v_mfma_f32_16x16x32_bf16 v[58:61], v[110:113], v[150:153], v[58:61]
	v_mfma_f32_16x16x32_bf16 v[46:49], v[102:105], v[158:161], v[46:49]
	v_mfma_f32_16x16x32_bf16 v[42:45], v[110:113], v[158:161], v[42:45]
	v_mfma_f32_16x16x32_bf16 v[30:33], v[102:105], v[166:169], v[30:33]
	v_mfma_f32_16x16x32_bf16 v[26:29], v[110:113], v[166:169], v[26:29]
	v_mfma_f32_16x16x32_bf16 v[14:17], v[102:105], v[200:203], v[14:17]
	v_mfma_f32_16x16x32_bf16 v[10:13], v[110:113], v[200:203], v[10:13]
	v_mfma_f32_16x16x32_bf16 v[54:57], v[204:207], v[146:149], 0
	v_mfma_f32_16x16x32_bf16 v[50:53], v[212:215], v[146:149], 0
	v_mfma_f32_16x16x32_bf16 v[38:41], v[204:207], v[154:157], 0
	v_mfma_f32_16x16x32_bf16 v[34:37], v[212:215], v[154:157], 0
	v_mfma_f32_16x16x32_bf16 v[22:25], v[204:207], v[162:165], 0
	v_mfma_f32_16x16x32_bf16 v[18:21], v[212:215], v[162:165], 0
	v_mfma_f32_16x16x32_bf16 v[6:9], v[204:207], v[196:199], 0
	v_mfma_f32_16x16x32_bf16 v[2:5], v[212:215], v[196:199], 0
	v_mfma_f32_16x16x32_bf16 v[54:57], v[208:211], v[150:153], v[54:57]
	v_mfma_f32_16x16x32_bf16 v[50:53], v[216:219], v[150:153], v[50:53]
	v_mfma_f32_16x16x32_bf16 v[38:41], v[208:211], v[158:161], v[38:41]
	v_mfma_f32_16x16x32_bf16 v[34:37], v[216:219], v[158:161], v[34:37]
	v_mfma_f32_16x16x32_bf16 v[22:25], v[208:211], v[166:169], v[22:25]
	v_mfma_f32_16x16x32_bf16 v[18:21], v[216:219], v[166:169], v[18:21]
	v_mfma_f32_16x16x32_bf16 v[6:9], v[208:211], v[200:203], v[6:9]
	v_mfma_f32_16x16x32_bf16 v[2:5], v[216:219], v[200:203], v[2:5]
	s_barrier
	s_setprio 0
	s_add_u32 s20, s46, 0x40000
	s_addc_u32 s21, s47, 0
	s_add_i32 s74, s66, s52
	v_lshl_add_u64 v[246:247], s[20:21], 0, v[176:177]
	s_mov_b32 m0, s74
	s_nop 0
	global_load_lds_dwordx4 v[246:247], off
	v_lshl_add_u64 v[246:247], s[20:21], 0, v[180:181]
	s_add_i32 m0, s74, 0x2000
	s_nop 0
	global_load_lds_dwordx4 v[246:247], off
	s_add_i32 s20, 0, 0x18000
	v_add_u32_e32 v110, s20, v171
	ds_read_b128 v[98:101], v110
	ds_read_b128 v[102:105], v110 offset:1024
	ds_read_b128 v[106:109], v110 offset:2048
	ds_read_b128 v[110:113], v110 offset:3072
	s_add_u32 s18, s18, 0x40000
	s_addc_u32 s19, s19, 0
	s_mov_b32 m0, s55
	v_lshl_add_u64 v[204:205], s[18:19], 0, v[174:175]
	ds_read_b128 v[146:149], v185 offset:32768
	ds_read_b128 v[150:153], v185 offset:33792
	ds_read_b128 v[154:157], v185 offset:34816
	ds_read_b128 v[158:161], v185 offset:35840
	ds_read_b128 v[162:165], v185 offset:36864
	ds_read_b128 v[166:169], v185 offset:37888
	ds_read_b128 v[196:199], v185 offset:38912
	ds_read_b128 v[200:203], v185 offset:39936
	global_load_lds_dwordx4 v[204:205], off
	v_lshl_add_u64 v[204:205], s[18:19], 0, v[178:179]
	s_mov_b32 m0, s56
	s_nop 0
	global_load_lds_dwordx4 v[204:205], off
	s_add_i32 s21, 0, 0x1c000
	v_add_u32_e32 v182, s21, v171
	ds_read_b128 v[204:207], v182
	ds_read_b128 v[208:211], v182 offset:1024
	ds_read_b128 v[212:215], v182 offset:2048
	ds_read_b128 v[216:219], v182 offset:3072
	s_waitcnt vmcnt(8)
	s_waitcnt lgkmcnt(0)
	s_setprio 1
	s_barrier
	v_mfma_f32_16x16x32_bf16 v[142:145], v[98:101], v[146:149], v[142:145]
	v_mfma_f32_16x16x32_bf16 v[138:141], v[106:109], v[146:149], v[138:141]
	v_mfma_f32_16x16x32_bf16 v[126:129], v[98:101], v[154:157], v[126:129]
	v_mfma_f32_16x16x32_bf16 v[122:125], v[106:109], v[154:157], v[122:125]
	v_mfma_f32_16x16x32_bf16 v[94:97], v[98:101], v[162:165], v[94:97]
	v_mfma_f32_16x16x32_bf16 v[90:93], v[106:109], v[162:165], v[90:93]
	v_mfma_f32_16x16x32_bf16 v[78:81], v[98:101], v[196:199], v[78:81]
	v_mfma_f32_16x16x32_bf16 v[74:77], v[106:109], v[196:199], v[74:77]
	v_mfma_f32_16x16x32_bf16 v[142:145], v[102:105], v[150:153], v[142:145]
	v_mfma_f32_16x16x32_bf16 v[138:141], v[110:113], v[150:153], v[138:141]
	v_mfma_f32_16x16x32_bf16 v[126:129], v[102:105], v[158:161], v[126:129]
	v_mfma_f32_16x16x32_bf16 v[122:125], v[110:113], v[158:161], v[122:125]
	v_mfma_f32_16x16x32_bf16 v[94:97], v[102:105], v[166:169], v[94:97]
	v_mfma_f32_16x16x32_bf16 v[90:93], v[110:113], v[166:169], v[90:93]
	v_mfma_f32_16x16x32_bf16 v[78:81], v[102:105], v[200:203], v[78:81]
	v_mfma_f32_16x16x32_bf16 v[74:77], v[110:113], v[200:203], v[74:77]
	v_mfma_f32_16x16x32_bf16 v[134:137], v[204:207], v[146:149], v[134:137]
	v_mfma_f32_16x16x32_bf16 v[130:133], v[212:215], v[146:149], v[130:133]
	v_mfma_f32_16x16x32_bf16 v[118:121], v[204:207], v[154:157], v[118:121]
	v_mfma_f32_16x16x32_bf16 v[114:117], v[212:215], v[154:157], v[114:117]
	v_mfma_f32_16x16x32_bf16 v[86:89], v[204:207], v[162:165], v[86:89]
	v_mfma_f32_16x16x32_bf16 v[82:85], v[212:215], v[162:165], v[82:85]
	v_mfma_f32_16x16x32_bf16 v[70:73], v[204:207], v[196:199], v[70:73]
	v_mfma_f32_16x16x32_bf16 v[66:69], v[212:215], v[196:199], v[66:69]
	v_mfma_f32_16x16x32_bf16 v[134:137], v[208:211], v[150:153], v[134:137]
	v_mfma_f32_16x16x32_bf16 v[130:133], v[216:219], v[150:153], v[130:133]
	v_mfma_f32_16x16x32_bf16 v[118:121], v[208:211], v[158:161], v[118:121]
	v_mfma_f32_16x16x32_bf16 v[114:117], v[216:219], v[158:161], v[114:117]
	v_mfma_f32_16x16x32_bf16 v[86:89], v[208:211], v[166:169], v[86:89]
	v_mfma_f32_16x16x32_bf16 v[82:85], v[216:219], v[166:169], v[82:85]
	v_mfma_f32_16x16x32_bf16 v[70:73], v[208:211], v[200:203], v[70:73]
	v_mfma_f32_16x16x32_bf16 v[66:69], v[216:219], v[200:203], v[66:69]
	s_barrier
	s_setprio 0
	s_add_i32 s18, s20, s52
	v_lshl_add_u64 v[220:221], v[220:221], 0, s[10:11]
	s_mov_b32 m0, s18
	s_nop 0
	global_load_lds_dwordx4 v[220:221], off
	v_lshl_add_u64 v[220:221], v[224:225], 0, s[10:11]
	s_add_i32 m0, s18, 0x2000
	s_nop 0
	global_load_lds_dwordx4 v[220:221], off
	s_mov_b32 m0, s62
	v_lshl_add_u64 v[220:221], v[226:227], 0, s[10:11]
	ds_read_b128 v[146:149], v185 offset:49152
	ds_read_b128 v[150:153], v185 offset:50176
	ds_read_b128 v[154:157], v185 offset:51200
	ds_read_b128 v[158:161], v185 offset:52224
	ds_read_b128 v[162:165], v185 offset:53248
	ds_read_b128 v[166:169], v185 offset:54272
	ds_read_b128 v[196:199], v185 offset:55296
	ds_read_b128 v[200:203], v185 offset:56320
	global_load_lds_dwordx4 v[220:221], off
	v_lshl_add_u64 v[220:221], v[228:229], 0, s[10:11]
	s_mov_b32 m0, s63
	s_nop 0
	global_load_lds_dwordx4 v[220:221], off
	s_add_u32 s18, s46, 0x40080
	s_addc_u32 s19, s47, 0
	s_add_i32 s20, s21, s52
	v_lshl_add_u64 v[248:249], s[18:19], 0, v[176:177]
	s_mov_b32 m0, s20
	s_nop 0
	global_load_lds_dwordx4 v[248:249], off
	v_lshl_add_u64 v[248:249], s[18:19], 0, v[180:181]
	s_add_i32 m0, s20, 0x2000
	s_nop 0
	global_load_lds_dwordx4 v[248:249], off
	s_waitcnt vmcnt(6)
	s_waitcnt lgkmcnt(0)
	s_setprio 1
	s_barrier
	v_mfma_f32_16x16x32_bf16 v[62:65], v[98:101], v[146:149], v[62:65]
	v_mfma_f32_16x16x32_bf16 v[58:61], v[106:109], v[146:149], v[58:61]
	v_mfma_f32_16x16x32_bf16 v[46:49], v[98:101], v[154:157], v[46:49]
	v_mfma_f32_16x16x32_bf16 v[42:45], v[106:109], v[154:157], v[42:45]
	v_mfma_f32_16x16x32_bf16 v[30:33], v[98:101], v[162:165], v[30:33]
	v_mfma_f32_16x16x32_bf16 v[26:29], v[106:109], v[162:165], v[26:29]
	v_mfma_f32_16x16x32_bf16 v[14:17], v[98:101], v[196:199], v[14:17]
	v_mfma_f32_16x16x32_bf16 v[10:13], v[106:109], v[196:199], v[10:13]
	v_mfma_f32_16x16x32_bf16 v[62:65], v[102:105], v[150:153], v[62:65]
	v_mfma_f32_16x16x32_bf16 v[58:61], v[110:113], v[150:153], v[58:61]
	v_mfma_f32_16x16x32_bf16 v[46:49], v[102:105], v[158:161], v[46:49]
	v_mfma_f32_16x16x32_bf16 v[42:45], v[110:113], v[158:161], v[42:45]
	v_mfma_f32_16x16x32_bf16 v[30:33], v[102:105], v[166:169], v[30:33]
	v_mfma_f32_16x16x32_bf16 v[26:29], v[110:113], v[166:169], v[26:29]
	v_mfma_f32_16x16x32_bf16 v[14:17], v[102:105], v[200:203], v[14:17]
	v_mfma_f32_16x16x32_bf16 v[10:13], v[110:113], v[200:203], v[10:13]
	v_mfma_f32_16x16x32_bf16 v[54:57], v[204:207], v[146:149], v[54:57]
	v_mfma_f32_16x16x32_bf16 v[50:53], v[212:215], v[146:149], v[50:53]
	v_mfma_f32_16x16x32_bf16 v[38:41], v[204:207], v[154:157], v[38:41]
	v_mfma_f32_16x16x32_bf16 v[34:37], v[212:215], v[154:157], v[34:37]
	v_mfma_f32_16x16x32_bf16 v[22:25], v[204:207], v[162:165], v[22:25]
	v_mfma_f32_16x16x32_bf16 v[18:21], v[212:215], v[162:165], v[18:21]
	v_mfma_f32_16x16x32_bf16 v[6:9], v[204:207], v[196:199], v[6:9]
	v_mfma_f32_16x16x32_bf16 v[2:5], v[212:215], v[196:199], v[2:5]
	v_mfma_f32_16x16x32_bf16 v[54:57], v[208:211], v[150:153], v[54:57]
	v_mfma_f32_16x16x32_bf16 v[50:53], v[216:219], v[150:153], v[50:53]
	v_mfma_f32_16x16x32_bf16 v[38:41], v[208:211], v[158:161], v[38:41]
	v_mfma_f32_16x16x32_bf16 v[34:37], v[216:219], v[158:161], v[34:37]
	v_mfma_f32_16x16x32_bf16 v[22:25], v[208:211], v[166:169], v[22:25]
	v_mfma_f32_16x16x32_bf16 v[18:21], v[216:219], v[166:169], v[18:21]
	v_mfma_f32_16x16x32_bf16 v[6:9], v[208:211], v[200:203], v[6:9]
	v_mfma_f32_16x16x32_bf16 v[2:5], v[216:219], v[200:203], v[2:5]
	s_barrier
	s_setprio 0
	s_add_i32 s73, s73, 2
	s_add_u32 s44, s44, 0x100
	s_addc_u32 s45, s45, 0
	s_add_u32 s71, s71, 0x100
	s_addc_u32 s72, s72, 0
	s_cmp_gt_u32 s73, 13
.LBB0_2845:
	ds_read_b128 v[98:101], v173
	ds_read_b128 v[102:105], v173 offset:1024
	ds_read_b128 v[106:109], v173 offset:2048
	ds_read_b128 v[110:113], v173 offset:3072
	s_add_u32 s18, s44, 0xfffc0080
	s_addc_u32 s19, s45, -1
	s_cmp_eq_u32 s73, 12
	s_cselect_b32 s19, s37, s19
	s_cselect_b32 s18, s43, s18
	s_cselect_b32 s47, s35, s72
	s_cselect_b32 s46, s70, s71
	v_lshl_add_u64 v[204:205], s[44:45], 0, v[188:189]
	s_add_i32 m0, s53, 0xc000
	ds_read_b128 v[146:149], v185
	ds_read_b128 v[150:153], v185 offset:1024
	ds_read_b128 v[154:157], v185 offset:2048
	ds_read_b128 v[158:161], v185 offset:3072
	ds_read_b128 v[162:165], v185 offset:4096
	ds_read_b128 v[166:169], v185 offset:5120
	ds_read_b128 v[196:199], v185 offset:6144
	ds_read_b128 v[200:203], v185 offset:7168
	global_load_lds_dwordx4 v[204:205], off
	v_lshl_add_u64 v[204:205], s[44:45], 0, v[190:191]
	s_add_i32 m0, s53, 0xe000
	s_nop 0
	global_load_lds_dwordx4 v[204:205], off
	ds_read_b128 v[204:207], v222
	ds_read_b128 v[208:211], v222 offset:1024
	ds_read_b128 v[212:215], v222 offset:2048
	ds_read_b128 v[216:219], v222 offset:3072
	s_waitcnt lgkmcnt(0)
	s_setprio 1
	s_barrier
	v_mfma_f32_16x16x32_bf16 v[142:145], v[98:101], v[146:149], v[142:145]
	v_mfma_f32_16x16x32_bf16 v[138:141], v[106:109], v[146:149], v[138:141]
	v_mfma_f32_16x16x32_bf16 v[126:129], v[98:101], v[154:157], v[126:129]
	v_mfma_f32_16x16x32_bf16 v[122:125], v[106:109], v[154:157], v[122:125]
	v_mfma_f32_16x16x32_bf16 v[94:97], v[98:101], v[162:165], v[94:97]
	v_mfma_f32_16x16x32_bf16 v[90:93], v[106:109], v[162:165], v[90:93]
	v_mfma_f32_16x16x32_bf16 v[78:81], v[98:101], v[196:199], v[78:81]
	v_mfma_f32_16x16x32_bf16 v[74:77], v[106:109], v[196:199], v[74:77]
	v_mfma_f32_16x16x32_bf16 v[142:145], v[102:105], v[150:153], v[142:145]
	v_mfma_f32_16x16x32_bf16 v[138:141], v[110:113], v[150:153], v[138:141]
	v_mfma_f32_16x16x32_bf16 v[126:129], v[102:105], v[158:161], v[126:129]
	v_mfma_f32_16x16x32_bf16 v[122:125], v[110:113], v[158:161], v[122:125]
	v_mfma_f32_16x16x32_bf16 v[94:97], v[102:105], v[166:169], v[94:97]
	v_mfma_f32_16x16x32_bf16 v[90:93], v[110:113], v[166:169], v[90:93]
	v_mfma_f32_16x16x32_bf16 v[78:81], v[102:105], v[200:203], v[78:81]
	v_mfma_f32_16x16x32_bf16 v[74:77], v[110:113], v[200:203], v[74:77]
	v_mfma_f32_16x16x32_bf16 v[134:137], v[204:207], v[146:149], v[134:137]
	v_mfma_f32_16x16x32_bf16 v[130:133], v[212:215], v[146:149], v[130:133]
	v_mfma_f32_16x16x32_bf16 v[118:121], v[204:207], v[154:157], v[118:121]
	v_mfma_f32_16x16x32_bf16 v[114:117], v[212:215], v[154:157], v[114:117]
	v_mfma_f32_16x16x32_bf16 v[86:89], v[204:207], v[162:165], v[86:89]
	v_mfma_f32_16x16x32_bf16 v[82:85], v[212:215], v[162:165], v[82:85]
	v_mfma_f32_16x16x32_bf16 v[70:73], v[204:207], v[196:199], v[70:73]
	v_mfma_f32_16x16x32_bf16 v[66:69], v[212:215], v[196:199], v[66:69]
	v_mfma_f32_16x16x32_bf16 v[134:137], v[208:211], v[150:153], v[134:137]
	v_mfma_f32_16x16x32_bf16 v[130:133], v[216:219], v[150:153], v[130:133]
	v_mfma_f32_16x16x32_bf16 v[118:121], v[208:211], v[158:161], v[118:121]
	v_mfma_f32_16x16x32_bf16 v[114:117], v[216:219], v[158:161], v[114:117]
	v_mfma_f32_16x16x32_bf16 v[86:89], v[208:211], v[166:169], v[86:89]
	v_mfma_f32_16x16x32_bf16 v[82:85], v[216:219], v[166:169], v[82:85]
	v_mfma_f32_16x16x32_bf16 v[70:73], v[208:211], v[200:203], v[70:73]
	v_mfma_f32_16x16x32_bf16 v[66:69], v[216:219], v[200:203], v[66:69]
	s_barrier
	s_setprio 0
	s_add_i32 s20, s65, s52
	v_lshl_add_u64 v[220:221], s[46:47], 0, v[176:177]
	s_mov_b32 m0, s20
	s_nop 0
	global_load_lds_dwordx4 v[220:221], off
	v_lshl_add_u64 v[224:225], s[46:47], 0, v[180:181]
	s_add_i32 m0, s20, 0x2000
	s_nop 0
	global_load_lds_dwordx4 v[224:225], off
	s_mov_b32 m0, s53
	v_lshl_add_u64 v[226:227], s[18:19], 0, v[174:175]
	ds_read_b128 v[146:149], v185 offset:16384
	ds_read_b128 v[150:153], v185 offset:17408
	ds_read_b128 v[154:157], v185 offset:18432
	ds_read_b128 v[158:161], v185 offset:19456
	ds_read_b128 v[162:165], v185 offset:20480
	ds_read_b128 v[166:169], v185 offset:21504
	ds_read_b128 v[196:199], v185 offset:22528
	ds_read_b128 v[200:203], v185 offset:23552
	global_load_lds_dwordx4 v[226:227], off
	v_lshl_add_u64 v[228:229], s[18:19], 0, v[178:179]
	s_mov_b32 m0, s54
	s_nop 0
	global_load_lds_dwordx4 v[228:229], off
	s_waitcnt vmcnt(6)
	s_waitcnt lgkmcnt(0)
	s_setprio 1
	s_barrier
	v_mfma_f32_16x16x32_bf16 v[62:65], v[98:101], v[146:149], v[62:65]
	v_mfma_f32_16x16x32_bf16 v[58:61], v[106:109], v[146:149], v[58:61]
	v_mfma_f32_16x16x32_bf16 v[46:49], v[98:101], v[154:157], v[46:49]
	v_mfma_f32_16x16x32_bf16 v[42:45], v[106:109], v[154:157], v[42:45]
	v_mfma_f32_16x16x32_bf16 v[30:33], v[98:101], v[162:165], v[30:33]
	v_mfma_f32_16x16x32_bf16 v[26:29], v[106:109], v[162:165], v[26:29]
	v_mfma_f32_16x16x32_bf16 v[14:17], v[98:101], v[196:199], v[14:17]
	v_mfma_f32_16x16x32_bf16 v[10:13], v[106:109], v[196:199], v[10:13]
	v_mfma_f32_16x16x32_bf16 v[62:65], v[102:105], v[150:153], v[62:65]
	v_mfma_f32_16x16x32_bf16 v[58:61], v[110:113], v[150:153], v[58:61]
	v_mfma_f32_16x16x32_bf16 v[46:49], v[102:105], v[158:161], v[46:49]
	v_mfma_f32_16x16x32_bf16 v[42:45], v[110:113], v[158:161], v[42:45]
	v_mfma_f32_16x16x32_bf16 v[30:33], v[102:105], v[166:169], v[30:33]
	v_mfma_f32_16x16x32_bf16 v[26:29], v[110:113], v[166:169], v[26:29]
	v_mfma_f32_16x16x32_bf16 v[14:17], v[102:105], v[200:203], v[14:17]
	v_mfma_f32_16x16x32_bf16 v[10:13], v[110:113], v[200:203], v[10:13]
	v_mfma_f32_16x16x32_bf16 v[54:57], v[204:207], v[146:149], v[54:57]
	v_mfma_f32_16x16x32_bf16 v[50:53], v[212:215], v[146:149], v[50:53]
	v_mfma_f32_16x16x32_bf16 v[38:41], v[204:207], v[154:157], v[38:41]
	v_mfma_f32_16x16x32_bf16 v[34:37], v[212:215], v[154:157], v[34:37]
	v_mfma_f32_16x16x32_bf16 v[22:25], v[204:207], v[162:165], v[22:25]
	v_mfma_f32_16x16x32_bf16 v[18:21], v[212:215], v[162:165], v[18:21]
	v_mfma_f32_16x16x32_bf16 v[6:9], v[204:207], v[196:199], v[6:9]
	v_mfma_f32_16x16x32_bf16 v[2:5], v[212:215], v[196:199], v[2:5]
	v_mfma_f32_16x16x32_bf16 v[54:57], v[208:211], v[150:153], v[54:57]
	v_mfma_f32_16x16x32_bf16 v[50:53], v[216:219], v[150:153], v[50:53]
	v_mfma_f32_16x16x32_bf16 v[38:41], v[208:211], v[158:161], v[38:41]
	v_mfma_f32_16x16x32_bf16 v[34:37], v[216:219], v[158:161], v[34:37]
	v_mfma_f32_16x16x32_bf16 v[22:25], v[208:211], v[166:169], v[22:25]
	v_mfma_f32_16x16x32_bf16 v[18:21], v[216:219], v[166:169], v[18:21]
	v_mfma_f32_16x16x32_bf16 v[6:9], v[208:211], v[200:203], v[6:9]
	v_mfma_f32_16x16x32_bf16 v[2:5], v[216:219], v[200:203], v[2:5]
	s_barrier
	s_setprio 0
	s_add_u32 s20, s46, 0x40000
	s_addc_u32 s21, s47, 0
	s_add_i32 s74, s66, s52
	v_lshl_add_u64 v[246:247], s[20:21], 0, v[176:177]
	s_mov_b32 m0, s74
	s_nop 0
	global_load_lds_dwordx4 v[246:247], off
	v_lshl_add_u64 v[246:247], s[20:21], 0, v[180:181]
	s_add_i32 m0, s74, 0x2000
	s_nop 0
	global_load_lds_dwordx4 v[246:247], off
	s_add_i32 s20, 0, 0x18000
	v_add_u32_e32 v110, s20, v171
	ds_read_b128 v[98:101], v110
	ds_read_b128 v[102:105], v110 offset:1024
	ds_read_b128 v[106:109], v110 offset:2048
	ds_read_b128 v[110:113], v110 offset:3072
	s_add_u32 s18, s18, 0x40000
	s_addc_u32 s19, s19, 0
	s_mov_b32 m0, s55
	v_lshl_add_u64 v[204:205], s[18:19], 0, v[174:175]
	ds_read_b128 v[146:149], v185 offset:32768
	ds_read_b128 v[150:153], v185 offset:33792
	ds_read_b128 v[154:157], v185 offset:34816
	ds_read_b128 v[158:161], v185 offset:35840
	ds_read_b128 v[162:165], v185 offset:36864
	ds_read_b128 v[166:169], v185 offset:37888
	ds_read_b128 v[196:199], v185 offset:38912
	ds_read_b128 v[200:203], v185 offset:39936
	global_load_lds_dwordx4 v[204:205], off
	v_lshl_add_u64 v[204:205], s[18:19], 0, v[178:179]
	s_mov_b32 m0, s56
	s_nop 0
	global_load_lds_dwordx4 v[204:205], off
	s_add_i32 s21, 0, 0x1c000
	v_add_u32_e32 v182, s21, v171
	ds_read_b128 v[204:207], v182
	ds_read_b128 v[208:211], v182 offset:1024
	ds_read_b128 v[212:215], v182 offset:2048
	ds_read_b128 v[216:219], v182 offset:3072
	s_waitcnt vmcnt(8)
	s_waitcnt lgkmcnt(0)
	s_setprio 1
	s_barrier
	v_mfma_f32_16x16x32_bf16 v[142:145], v[98:101], v[146:149], v[142:145]
	v_mfma_f32_16x16x32_bf16 v[138:141], v[106:109], v[146:149], v[138:141]
	v_mfma_f32_16x16x32_bf16 v[126:129], v[98:101], v[154:157], v[126:129]
	v_mfma_f32_16x16x32_bf16 v[122:125], v[106:109], v[154:157], v[122:125]
	v_mfma_f32_16x16x32_bf16 v[94:97], v[98:101], v[162:165], v[94:97]
	v_mfma_f32_16x16x32_bf16 v[90:93], v[106:109], v[162:165], v[90:93]
	v_mfma_f32_16x16x32_bf16 v[78:81], v[98:101], v[196:199], v[78:81]
	v_mfma_f32_16x16x32_bf16 v[74:77], v[106:109], v[196:199], v[74:77]
	v_mfma_f32_16x16x32_bf16 v[142:145], v[102:105], v[150:153], v[142:145]
	v_mfma_f32_16x16x32_bf16 v[138:141], v[110:113], v[150:153], v[138:141]
	v_mfma_f32_16x16x32_bf16 v[126:129], v[102:105], v[158:161], v[126:129]
	v_mfma_f32_16x16x32_bf16 v[122:125], v[110:113], v[158:161], v[122:125]
	v_mfma_f32_16x16x32_bf16 v[94:97], v[102:105], v[166:169], v[94:97]
	v_mfma_f32_16x16x32_bf16 v[90:93], v[110:113], v[166:169], v[90:93]
	v_mfma_f32_16x16x32_bf16 v[78:81], v[102:105], v[200:203], v[78:81]
	v_mfma_f32_16x16x32_bf16 v[74:77], v[110:113], v[200:203], v[74:77]
	v_mfma_f32_16x16x32_bf16 v[134:137], v[204:207], v[146:149], v[134:137]
	v_mfma_f32_16x16x32_bf16 v[130:133], v[212:215], v[146:149], v[130:133]
	v_mfma_f32_16x16x32_bf16 v[118:121], v[204:207], v[154:157], v[118:121]
	v_mfma_f32_16x16x32_bf16 v[114:117], v[212:215], v[154:157], v[114:117]
	v_mfma_f32_16x16x32_bf16 v[86:89], v[204:207], v[162:165], v[86:89]
	v_mfma_f32_16x16x32_bf16 v[82:85], v[212:215], v[162:165], v[82:85]
	v_mfma_f32_16x16x32_bf16 v[70:73], v[204:207], v[196:199], v[70:73]
	v_mfma_f32_16x16x32_bf16 v[66:69], v[212:215], v[196:199], v[66:69]
	v_mfma_f32_16x16x32_bf16 v[134:137], v[208:211], v[150:153], v[134:137]
	v_mfma_f32_16x16x32_bf16 v[130:133], v[216:219], v[150:153], v[130:133]
	v_mfma_f32_16x16x32_bf16 v[118:121], v[208:211], v[158:161], v[118:121]
	v_mfma_f32_16x16x32_bf16 v[114:117], v[216:219], v[158:161], v[114:117]
	v_mfma_f32_16x16x32_bf16 v[86:89], v[208:211], v[166:169], v[86:89]
	v_mfma_f32_16x16x32_bf16 v[82:85], v[216:219], v[166:169], v[82:85]
	v_mfma_f32_16x16x32_bf16 v[70:73], v[208:211], v[200:203], v[70:73]
	v_mfma_f32_16x16x32_bf16 v[66:69], v[216:219], v[200:203], v[66:69]
	s_barrier
	s_setprio 0
	s_add_i32 s18, s20, s52
	v_lshl_add_u64 v[220:221], v[220:221], 0, s[10:11]
	s_mov_b32 m0, s18
	s_nop 0
	global_load_lds_dwordx4 v[220:221], off
	v_lshl_add_u64 v[220:221], v[224:225], 0, s[10:11]
	s_add_i32 m0, s18, 0x2000
	s_nop 0
	global_load_lds_dwordx4 v[220:221], off
	s_mov_b32 m0, s62
	v_lshl_add_u64 v[220:221], v[226:227], 0, s[10:11]
	ds_read_b128 v[146:149], v185 offset:49152
	ds_read_b128 v[150:153], v185 offset:50176
	ds_read_b128 v[154:157], v185 offset:51200
	ds_read_b128 v[158:161], v185 offset:52224
	ds_read_b128 v[162:165], v185 offset:53248
	ds_read_b128 v[166:169], v185 offset:54272
	ds_read_b128 v[196:199], v185 offset:55296
	ds_read_b128 v[200:203], v185 offset:56320
	global_load_lds_dwordx4 v[220:221], off
	v_lshl_add_u64 v[220:221], v[228:229], 0, s[10:11]
	s_mov_b32 m0, s63
	s_nop 0
	global_load_lds_dwordx4 v[220:221], off
	s_add_u32 s18, s46, 0x40080
	s_addc_u32 s19, s47, 0
	s_add_i32 s20, s21, s52
	v_lshl_add_u64 v[248:249], s[18:19], 0, v[176:177]
	s_mov_b32 m0, s20
	s_nop 0
	global_load_lds_dwordx4 v[248:249], off
	v_lshl_add_u64 v[248:249], s[18:19], 0, v[180:181]
	s_add_i32 m0, s20, 0x2000
	s_nop 0
	global_load_lds_dwordx4 v[248:249], off
	s_waitcnt vmcnt(6)
	s_waitcnt lgkmcnt(0)
	s_setprio 1
	s_barrier
	v_mfma_f32_16x16x32_bf16 v[62:65], v[98:101], v[146:149], v[62:65]
	v_mfma_f32_16x16x32_bf16 v[58:61], v[106:109], v[146:149], v[58:61]
	v_mfma_f32_16x16x32_bf16 v[46:49], v[98:101], v[154:157], v[46:49]
	v_mfma_f32_16x16x32_bf16 v[42:45], v[106:109], v[154:157], v[42:45]
	v_mfma_f32_16x16x32_bf16 v[30:33], v[98:101], v[162:165], v[30:33]
	v_mfma_f32_16x16x32_bf16 v[26:29], v[106:109], v[162:165], v[26:29]
	v_mfma_f32_16x16x32_bf16 v[14:17], v[98:101], v[196:199], v[14:17]
	v_mfma_f32_16x16x32_bf16 v[10:13], v[106:109], v[196:199], v[10:13]
	v_mfma_f32_16x16x32_bf16 v[62:65], v[102:105], v[150:153], v[62:65]
	v_mfma_f32_16x16x32_bf16 v[58:61], v[110:113], v[150:153], v[58:61]
	v_mfma_f32_16x16x32_bf16 v[46:49], v[102:105], v[158:161], v[46:49]
	v_mfma_f32_16x16x32_bf16 v[42:45], v[110:113], v[158:161], v[42:45]
	v_mfma_f32_16x16x32_bf16 v[30:33], v[102:105], v[166:169], v[30:33]
	v_mfma_f32_16x16x32_bf16 v[26:29], v[110:113], v[166:169], v[26:29]
	v_mfma_f32_16x16x32_bf16 v[14:17], v[102:105], v[200:203], v[14:17]
	v_mfma_f32_16x16x32_bf16 v[10:13], v[110:113], v[200:203], v[10:13]
	v_mfma_f32_16x16x32_bf16 v[54:57], v[204:207], v[146:149], v[54:57]
	v_mfma_f32_16x16x32_bf16 v[50:53], v[212:215], v[146:149], v[50:53]
	v_mfma_f32_16x16x32_bf16 v[38:41], v[204:207], v[154:157], v[38:41]
	v_mfma_f32_16x16x32_bf16 v[34:37], v[212:215], v[154:157], v[34:37]
	v_mfma_f32_16x16x32_bf16 v[22:25], v[204:207], v[162:165], v[22:25]
	v_mfma_f32_16x16x32_bf16 v[18:21], v[212:215], v[162:165], v[18:21]
	v_mfma_f32_16x16x32_bf16 v[6:9], v[204:207], v[196:199], v[6:9]
	v_mfma_f32_16x16x32_bf16 v[2:5], v[212:215], v[196:199], v[2:5]
	v_mfma_f32_16x16x32_bf16 v[54:57], v[208:211], v[150:153], v[54:57]
	v_mfma_f32_16x16x32_bf16 v[50:53], v[216:219], v[150:153], v[50:53]
	v_mfma_f32_16x16x32_bf16 v[38:41], v[208:211], v[158:161], v[38:41]
	v_mfma_f32_16x16x32_bf16 v[34:37], v[216:219], v[158:161], v[34:37]
	v_mfma_f32_16x16x32_bf16 v[22:25], v[208:211], v[166:169], v[22:25]
	v_mfma_f32_16x16x32_bf16 v[18:21], v[216:219], v[166:169], v[18:21]
	v_mfma_f32_16x16x32_bf16 v[6:9], v[208:211], v[200:203], v[6:9]
	v_mfma_f32_16x16x32_bf16 v[2:5], v[216:219], v[200:203], v[2:5]
	s_barrier
	s_setprio 0
	s_add_i32 s73, s73, 2
	s_add_u32 s44, s44, 0x100
	s_addc_u32 s45, s45, 0
	s_add_u32 s71, s71, 0x100
	s_addc_u32 s72, s72, 0
	s_cmp_gt_u32 s73, 13
	s_cbranch_scc0 .LBB0_2845
	s_ashr_i32 s18, s42, 3
	s_mul_hi_i32 s19, s18, 0x9000
	s_mul_i32 s18, s18, 0x9000
	s_add_u32 s20, s58, s18
	s_addc_u32 s21, s59, s19
	s_lshl_b32 s44, s0, 8
	v_lshl_add_u32 v220, s42, 8, v1
	s_ashr_i32 s45, s44, 31
	s_lshl_b64 s[18:19], s[44:45], 2
	v_ashrrev_i32_e32 v221, 31, v220
	v_lshl_add_u64 v[146:147], s[44:45], 1, v[186:187]
	v_lshlrev_b64 v[98:99], 11, v[220:221]
	s_add_u32 s18, s20, s18
	v_lshl_add_u64 v[98:99], v[146:147], 0, v[98:99]
	s_addc_u32 s19, s21, s19
	v_lshlrev_b32_e32 v182, 2, v184
	global_load_dwordx4 v[224:227], v[98:99], off
	global_load_dwordx4 v[234:237], v[98:99], off offset:256
	v_lshl_add_u64 v[98:99], s[18:19], 0, v[182:183]
	v_add_co_u32_e32 v102, vcc, s68, v98
	v_lshl_add_u64 v[100:101], v[98:99], 0, s[16:17]
	s_nop 0
	v_addc_co_u32_e32 v103, vcc, 0, v99, vcc
	global_load_dwordx4 v[198:201], v[102:103], off
	global_load_dwordx4 v[238:241], v[100:101], off offset:16
	global_load_dwordx4 v[202:205], v[102:103], off offset:512
	v_lshl_add_u64 v[100:101], v[98:99], 0, s[24:25]
	global_load_dwordx4 v[242:245], v[100:101], off offset:16
	v_add_co_u32_e32 v100, vcc, s67, v98
	v_or_b32_e32 v218, 16, v220
	s_nop 0
	v_addc_co_u32_e32 v101, vcc, 0, v99, vcc
	global_load_dwordx4 v[110:113], v[100:101], off
	global_load_dwordx4 v[106:109], v[100:101], off offset:512
	v_lshl_add_u64 v[100:101], v[98:99], 0, s[12:13]
	v_lshl_add_u64 v[98:99], v[98:99], 0, s[14:15]
	global_load_dwordx4 v[102:105], v[100:101], off offset:16
	v_or_b32_e32 v216, 32, v220
	global_load_dwordx4 v[98:101], v[98:99], off offset:16
	v_or_b32_e32 v214, 48, v220
	v_ashrrev_i32_e32 v219, 31, v218
	v_ashrrev_i32_e32 v217, 31, v216
	v_ashrrev_i32_e32 v215, 31, v214
	v_lshlrev_b64 v[148:149], 11, v[218:219]
	v_lshlrev_b64 v[150:151], 11, v[216:217]
	v_lshlrev_b64 v[152:153], 11, v[214:215]
	v_lshl_add_u64 v[148:149], v[146:147], 0, v[148:149]
	v_lshl_add_u64 v[150:151], v[146:147], 0, v[150:151]
	v_lshl_add_u64 v[146:147], v[146:147], 0, v[152:153]
	global_load_dwordx4 v[166:169], v[148:149], off
	global_load_dwordx4 v[162:165], v[148:149], off offset:256
	global_load_dwordx4 v[158:161], v[150:151], off
	global_load_dwordx4 v[154:157], v[150:151], off offset:256
	s_nop 0
	global_load_dwordx4 v[150:153], v[146:147], off
	s_nop 0
	global_load_dwordx4 v[146:149], v[146:147], off offset:256
	v_or_b32_e32 v196, s44, v184
	v_mov_b32_e32 v197, s45
	s_lshl_b32 s42, s0, 2
	s_ashr_i32 s43, s42, 31
	s_waitcnt vmcnt(0)
	v_lshlrev_b32_e32 v228, 16, v224
	v_and_b32_e32 v229, 0xffff0000, v224
	v_lshlrev_b32_e32 v224, 16, v225
	v_and_b32_e32 v225, 0xffff0000, v225
	v_lshlrev_b32_e32 v250, 16, v236
	v_and_b32_e32 v251, 0xffff0000, v236
	v_lshlrev_b32_e32 v248, 16, v226
	v_and_b32_e32 v249, 0xffff0000, v226
	v_lshlrev_b32_e32 v246, 16, v234
	v_and_b32_e32 v247, 0xffff0000, v234
	v_lshlrev_b32_e32 v234, 16, v235
	v_and_b32_e32 v235, 0xffff0000, v235
	v_pk_add_f32 v[210:211], v[202:203], 1.0 op_sel_hi:[1,0]
	v_pk_add_f32 v[206:207], v[204:205], 1.0 op_sel_hi:[1,0]
	v_pk_add_f32 v[208:209], v[200:201], 1.0 op_sel_hi:[1,0]
	v_pk_fma_f32 v[144:145], v[144:145], v[112:113], v[224:225]
	v_pk_fma_f32 v[142:143], v[142:143], v[110:111], v[228:229]
	v_pk_fma_f32 v[134:135], v[134:135], v[106:107], v[246:247]
	v_pk_fma_f32 v[136:137], v[136:137], v[108:109], v[234:235]
	v_pk_fma_f32 v[138:139], v[138:139], v[102:103], v[248:249]
	v_pk_mul_f32 v[234:235], v[210:211], v[134:135]
	v_pk_fma_f32 v[224:225], v[130:131], v[98:99], v[250:251]
	v_lshlrev_b32_e32 v130, 16, v227
	v_and_b32_e32 v131, 0xffff0000, v227
	v_pk_fma_f32 v[140:141], v[140:141], v[104:105], v[130:131]
	v_lshlrev_b32_e32 v130, 16, v237
	v_and_b32_e32 v131, 0xffff0000, v237
	v_pk_fma_f32 v[236:237], v[132:133], v[100:101], v[130:131]
	v_lshlrev_b64 v[130:131], 10, v[220:221]
	v_lshl_add_u64 v[130:131], v[130:131], 0, v[196:197]
	v_lshlrev_b64 v[248:249], 1, v[130:131]
	v_lshl_add_u64 v[250:251], s[28:29], 0, v[248:249]
	v_cvt_pk_bf16_f32 v130, v142, v143
	v_cvt_pk_bf16_f32 v131, v144, v145
	v_cvt_pk_bf16_f32 v132, v138, v139
	v_cvt_pk_bf16_f32 v133, v140, v141
	global_store_dwordx4 v[250:251], v[130:133], off nt
	v_pk_add_f32 v[200:201], v[240:241], 1.0 op_sel_hi:[1,0]
	v_pk_mul_f32 v[240:241], v[206:207], v[136:137]
	v_cvt_pk_bf16_f32 v130, v134, v135
	v_cvt_pk_bf16_f32 v131, v136, v137
	v_cvt_pk_bf16_f32 v132, v224, v225
	v_cvt_pk_bf16_f32 v133, v236, v237
	global_store_dwordx4 v[250:251], v[130:133], off offset:256 nt
	v_pk_add_f32 v[204:205], v[238:239], 1.0 op_sel_hi:[1,0]
	v_pk_add_f32 v[202:203], v[242:243], 1.0 op_sel_hi:[1,0]
	v_pk_mul_f32 v[132:133], v[134:135], v[134:135]
	v_pk_mul_f32 v[134:135], v[136:137], v[136:137]
	v_pk_fma_f32 v[132:133], v[142:143], v[142:143], v[132:133]
	v_pk_fma_f32 v[134:135], v[144:145], v[144:145], v[134:135]
	v_add_f32_e32 v132, v132, v133
	v_pk_mul_f32 v[136:137], v[224:225], v[224:225]
	v_add_f32_e32 v132, v134, v132
	v_pk_fma_f32 v[136:137], v[138:139], v[138:139], v[136:137]
	v_add_f32_e32 v132, v135, v132
	v_pk_mul_f32 v[242:243], v[204:205], v[138:139]
	v_pk_mul_f32 v[138:139], v[236:237], v[236:237]
	v_add_f32_e32 v132, v136, v132
	v_pk_fma_f32 v[138:139], v[140:141], v[140:141], v[138:139]
	v_add_f32_e32 v132, v137, v132
	v_add_f32_e32 v132, v138, v132
	v_and_b32_e32 v133, 64, v223
	v_add_f32_e32 v134, v139, v132
	v_xor_b32_e32 v132, 16, v223
	v_add_u32_e32 v135, 64, v133
	v_cmp_lt_i32_e32 vcc, v132, v135
	v_pk_add_f32 v[212:213], v[198:199], 1.0 op_sel_hi:[1,0]
	v_pk_mul_f32 v[238:239], v[208:209], v[144:145]
	v_cndmask_b32_e32 v132, v223, v132, vcc
	v_pk_mul_f32 v[228:229], v[212:213], v[142:143]
	v_lshlrev_b32_e32 v142, 2, v132
	v_pk_mul_f32 v[226:227], v[200:201], v[140:141]
	ds_bpermute_b32 v136, v142, v134
	v_lshl_add_u64 v[248:249], s[6:7], 0, v[248:249]
	v_cvt_pk_bf16_f32 v130, v228, v229
	v_cvt_pk_bf16_f32 v131, v238, v239
	v_cvt_pk_bf16_f32 v132, v242, v243
	v_cvt_pk_bf16_f32 v133, v226, v227
	global_store_dwordx4 v[248:249], v[130:133], off nt
	v_pk_add_f32 v[198:199], v[244:245], 1.0 op_sel_hi:[1,0]
	v_pk_mul_f32 v[244:245], v[202:203], v[224:225]
	v_xor_b32_e32 v131, 32, v223
	v_cmp_lt_i32_e32 vcc, v131, v135
	s_waitcnt lgkmcnt(0)
	v_add_f32_e32 v130, v134, v136
	v_pk_mul_f32 v[246:247], v[198:199], v[236:237]
	v_cndmask_b32_e32 v131, v223, v131, vcc
	v_lshlrev_b32_e32 v143, 2, v131
	ds_bpermute_b32 v131, v143, v130
	v_cvt_pk_bf16_f32 v132, v234, v235
	v_cvt_pk_bf16_f32 v133, v240, v241
	v_cvt_pk_bf16_f32 v134, v244, v245
	v_cvt_pk_bf16_f32 v135, v246, v247
	global_store_dwordx4 v[248:249], v[132:135], off offset:256 nt
	s_and_saveexec_b64 s[18:19], s[2:3]
	s_cbranch_execz .LBB0_2848
	s_waitcnt lgkmcnt(0)
	v_add_f32_e32 v132, v130, v131
	v_lshlrev_b64 v[130:131], 6, v[220:221]
	v_lshl_add_u64 v[130:131], s[8:9], 0, v[130:131]
	v_lshl_add_u64 v[130:131], s[42:43], 2, v[130:131]
	s_lshl_b32 s0, s61, 2
	v_lshl_add_u64 v[130:131], v[130:131], 0, s[0:1]
	global_store_dword v[130:131], v132, off

.LBB0_3264:
	s_ashr_i32 s11, s10, 31
	v_cmp_lt_i64_e32 vcc, s[12:13], v[162:163]
	s_lshl_b64 s[12:13], s[10:11], 19
	s_add_u32 s12, s36, s12
	s_addc_u32 s13, s37, s13
	s_and_b64 s[14:15], vcc, exec
	s_cselect_b32 s11, s13, s25
	s_cselect_b32 s57, s12, s24
	s_ashr_i32 s9, s8, 31
	s_lshl_b64 s[14:15], s[8:9], 19
	s_add_u32 s14, s38, s14
	s_addc_u32 s15, s39, s15
	s_and_b64 s[18:19], vcc, exec
	s_cselect_b32 s9, s15, s35
	s_cselect_b32 s60, s14, s34
	s_add_u32 s24, s24, 0x40080
	s_addc_u32 s25, s25, 0
	s_add_u32 s61, s34, 0x100
	s_addc_u32 s62, s35, 0
	s_mov_b32 s63, -2
	ds_read_b128 v[130:133], v171
	ds_read_b128 v[134:137], v171 offset:1024
	ds_read_b128 v[138:141], v171 offset:2048
	ds_read_b128 v[142:145], v171 offset:3072
	s_add_u32 s18, s24, 0xfffc0080
	s_addc_u32 s19, s25, -1
	s_cmp_eq_u32 s63, 12
	s_cselect_b32 s19, s11, s19
	s_cselect_b32 s18, s57, s18
	s_cselect_b32 s35, s9, s62
	s_cselect_b32 s34, s60, s61
	v_lshl_add_u64 v[174:175], s[24:25], 0, v[158:159]
	s_add_i32 m0, s43, 0xc000
	ds_read_b128 v[166:169], v173
	ds_read_b128 v[178:181], v173 offset:1024
	ds_read_b128 v[182:185], v173 offset:2048
	ds_read_b128 v[186:189], v173 offset:3072
	ds_read_b128 v[190:193], v173 offset:4096
	ds_read_b128 v[194:197], v173 offset:5120
	ds_read_b128 v[198:201], v173 offset:6144
	ds_read_b128 v[202:205], v173 offset:7168
	global_load_lds_dwordx4 v[174:175], off
	v_lshl_add_u64 v[174:175], s[24:25], 0, v[160:161]
	s_add_i32 m0, s43, 0xe000
	s_nop 0
	global_load_lds_dwordx4 v[174:175], off
	ds_read_b128 v[206:209], v177
	ds_read_b128 v[210:213], v177 offset:1024
	ds_read_b128 v[214:217], v177 offset:2048
	ds_read_b128 v[218:221], v177 offset:3072
	s_waitcnt lgkmcnt(0)
	s_setprio 1
	s_barrier
	v_mfma_f32_16x16x32_bf16 v[126:129], v[130:133], v[166:169], 0
	v_mfma_f32_16x16x32_bf16 v[122:125], v[138:141], v[166:169], 0
	v_mfma_f32_16x16x32_bf16 v[110:113], v[130:133], v[182:185], 0
	v_mfma_f32_16x16x32_bf16 v[106:109], v[138:141], v[182:185], 0
	v_mfma_f32_16x16x32_bf16 v[94:97], v[130:133], v[190:193], 0
	v_mfma_f32_16x16x32_bf16 v[90:93], v[138:141], v[190:193], 0
	v_mfma_f32_16x16x32_bf16 v[78:81], v[130:133], v[198:201], 0
	v_mfma_f32_16x16x32_bf16 v[74:77], v[138:141], v[198:201], 0
	v_mfma_f32_16x16x32_bf16 v[126:129], v[134:137], v[178:181], v[126:129]
	v_mfma_f32_16x16x32_bf16 v[122:125], v[142:145], v[178:181], v[122:125]
	v_mfma_f32_16x16x32_bf16 v[110:113], v[134:137], v[186:189], v[110:113]
	v_mfma_f32_16x16x32_bf16 v[106:109], v[142:145], v[186:189], v[106:109]
	v_mfma_f32_16x16x32_bf16 v[94:97], v[134:137], v[194:197], v[94:97]
	v_mfma_f32_16x16x32_bf16 v[90:93], v[142:145], v[194:197], v[90:93]
	v_mfma_f32_16x16x32_bf16 v[78:81], v[134:137], v[202:205], v[78:81]
	v_mfma_f32_16x16x32_bf16 v[74:77], v[142:145], v[202:205], v[74:77]
	v_mfma_f32_16x16x32_bf16 v[118:121], v[206:209], v[166:169], 0
	v_mfma_f32_16x16x32_bf16 v[114:117], v[214:217], v[166:169], 0
	v_mfma_f32_16x16x32_bf16 v[102:105], v[206:209], v[182:185], 0
	v_mfma_f32_16x16x32_bf16 v[98:101], v[214:217], v[182:185], 0
	v_mfma_f32_16x16x32_bf16 v[86:89], v[206:209], v[190:193], 0
	v_mfma_f32_16x16x32_bf16 v[82:85], v[214:217], v[190:193], 0
	v_mfma_f32_16x16x32_bf16 v[70:73], v[206:209], v[198:201], 0
	v_mfma_f32_16x16x32_bf16 v[66:69], v[214:217], v[198:201], 0
	v_mfma_f32_16x16x32_bf16 v[118:121], v[210:213], v[178:181], v[118:121]
	v_mfma_f32_16x16x32_bf16 v[114:117], v[218:221], v[178:181], v[114:117]
	v_mfma_f32_16x16x32_bf16 v[102:105], v[210:213], v[186:189], v[102:105]
	v_mfma_f32_16x16x32_bf16 v[98:101], v[218:221], v[186:189], v[98:101]
	v_mfma_f32_16x16x32_bf16 v[86:89], v[210:213], v[194:197], v[86:89]
	v_mfma_f32_16x16x32_bf16 v[82:85], v[218:221], v[194:197], v[82:85]
	v_mfma_f32_16x16x32_bf16 v[70:73], v[210:213], v[202:205], v[70:73]
	v_mfma_f32_16x16x32_bf16 v[66:69], v[218:221], v[202:205], v[66:69]
	s_barrier
	s_setprio 0
	s_add_i32 s20, s54, s42
	v_lshl_add_u64 v[174:175], s[34:35], 0, v[150:151]
	s_mov_b32 m0, s20
	s_nop 0
	global_load_lds_dwordx4 v[174:175], off
	v_lshl_add_u64 v[222:223], s[34:35], 0, v[146:147]
	s_add_i32 m0, s20, 0x2000
	s_nop 0
	global_load_lds_dwordx4 v[222:223], off
	s_mov_b32 m0, s43
	v_lshl_add_u64 v[224:225], s[18:19], 0, v[152:153]
	ds_read_b128 v[166:169], v173 offset:16384
	ds_read_b128 v[178:181], v173 offset:17408
	ds_read_b128 v[182:185], v173 offset:18432
	ds_read_b128 v[186:189], v173 offset:19456
	ds_read_b128 v[190:193], v173 offset:20480
	ds_read_b128 v[194:197], v173 offset:21504
	ds_read_b128 v[198:201], v173 offset:22528
	ds_read_b128 v[202:205], v173 offset:23552
	global_load_lds_dwordx4 v[224:225], off
	v_lshl_add_u64 v[226:227], s[18:19], 0, v[148:149]
	s_mov_b32 m0, s44
	s_nop 0
	global_load_lds_dwordx4 v[226:227], off
	s_waitcnt vmcnt(6)
	s_waitcnt lgkmcnt(0)
	s_setprio 1
	s_barrier
	v_mfma_f32_16x16x32_bf16 v[62:65], v[130:133], v[166:169], 0
	v_mfma_f32_16x16x32_bf16 v[58:61], v[138:141], v[166:169], 0
	v_mfma_f32_16x16x32_bf16 v[46:49], v[130:133], v[182:185], 0
	v_mfma_f32_16x16x32_bf16 v[42:45], v[138:141], v[182:185], 0
	v_mfma_f32_16x16x32_bf16 v[30:33], v[130:133], v[190:193], 0
	v_mfma_f32_16x16x32_bf16 v[26:29], v[138:141], v[190:193], 0
	v_mfma_f32_16x16x32_bf16 v[14:17], v[130:133], v[198:201], 0
	v_mfma_f32_16x16x32_bf16 v[10:13], v[138:141], v[198:201], 0
	v_mfma_f32_16x16x32_bf16 v[62:65], v[134:137], v[178:181], v[62:65]
	v_mfma_f32_16x16x32_bf16 v[58:61], v[142:145], v[178:181], v[58:61]
	v_mfma_f32_16x16x32_bf16 v[46:49], v[134:137], v[186:189], v[46:49]
	v_mfma_f32_16x16x32_bf16 v[42:45], v[142:145], v[186:189], v[42:45]
	v_mfma_f32_16x16x32_bf16 v[30:33], v[134:137], v[194:197], v[30:33]
	v_mfma_f32_16x16x32_bf16 v[26:29], v[142:145], v[194:197], v[26:29]
	v_mfma_f32_16x16x32_bf16 v[14:17], v[134:137], v[202:205], v[14:17]
	v_mfma_f32_16x16x32_bf16 v[10:13], v[142:145], v[202:205], v[10:13]
	v_mfma_f32_16x16x32_bf16 v[54:57], v[206:209], v[166:169], 0
	v_mfma_f32_16x16x32_bf16 v[50:53], v[214:217], v[166:169], 0
	v_mfma_f32_16x16x32_bf16 v[38:41], v[206:209], v[182:185], 0
	v_mfma_f32_16x16x32_bf16 v[34:37], v[214:217], v[182:185], 0
	v_mfma_f32_16x16x32_bf16 v[22:25], v[206:209], v[190:193], 0
	v_mfma_f32_16x16x32_bf16 v[18:21], v[214:217], v[190:193], 0
	v_mfma_f32_16x16x32_bf16 v[6:9], v[206:209], v[198:201], 0
	v_mfma_f32_16x16x32_bf16 v[2:5], v[214:217], v[198:201], 0
	v_mfma_f32_16x16x32_bf16 v[54:57], v[210:213], v[178:181], v[54:57]
	v_mfma_f32_16x16x32_bf16 v[50:53], v[218:221], v[178:181], v[50:53]
	v_mfma_f32_16x16x32_bf16 v[38:41], v[210:213], v[186:189], v[38:41]
	v_mfma_f32_16x16x32_bf16 v[34:37], v[218:221], v[186:189], v[34:37]
	v_mfma_f32_16x16x32_bf16 v[22:25], v[210:213], v[194:197], v[22:25]
	v_mfma_f32_16x16x32_bf16 v[18:21], v[218:221], v[194:197], v[18:21]
	v_mfma_f32_16x16x32_bf16 v[6:9], v[210:213], v[202:205], v[6:9]
	v_mfma_f32_16x16x32_bf16 v[2:5], v[218:221], v[202:205], v[2:5]
	s_barrier
	s_setprio 0
	s_add_u32 s20, s34, 0x40000
	s_addc_u32 s21, s35, 0
	s_add_i32 s64, s55, s42
	v_lshl_add_u64 v[246:247], s[20:21], 0, v[150:151]
	s_mov_b32 m0, s64
	s_nop 0
	global_load_lds_dwordx4 v[246:247], off
	v_lshl_add_u64 v[246:247], s[20:21], 0, v[146:147]
	s_add_i32 m0, s64, 0x2000
	s_nop 0
	global_load_lds_dwordx4 v[246:247], off
	s_add_i32 s20, 0, 0x18000
	v_add_u32_e32 v142, s20, v157
	ds_read_b128 v[130:133], v142
	ds_read_b128 v[134:137], v142 offset:1024
	ds_read_b128 v[138:141], v142 offset:2048
	ds_read_b128 v[142:145], v142 offset:3072
	s_add_u32 s18, s18, 0x40000
	s_addc_u32 s19, s19, 0
	s_mov_b32 m0, s45
	v_lshl_add_u64 v[206:207], s[18:19], 0, v[152:153]
	ds_read_b128 v[166:169], v173 offset:32768
	ds_read_b128 v[178:181], v173 offset:33792
	ds_read_b128 v[182:185], v173 offset:34816
	ds_read_b128 v[186:189], v173 offset:35840
	ds_read_b128 v[190:193], v173 offset:36864
	ds_read_b128 v[194:197], v173 offset:37888
	ds_read_b128 v[198:201], v173 offset:38912
	ds_read_b128 v[202:205], v173 offset:39936
	global_load_lds_dwordx4 v[206:207], off
	v_lshl_add_u64 v[206:207], s[18:19], 0, v[148:149]
	s_mov_b32 m0, s46
	s_nop 0
	global_load_lds_dwordx4 v[206:207], off
	s_add_i32 s21, 0, 0x1c000
	v_add_u32_e32 v154, s21, v157
	ds_read_b128 v[206:209], v154
	ds_read_b128 v[210:213], v154 offset:1024
	ds_read_b128 v[214:217], v154 offset:2048
	ds_read_b128 v[218:221], v154 offset:3072
	s_waitcnt vmcnt(8)
	s_waitcnt lgkmcnt(0)
	s_setprio 1
	s_barrier
	v_mfma_f32_16x16x32_bf16 v[126:129], v[130:133], v[166:169], v[126:129]
	v_mfma_f32_16x16x32_bf16 v[122:125], v[138:141], v[166:169], v[122:125]
	v_mfma_f32_16x16x32_bf16 v[110:113], v[130:133], v[182:185], v[110:113]
	v_mfma_f32_16x16x32_bf16 v[106:109], v[138:141], v[182:185], v[106:109]
	v_mfma_f32_16x16x32_bf16 v[94:97], v[130:133], v[190:193], v[94:97]
	v_mfma_f32_16x16x32_bf16 v[90:93], v[138:141], v[190:193], v[90:93]
	v_mfma_f32_16x16x32_bf16 v[78:81], v[130:133], v[198:201], v[78:81]
	v_mfma_f32_16x16x32_bf16 v[74:77], v[138:141], v[198:201], v[74:77]
	v_mfma_f32_16x16x32_bf16 v[126:129], v[134:137], v[178:181], v[126:129]
	v_mfma_f32_16x16x32_bf16 v[122:125], v[142:145], v[178:181], v[122:125]
	v_mfma_f32_16x16x32_bf16 v[110:113], v[134:137], v[186:189], v[110:113]
	v_mfma_f32_16x16x32_bf16 v[106:109], v[142:145], v[186:189], v[106:109]
	v_mfma_f32_16x16x32_bf16 v[94:97], v[134:137], v[194:197], v[94:97]
	v_mfma_f32_16x16x32_bf16 v[90:93], v[142:145], v[194:197], v[90:93]
	v_mfma_f32_16x16x32_bf16 v[78:81], v[134:137], v[202:205], v[78:81]
	v_mfma_f32_16x16x32_bf16 v[74:77], v[142:145], v[202:205], v[74:77]
	v_mfma_f32_16x16x32_bf16 v[118:121], v[206:209], v[166:169], v[118:121]
	v_mfma_f32_16x16x32_bf16 v[114:117], v[214:217], v[166:169], v[114:117]
	v_mfma_f32_16x16x32_bf16 v[102:105], v[206:209], v[182:185], v[102:105]
	v_mfma_f32_16x16x32_bf16 v[98:101], v[214:217], v[182:185], v[98:101]
	v_mfma_f32_16x16x32_bf16 v[86:89], v[206:209], v[190:193], v[86:89]
	v_mfma_f32_16x16x32_bf16 v[82:85], v[214:217], v[190:193], v[82:85]
	v_mfma_f32_16x16x32_bf16 v[70:73], v[206:209], v[198:201], v[70:73]
	v_mfma_f32_16x16x32_bf16 v[66:69], v[214:217], v[198:201], v[66:69]
	v_mfma_f32_16x16x32_bf16 v[118:121], v[210:213], v[178:181], v[118:121]
	v_mfma_f32_16x16x32_bf16 v[114:117], v[218:221], v[178:181], v[114:117]
	v_mfma_f32_16x16x32_bf16 v[102:105], v[210:213], v[186:189], v[102:105]
	v_mfma_f32_16x16x32_bf16 v[98:101], v[218:221], v[186:189], v[98:101]
	v_mfma_f32_16x16x32_bf16 v[86:89], v[210:213], v[194:197], v[86:89]
	v_mfma_f32_16x16x32_bf16 v[82:85], v[218:221], v[194:197], v[82:85]
	v_mfma_f32_16x16x32_bf16 v[70:73], v[210:213], v[202:205], v[70:73]
	v_mfma_f32_16x16x32_bf16 v[66:69], v[218:221], v[202:205], v[66:69]
	s_barrier
	s_setprio 0
	s_add_i32 s18, s20, s42
	v_lshl_add_u64 v[174:175], v[174:175], 0, s[6:7]
	s_mov_b32 m0, s18
	s_nop 0
	global_load_lds_dwordx4 v[174:175], off
	v_lshl_add_u64 v[174:175], v[222:223], 0, s[6:7]
	s_add_i32 m0, s18, 0x2000
	s_nop 0
	global_load_lds_dwordx4 v[174:175], off
	s_mov_b32 m0, s50
	v_lshl_add_u64 v[174:175], v[224:225], 0, s[6:7]
	ds_read_b128 v[166:169], v173 offset:49152
	ds_read_b128 v[178:181], v173 offset:50176
	ds_read_b128 v[182:185], v173 offset:51200
	ds_read_b128 v[186:189], v173 offset:52224
	ds_read_b128 v[190:193], v173 offset:53248
	ds_read_b128 v[194:197], v173 offset:54272
	ds_read_b128 v[198:201], v173 offset:55296
	ds_read_b128 v[202:205], v173 offset:56320
	global_load_lds_dwordx4 v[174:175], off
	v_lshl_add_u64 v[174:175], v[226:227], 0, s[6:7]
	s_mov_b32 m0, s51
	s_nop 0
	global_load_lds_dwordx4 v[174:175], off
	s_add_u32 s18, s34, 0x40080
	s_addc_u32 s19, s35, 0
	s_add_i32 s20, s21, s42
	v_lshl_add_u64 v[248:249], s[18:19], 0, v[150:151]
	s_mov_b32 m0, s20
	s_nop 0
	global_load_lds_dwordx4 v[248:249], off
	v_lshl_add_u64 v[248:249], s[18:19], 0, v[146:147]
	s_add_i32 m0, s20, 0x2000
	s_nop 0
	global_load_lds_dwordx4 v[248:249], off
	s_waitcnt vmcnt(6)
	s_waitcnt lgkmcnt(0)
	s_setprio 1
	s_barrier
	v_mfma_f32_16x16x32_bf16 v[62:65], v[130:133], v[166:169], v[62:65]
	v_mfma_f32_16x16x32_bf16 v[58:61], v[138:141], v[166:169], v[58:61]
	v_mfma_f32_16x16x32_bf16 v[46:49], v[130:133], v[182:185], v[46:49]
	v_mfma_f32_16x16x32_bf16 v[42:45], v[138:141], v[182:185], v[42:45]
	v_mfma_f32_16x16x32_bf16 v[30:33], v[130:133], v[190:193], v[30:33]
	v_mfma_f32_16x16x32_bf16 v[26:29], v[138:141], v[190:193], v[26:29]
	v_mfma_f32_16x16x32_bf16 v[14:17], v[130:133], v[198:201], v[14:17]
	v_mfma_f32_16x16x32_bf16 v[10:13], v[138:141], v[198:201], v[10:13]
	v_mfma_f32_16x16x32_bf16 v[62:65], v[134:137], v[178:181], v[62:65]
	v_mfma_f32_16x16x32_bf16 v[58:61], v[142:145], v[178:181], v[58:61]
	v_mfma_f32_16x16x32_bf16 v[46:49], v[134:137], v[186:189], v[46:49]
	v_mfma_f32_16x16x32_bf16 v[42:45], v[142:145], v[186:189], v[42:45]
	v_mfma_f32_16x16x32_bf16 v[30:33], v[134:137], v[194:197], v[30:33]
	v_mfma_f32_16x16x32_bf16 v[26:29], v[142:145], v[194:197], v[26:29]
	v_mfma_f32_16x16x32_bf16 v[14:17], v[134:137], v[202:205], v[14:17]
	v_mfma_f32_16x16x32_bf16 v[10:13], v[142:145], v[202:205], v[10:13]
	v_mfma_f32_16x16x32_bf16 v[54:57], v[206:209], v[166:169], v[54:57]
	v_mfma_f32_16x16x32_bf16 v[50:53], v[214:217], v[166:169], v[50:53]
	v_mfma_f32_16x16x32_bf16 v[38:41], v[206:209], v[182:185], v[38:41]
	v_mfma_f32_16x16x32_bf16 v[34:37], v[214:217], v[182:185], v[34:37]
	v_mfma_f32_16x16x32_bf16 v[22:25], v[206:209], v[190:193], v[22:25]
	v_mfma_f32_16x16x32_bf16 v[18:21], v[214:217], v[190:193], v[18:21]
	v_mfma_f32_16x16x32_bf16 v[6:9], v[206:209], v[198:201], v[6:9]
	v_mfma_f32_16x16x32_bf16 v[2:5], v[214:217], v[198:201], v[2:5]
	v_mfma_f32_16x16x32_bf16 v[54:57], v[210:213], v[178:181], v[54:57]
	v_mfma_f32_16x16x32_bf16 v[50:53], v[218:221], v[178:181], v[50:53]
	v_mfma_f32_16x16x32_bf16 v[38:41], v[210:213], v[186:189], v[38:41]
	v_mfma_f32_16x16x32_bf16 v[34:37], v[218:221], v[186:189], v[34:37]
	v_mfma_f32_16x16x32_bf16 v[22:25], v[210:213], v[194:197], v[22:25]
	v_mfma_f32_16x16x32_bf16 v[18:21], v[218:221], v[194:197], v[18:21]
	v_mfma_f32_16x16x32_bf16 v[6:9], v[210:213], v[202:205], v[6:9]
	v_mfma_f32_16x16x32_bf16 v[2:5], v[218:221], v[202:205], v[2:5]
	s_barrier
	s_setprio 0
	s_add_i32 s63, s63, 2
	s_add_u32 s24, s24, 0x100
	s_addc_u32 s25, s25, 0
	s_add_u32 s61, s61, 0x100
	s_addc_u32 s62, s62, 0
	s_cmp_gt_u32 s63, 13
.LBB0_3265:
	ds_read_b128 v[130:133], v171
	ds_read_b128 v[134:137], v171 offset:1024
	ds_read_b128 v[138:141], v171 offset:2048
	ds_read_b128 v[142:145], v171 offset:3072
	s_add_u32 s18, s24, 0xfffc0080
	s_addc_u32 s19, s25, -1
	s_cmp_eq_u32 s63, 12
	s_cselect_b32 s19, s11, s19
	s_cselect_b32 s18, s57, s18
	s_cselect_b32 s35, s9, s62
	s_cselect_b32 s34, s60, s61
	v_lshl_add_u64 v[174:175], s[24:25], 0, v[158:159]
	s_add_i32 m0, s43, 0xc000
	ds_read_b128 v[166:169], v173
	ds_read_b128 v[178:181], v173 offset:1024
	ds_read_b128 v[182:185], v173 offset:2048
	ds_read_b128 v[186:189], v173 offset:3072
	ds_read_b128 v[190:193], v173 offset:4096
	ds_read_b128 v[194:197], v173 offset:5120
	ds_read_b128 v[198:201], v173 offset:6144
	ds_read_b128 v[202:205], v173 offset:7168
	global_load_lds_dwordx4 v[174:175], off
	v_lshl_add_u64 v[174:175], s[24:25], 0, v[160:161]
	s_add_i32 m0, s43, 0xe000
	s_nop 0
	global_load_lds_dwordx4 v[174:175], off
	ds_read_b128 v[206:209], v177
	ds_read_b128 v[210:213], v177 offset:1024
	ds_read_b128 v[214:217], v177 offset:2048
	ds_read_b128 v[218:221], v177 offset:3072
	s_waitcnt lgkmcnt(0)
	s_setprio 1
	s_barrier
	v_mfma_f32_16x16x32_bf16 v[126:129], v[130:133], v[166:169], v[126:129]
	v_mfma_f32_16x16x32_bf16 v[122:125], v[138:141], v[166:169], v[122:125]
	v_mfma_f32_16x16x32_bf16 v[110:113], v[130:133], v[182:185], v[110:113]
	v_mfma_f32_16x16x32_bf16 v[106:109], v[138:141], v[182:185], v[106:109]
	v_mfma_f32_16x16x32_bf16 v[94:97], v[130:133], v[190:193], v[94:97]
	v_mfma_f32_16x16x32_bf16 v[90:93], v[138:141], v[190:193], v[90:93]
	v_mfma_f32_16x16x32_bf16 v[78:81], v[130:133], v[198:201], v[78:81]
	v_mfma_f32_16x16x32_bf16 v[74:77], v[138:141], v[198:201], v[74:77]
	v_mfma_f32_16x16x32_bf16 v[126:129], v[134:137], v[178:181], v[126:129]
	v_mfma_f32_16x16x32_bf16 v[122:125], v[142:145], v[178:181], v[122:125]
	v_mfma_f32_16x16x32_bf16 v[110:113], v[134:137], v[186:189], v[110:113]
	v_mfma_f32_16x16x32_bf16 v[106:109], v[142:145], v[186:189], v[106:109]
	v_mfma_f32_16x16x32_bf16 v[94:97], v[134:137], v[194:197], v[94:97]
	v_mfma_f32_16x16x32_bf16 v[90:93], v[142:145], v[194:197], v[90:93]
	v_mfma_f32_16x16x32_bf16 v[78:81], v[134:137], v[202:205], v[78:81]
	v_mfma_f32_16x16x32_bf16 v[74:77], v[142:145], v[202:205], v[74:77]
	v_mfma_f32_16x16x32_bf16 v[118:121], v[206:209], v[166:169], v[118:121]
	v_mfma_f32_16x16x32_bf16 v[114:117], v[214:217], v[166:169], v[114:117]
	v_mfma_f32_16x16x32_bf16 v[102:105], v[206:209], v[182:185], v[102:105]
	v_mfma_f32_16x16x32_bf16 v[98:101], v[214:217], v[182:185], v[98:101]
	v_mfma_f32_16x16x32_bf16 v[86:89], v[206:209], v[190:193], v[86:89]
	v_mfma_f32_16x16x32_bf16 v[82:85], v[214:217], v[190:193], v[82:85]
	v_mfma_f32_16x16x32_bf16 v[70:73], v[206:209], v[198:201], v[70:73]
	v_mfma_f32_16x16x32_bf16 v[66:69], v[214:217], v[198:201], v[66:69]
	v_mfma_f32_16x16x32_bf16 v[118:121], v[210:213], v[178:181], v[118:121]
	v_mfma_f32_16x16x32_bf16 v[114:117], v[218:221], v[178:181], v[114:117]
	v_mfma_f32_16x16x32_bf16 v[102:105], v[210:213], v[186:189], v[102:105]
	v_mfma_f32_16x16x32_bf16 v[98:101], v[218:221], v[186:189], v[98:101]
	v_mfma_f32_16x16x32_bf16 v[86:89], v[210:213], v[194:197], v[86:89]
	v_mfma_f32_16x16x32_bf16 v[82:85], v[218:221], v[194:197], v[82:85]
	v_mfma_f32_16x16x32_bf16 v[70:73], v[210:213], v[202:205], v[70:73]
	v_mfma_f32_16x16x32_bf16 v[66:69], v[218:221], v[202:205], v[66:69]
	s_barrier
	s_setprio 0
	s_add_i32 s20, s54, s42
	v_lshl_add_u64 v[174:175], s[34:35], 0, v[150:151]
	s_mov_b32 m0, s20
	s_nop 0
	global_load_lds_dwordx4 v[174:175], off
	v_lshl_add_u64 v[222:223], s[34:35], 0, v[146:147]
	s_add_i32 m0, s20, 0x2000
	s_nop 0
	global_load_lds_dwordx4 v[222:223], off
	s_mov_b32 m0, s43
	v_lshl_add_u64 v[224:225], s[18:19], 0, v[152:153]
	ds_read_b128 v[166:169], v173 offset:16384
	ds_read_b128 v[178:181], v173 offset:17408
	ds_read_b128 v[182:185], v173 offset:18432
	ds_read_b128 v[186:189], v173 offset:19456
	ds_read_b128 v[190:193], v173 offset:20480
	ds_read_b128 v[194:197], v173 offset:21504
	ds_read_b128 v[198:201], v173 offset:22528
	ds_read_b128 v[202:205], v173 offset:23552
	global_load_lds_dwordx4 v[224:225], off
	v_lshl_add_u64 v[226:227], s[18:19], 0, v[148:149]
	s_mov_b32 m0, s44
	s_nop 0
	global_load_lds_dwordx4 v[226:227], off
	s_waitcnt vmcnt(6)
	s_waitcnt lgkmcnt(0)
	s_setprio 1
	s_barrier
	v_mfma_f32_16x16x32_bf16 v[62:65], v[130:133], v[166:169], v[62:65]
	v_mfma_f32_16x16x32_bf16 v[58:61], v[138:141], v[166:169], v[58:61]
	v_mfma_f32_16x16x32_bf16 v[46:49], v[130:133], v[182:185], v[46:49]
	v_mfma_f32_16x16x32_bf16 v[42:45], v[138:141], v[182:185], v[42:45]
	v_mfma_f32_16x16x32_bf16 v[30:33], v[130:133], v[190:193], v[30:33]
	v_mfma_f32_16x16x32_bf16 v[26:29], v[138:141], v[190:193], v[26:29]
	v_mfma_f32_16x16x32_bf16 v[14:17], v[130:133], v[198:201], v[14:17]
	v_mfma_f32_16x16x32_bf16 v[10:13], v[138:141], v[198:201], v[10:13]
	v_mfma_f32_16x16x32_bf16 v[62:65], v[134:137], v[178:181], v[62:65]
	v_mfma_f32_16x16x32_bf16 v[58:61], v[142:145], v[178:181], v[58:61]
	v_mfma_f32_16x16x32_bf16 v[46:49], v[134:137], v[186:189], v[46:49]
	v_mfma_f32_16x16x32_bf16 v[42:45], v[142:145], v[186:189], v[42:45]
	v_mfma_f32_16x16x32_bf16 v[30:33], v[134:137], v[194:197], v[30:33]
	v_mfma_f32_16x16x32_bf16 v[26:29], v[142:145], v[194:197], v[26:29]
	v_mfma_f32_16x16x32_bf16 v[14:17], v[134:137], v[202:205], v[14:17]
	v_mfma_f32_16x16x32_bf16 v[10:13], v[142:145], v[202:205], v[10:13]
	v_mfma_f32_16x16x32_bf16 v[54:57], v[206:209], v[166:169], v[54:57]
	v_mfma_f32_16x16x32_bf16 v[50:53], v[214:217], v[166:169], v[50:53]
	v_mfma_f32_16x16x32_bf16 v[38:41], v[206:209], v[182:185], v[38:41]
	v_mfma_f32_16x16x32_bf16 v[34:37], v[214:217], v[182:185], v[34:37]
	v_mfma_f32_16x16x32_bf16 v[22:25], v[206:209], v[190:193], v[22:25]
	v_mfma_f32_16x16x32_bf16 v[18:21], v[214:217], v[190:193], v[18:21]
	v_mfma_f32_16x16x32_bf16 v[6:9], v[206:209], v[198:201], v[6:9]
	v_mfma_f32_16x16x32_bf16 v[2:5], v[214:217], v[198:201], v[2:5]
	v_mfma_f32_16x16x32_bf16 v[54:57], v[210:213], v[178:181], v[54:57]
	v_mfma_f32_16x16x32_bf16 v[50:53], v[218:221], v[178:181], v[50:53]
	v_mfma_f32_16x16x32_bf16 v[38:41], v[210:213], v[186:189], v[38:41]
	v_mfma_f32_16x16x32_bf16 v[34:37], v[218:221], v[186:189], v[34:37]
	v_mfma_f32_16x16x32_bf16 v[22:25], v[210:213], v[194:197], v[22:25]
	v_mfma_f32_16x16x32_bf16 v[18:21], v[218:221], v[194:197], v[18:21]
	v_mfma_f32_16x16x32_bf16 v[6:9], v[210:213], v[202:205], v[6:9]
	v_mfma_f32_16x16x32_bf16 v[2:5], v[218:221], v[202:205], v[2:5]
	s_barrier
	s_setprio 0
	s_add_u32 s20, s34, 0x40000
	s_addc_u32 s21, s35, 0
	s_add_i32 s64, s55, s42
	v_lshl_add_u64 v[246:247], s[20:21], 0, v[150:151]
	s_mov_b32 m0, s64
	s_nop 0
	global_load_lds_dwordx4 v[246:247], off
	v_lshl_add_u64 v[246:247], s[20:21], 0, v[146:147]
	s_add_i32 m0, s64, 0x2000
	s_nop 0
	global_load_lds_dwordx4 v[246:247], off
	s_add_i32 s20, 0, 0x18000
	v_add_u32_e32 v142, s20, v157
	ds_read_b128 v[130:133], v142
	ds_read_b128 v[134:137], v142 offset:1024
	ds_read_b128 v[138:141], v142 offset:2048
	ds_read_b128 v[142:145], v142 offset:3072
	s_add_u32 s18, s18, 0x40000
	s_addc_u32 s19, s19, 0
	s_mov_b32 m0, s45
	v_lshl_add_u64 v[206:207], s[18:19], 0, v[152:153]
	ds_read_b128 v[166:169], v173 offset:32768
	ds_read_b128 v[178:181], v173 offset:33792
	ds_read_b128 v[182:185], v173 offset:34816
	ds_read_b128 v[186:189], v173 offset:35840
	ds_read_b128 v[190:193], v173 offset:36864
	ds_read_b128 v[194:197], v173 offset:37888
	ds_read_b128 v[198:201], v173 offset:38912
	ds_read_b128 v[202:205], v173 offset:39936
	global_load_lds_dwordx4 v[206:207], off
	v_lshl_add_u64 v[206:207], s[18:19], 0, v[148:149]
	s_mov_b32 m0, s46
	s_nop 0
	global_load_lds_dwordx4 v[206:207], off
	s_add_i32 s21, 0, 0x1c000
	v_add_u32_e32 v154, s21, v157
	ds_read_b128 v[206:209], v154
	ds_read_b128 v[210:213], v154 offset:1024
	ds_read_b128 v[214:217], v154 offset:2048
	ds_read_b128 v[218:221], v154 offset:3072
	s_waitcnt vmcnt(8)
	s_waitcnt lgkmcnt(0)
	s_setprio 1
	s_barrier
	v_mfma_f32_16x16x32_bf16 v[126:129], v[130:133], v[166:169], v[126:129]
	v_mfma_f32_16x16x32_bf16 v[122:125], v[138:141], v[166:169], v[122:125]
	v_mfma_f32_16x16x32_bf16 v[110:113], v[130:133], v[182:185], v[110:113]
	v_mfma_f32_16x16x32_bf16 v[106:109], v[138:141], v[182:185], v[106:109]
	v_mfma_f32_16x16x32_bf16 v[94:97], v[130:133], v[190:193], v[94:97]
	v_mfma_f32_16x16x32_bf16 v[90:93], v[138:141], v[190:193], v[90:93]
	v_mfma_f32_16x16x32_bf16 v[78:81], v[130:133], v[198:201], v[78:81]
	v_mfma_f32_16x16x32_bf16 v[74:77], v[138:141], v[198:201], v[74:77]
	v_mfma_f32_16x16x32_bf16 v[126:129], v[134:137], v[178:181], v[126:129]
	v_mfma_f32_16x16x32_bf16 v[122:125], v[142:145], v[178:181], v[122:125]
	v_mfma_f32_16x16x32_bf16 v[110:113], v[134:137], v[186:189], v[110:113]
	v_mfma_f32_16x16x32_bf16 v[106:109], v[142:145], v[186:189], v[106:109]
	v_mfma_f32_16x16x32_bf16 v[94:97], v[134:137], v[194:197], v[94:97]
	v_mfma_f32_16x16x32_bf16 v[90:93], v[142:145], v[194:197], v[90:93]
	v_mfma_f32_16x16x32_bf16 v[78:81], v[134:137], v[202:205], v[78:81]
	v_mfma_f32_16x16x32_bf16 v[74:77], v[142:145], v[202:205], v[74:77]
	v_mfma_f32_16x16x32_bf16 v[118:121], v[206:209], v[166:169], v[118:121]
	v_mfma_f32_16x16x32_bf16 v[114:117], v[214:217], v[166:169], v[114:117]
	v_mfma_f32_16x16x32_bf16 v[102:105], v[206:209], v[182:185], v[102:105]
	v_mfma_f32_16x16x32_bf16 v[98:101], v[214:217], v[182:185], v[98:101]
	v_mfma_f32_16x16x32_bf16 v[86:89], v[206:209], v[190:193], v[86:89]
	v_mfma_f32_16x16x32_bf16 v[82:85], v[214:217], v[190:193], v[82:85]
	v_mfma_f32_16x16x32_bf16 v[70:73], v[206:209], v[198:201], v[70:73]
	v_mfma_f32_16x16x32_bf16 v[66:69], v[214:217], v[198:201], v[66:69]
	v_mfma_f32_16x16x32_bf16 v[118:121], v[210:213], v[178:181], v[118:121]
	v_mfma_f32_16x16x32_bf16 v[114:117], v[218:221], v[178:181], v[114:117]
	v_mfma_f32_16x16x32_bf16 v[102:105], v[210:213], v[186:189], v[102:105]
	v_mfma_f32_16x16x32_bf16 v[98:101], v[218:221], v[186:189], v[98:101]
	v_mfma_f32_16x16x32_bf16 v[86:89], v[210:213], v[194:197], v[86:89]
	v_mfma_f32_16x16x32_bf16 v[82:85], v[218:221], v[194:197], v[82:85]
	v_mfma_f32_16x16x32_bf16 v[70:73], v[210:213], v[202:205], v[70:73]
	v_mfma_f32_16x16x32_bf16 v[66:69], v[218:221], v[202:205], v[66:69]
	s_barrier
	s_setprio 0
	s_add_i32 s18, s20, s42
	v_lshl_add_u64 v[174:175], v[174:175], 0, s[6:7]
	s_mov_b32 m0, s18
	s_nop 0
	global_load_lds_dwordx4 v[174:175], off
	v_lshl_add_u64 v[174:175], v[222:223], 0, s[6:7]
	s_add_i32 m0, s18, 0x2000
	s_nop 0
	global_load_lds_dwordx4 v[174:175], off
	s_mov_b32 m0, s50
	v_lshl_add_u64 v[174:175], v[224:225], 0, s[6:7]
	ds_read_b128 v[166:169], v173 offset:49152
	ds_read_b128 v[178:181], v173 offset:50176
	ds_read_b128 v[182:185], v173 offset:51200
	ds_read_b128 v[186:189], v173 offset:52224
	ds_read_b128 v[190:193], v173 offset:53248
	ds_read_b128 v[194:197], v173 offset:54272
	ds_read_b128 v[198:201], v173 offset:55296
	ds_read_b128 v[202:205], v173 offset:56320
	global_load_lds_dwordx4 v[174:175], off
	v_lshl_add_u64 v[174:175], v[226:227], 0, s[6:7]
	s_mov_b32 m0, s51
	s_nop 0
	global_load_lds_dwordx4 v[174:175], off
	s_add_u32 s18, s34, 0x40080
	s_addc_u32 s19, s35, 0
	s_add_i32 s20, s21, s42
	v_lshl_add_u64 v[248:249], s[18:19], 0, v[150:151]
	s_mov_b32 m0, s20
	s_nop 0
	global_load_lds_dwordx4 v[248:249], off
	v_lshl_add_u64 v[248:249], s[18:19], 0, v[146:147]
	s_add_i32 m0, s20, 0x2000
	s_nop 0
	global_load_lds_dwordx4 v[248:249], off
	s_waitcnt vmcnt(6)
	s_waitcnt lgkmcnt(0)
	s_setprio 1
	s_barrier
	v_mfma_f32_16x16x32_bf16 v[62:65], v[130:133], v[166:169], v[62:65]
	v_mfma_f32_16x16x32_bf16 v[58:61], v[138:141], v[166:169], v[58:61]
	v_mfma_f32_16x16x32_bf16 v[46:49], v[130:133], v[182:185], v[46:49]
	v_mfma_f32_16x16x32_bf16 v[42:45], v[138:141], v[182:185], v[42:45]
	v_mfma_f32_16x16x32_bf16 v[30:33], v[130:133], v[190:193], v[30:33]
	v_mfma_f32_16x16x32_bf16 v[26:29], v[138:141], v[190:193], v[26:29]
	v_mfma_f32_16x16x32_bf16 v[14:17], v[130:133], v[198:201], v[14:17]
	v_mfma_f32_16x16x32_bf16 v[10:13], v[138:141], v[198:201], v[10:13]
	v_mfma_f32_16x16x32_bf16 v[62:65], v[134:137], v[178:181], v[62:65]
	v_mfma_f32_16x16x32_bf16 v[58:61], v[142:145], v[178:181], v[58:61]
	v_mfma_f32_16x16x32_bf16 v[46:49], v[134:137], v[186:189], v[46:49]
	v_mfma_f32_16x16x32_bf16 v[42:45], v[142:145], v[186:189], v[42:45]
	v_mfma_f32_16x16x32_bf16 v[30:33], v[134:137], v[194:197], v[30:33]
	v_mfma_f32_16x16x32_bf16 v[26:29], v[142:145], v[194:197], v[26:29]
	v_mfma_f32_16x16x32_bf16 v[14:17], v[134:137], v[202:205], v[14:17]
	v_mfma_f32_16x16x32_bf16 v[10:13], v[142:145], v[202:205], v[10:13]
	v_mfma_f32_16x16x32_bf16 v[54:57], v[206:209], v[166:169], v[54:57]
	v_mfma_f32_16x16x32_bf16 v[50:53], v[214:217], v[166:169], v[50:53]
	v_mfma_f32_16x16x32_bf16 v[38:41], v[206:209], v[182:185], v[38:41]
	v_mfma_f32_16x16x32_bf16 v[34:37], v[214:217], v[182:185], v[34:37]
	v_mfma_f32_16x16x32_bf16 v[22:25], v[206:209], v[190:193], v[22:25]
	v_mfma_f32_16x16x32_bf16 v[18:21], v[214:217], v[190:193], v[18:21]
	v_mfma_f32_16x16x32_bf16 v[6:9], v[206:209], v[198:201], v[6:9]
	v_mfma_f32_16x16x32_bf16 v[2:5], v[214:217], v[198:201], v[2:5]
	v_mfma_f32_16x16x32_bf16 v[54:57], v[210:213], v[178:181], v[54:57]
	v_mfma_f32_16x16x32_bf16 v[50:53], v[218:221], v[178:181], v[50:53]
	v_mfma_f32_16x16x32_bf16 v[38:41], v[210:213], v[186:189], v[38:41]
	v_mfma_f32_16x16x32_bf16 v[34:37], v[218:221], v[186:189], v[34:37]
	v_mfma_f32_16x16x32_bf16 v[22:25], v[210:213], v[194:197], v[22:25]
	v_mfma_f32_16x16x32_bf16 v[18:21], v[218:221], v[194:197], v[18:21]
	v_mfma_f32_16x16x32_bf16 v[6:9], v[210:213], v[202:205], v[6:9]
	v_mfma_f32_16x16x32_bf16 v[2:5], v[218:221], v[202:205], v[2:5]
	s_barrier
	s_setprio 0
	s_add_i32 s63, s63, 2
	s_add_u32 s24, s24, 0x100
	s_addc_u32 s25, s25, 0
	s_add_u32 s61, s61, 0x100
	s_addc_u32 s62, s62, 0
	s_cmp_gt_u32 s63, 13
	s_cbranch_scc0 .LBB0_3265
	s_ashr_i32 s9, s16, 3
	s_mul_hi_i32 s11, s9, 0x5800
	s_mulk_i32 s9, 0x5800
	s_add_u32 s9, s48, s9
	s_addc_u32 s11, s49, s11
	s_lshl_b32 s18, s17, 8
	s_ashr_i32 s19, s18, 31
	s_lshl_b64 s[18:19], s[18:19], 2
	v_lshl_add_u32 v180, s16, 8, v1
	s_add_u32 s18, s9, s18
	s_addc_u32 s19, s11, s19
	v_lshlrev_b32_e32 v130, 2, v156
	v_ashrrev_i32_e32 v181, 31, v180
	global_load_dwordx4 v[142:145], v130, s[18:19]
	v_lshl_add_u64 v[182:183], v[180:181], 2, s[4:5]
	global_load_dword v190, v[182:183], off
	global_load_dwordx4 v[138:141], v130, s[18:19] offset:512
	global_load_dwordx4 v[134:137], v130, s[18:19] offset:16
	s_nop 0
	global_load_dwordx4 v[130:133], v130, s[18:19] offset:528
	v_or_b32_e32 v192, 16, v180
	v_ashrrev_i32_e32 v193, 31, v192
	v_lshl_add_u64 v[168:169], v[192:193], 2, s[4:5]
	global_load_dword v194, v[168:169], off
	v_or_b32_e32 v188, 32, v180
	v_or_b32_e32 v184, 48, v180
	v_mov_b64_e32 v[166:167], s[0:1]
	v_add_u32_e32 v178, 0x90, v180
	v_add_u32_e32 v174, 0xa0, v180
	v_add_u32_e32 v168, 0xb0, v180
	v_ashrrev_i32_e32 v189, 31, v188
	v_ashrrev_i32_e32 v185, 31, v184
	v_add_u32_e32 v193, 0x80, v180
	v_mad_i64_i32 v[196:197], s[18:19], v180, s56, v[166:167]
	v_ashrrev_i32_e32 v179, 31, v178
	v_ashrrev_i32_e32 v175, 31, v174
	v_ashrrev_i32_e32 v169, 31, v168
	v_lshl_add_u64 v[180:181], v[188:189], 2, s[4:5]
	v_lshl_add_u64 v[186:187], v[184:185], 2, s[4:5]
	v_lshl_add_u64 v[198:199], v[178:179], 2, s[4:5]
	v_lshl_add_u64 v[200:201], v[174:175], 2, s[4:5]
	v_lshl_add_u64 v[202:203], v[168:169], 2, s[4:5]
	global_load_dword v204, v[180:181], off
	s_nop 0
	global_load_dword v186, v[186:187], off
	s_nop 0
	global_load_dword v180, v[198:199], off
	global_load_dword v176, v[200:201], off
	global_load_dword v172, v[202:203], off
	s_nop 0
	global_load_dword v182, v[182:183], off offset:512
	s_lshl_b32 s16, s17, 7
	s_ashr_i32 s17, s16, 31
	s_lshl_b64 s[16:17], s[16:17], 1
	v_lshlrev_b32_e32 v154, 1, v156
	v_lshl_add_u64 v[196:197], v[196:197], 0, s[16:17]
	s_and_b64 vcc, exec, s[2:3]
	s_mov_b64 s[34:35], s[14:15]
	s_mov_b64 s[24:25], s[12:13]
	s_waitcnt vmcnt(0)
	v_pk_fma_f32 v[118:119], v[118:119], v[190:191], v[138:139] op_sel_hi:[1,0,1]
	v_pk_fma_f32 v[126:127], v[126:127], v[190:191], v[142:143] op_sel_hi:[1,0,1]
	v_pk_fma_f32 v[128:129], v[128:129], v[190:191], v[144:145] op_sel_hi:[1,0,1]
	v_pk_fma_f32 v[122:123], v[122:123], v[190:191], v[134:135] op_sel_hi:[1,0,1]
	v_pk_fma_f32 v[124:125], v[124:125], v[190:191], v[136:137] op_sel_hi:[1,0,1]
	v_mul_f32_e32 v169, 0xbfb8aa3b, v126
	v_mul_f32_e32 v175, 0xbfb8aa3b, v127
	v_mul_f32_e32 v179, 0xbfb8aa3b, v128
	v_mul_f32_e32 v181, 0xbfb8aa3b, v129
	v_mul_f32_e32 v183, 0xbfb8aa3b, v122
	v_mul_f32_e32 v185, 0xbfb8aa3b, v123
	v_mul_f32_e32 v187, 0xbfb8aa3b, v124
	v_mul_f32_e32 v189, 0xbfb8aa3b, v125
	v_exp_f32_e32 v169, v169
	v_exp_f32_e32 v175, v175
	v_exp_f32_e32 v179, v179
	v_exp_f32_e32 v181, v181
	v_exp_f32_e32 v183, v183
	v_exp_f32_e32 v185, v185
	v_exp_f32_e32 v187, v187
	v_exp_f32_e32 v189, v189
	v_add_f32_e32 v169, 1.0, v169
	v_add_f32_e32 v175, 1.0, v175
	v_add_f32_e32 v179, 1.0, v179
	v_add_f32_e32 v181, 1.0, v181
	v_add_f32_e32 v183, 1.0, v183
	v_add_f32_e32 v185, 1.0, v185
	v_add_f32_e32 v187, 1.0, v187
	v_add_f32_e32 v189, 1.0, v189
	v_pk_fma_f32 v[120:121], v[120:121], v[190:191], v[140:141] op_sel_hi:[1,0,1]
	v_pk_fma_f32 v[114:115], v[114:115], v[190:191], v[130:131] op_sel_hi:[1,0,1]
	v_pk_fma_f32 v[116:117], v[116:117], v[190:191], v[132:133] op_sel_hi:[1,0,1]
	v_rcp_f32_e32 v190, v169
	v_rcp_f32_e32 v191, v175
	v_rcp_f32_e32 v198, v179
	v_rcp_f32_e32 v199, v181
	v_rcp_f32_e32 v200, v183
	v_rcp_f32_e32 v201, v185
	v_rcp_f32_e32 v202, v187
	v_rcp_f32_e32 v203, v189
	v_pk_mul_f32 v[126:127], v[126:127], v[190:191]
	v_pk_mul_f32 v[128:129], v[128:129], v[198:199]
	v_pk_mul_f32 v[122:123], v[122:123], v[200:201]
	v_pk_mul_f32 v[124:125], v[124:125], v[202:203]
	v_pk_mul_f32 v[118:119], v[118:119], v[126:127]
	v_pk_mul_f32 v[120:121], v[120:121], v[128:129]
	v_pk_mul_f32 v[122:123], v[114:115], v[122:123]
	v_pk_mul_f32 v[124:125], v[116:117], v[124:125]
	v_pk_fma_f32 v[110:111], v[110:111], v[194:195], v[142:143] op_sel_hi:[1,0,1]
	v_lshl_add_u64 v[126:127], v[196:197], 0, v[154:155]
	v_cvt_pk_bf16_f32 v114, v118, v119
	v_cvt_pk_bf16_f32 v115, v120, v121
	v_cvt_pk_bf16_f32 v116, v122, v123
	v_cvt_pk_bf16_f32 v117, v124, v125
	v_mul_f32_e32 v118, 0xbfb8aa3b, v110
	v_mul_f32_e32 v119, 0xbfb8aa3b, v111
	v_pk_fma_f32 v[112:113], v[112:113], v[194:195], v[144:145] op_sel_hi:[1,0,1]
	v_exp_f32_e32 v118, v118
	v_exp_f32_e32 v119, v119
	global_store_dwordx4 v[126:127], v[114:117], off nt
	v_pk_fma_f32 v[102:103], v[102:103], v[194:195], v[138:139] op_sel_hi:[1,0,1]
	v_pk_fma_f32 v[106:107], v[106:107], v[194:195], v[134:135] op_sel_hi:[1,0,1]
	v_mul_f32_e32 v116, 0xbfb8aa3b, v112
	v_mul_f32_e32 v117, 0xbfb8aa3b, v113
	v_exp_f32_e32 v116, v116
	v_exp_f32_e32 v117, v117
	v_add_f32_e32 v114, 1.0, v118
	v_add_f32_e32 v115, 1.0, v119
	v_rcp_f32_e32 v114, v114
	v_rcp_f32_e32 v115, v115
	v_add_f32_e32 v116, 1.0, v116
	v_add_f32_e32 v117, 1.0, v117
	v_rcp_f32_e32 v116, v116
	v_rcp_f32_e32 v117, v117
	v_pk_mul_f32 v[110:111], v[110:111], v[114:115]
	v_pk_fma_f32 v[104:105], v[104:105], v[194:195], v[140:141] op_sel_hi:[1,0,1]
	v_pk_mul_f32 v[102:103], v[102:103], v[110:111]
	v_pk_mul_f32 v[110:111], v[112:113], v[116:117]
	v_mul_f32_e32 v112, 0xbfb8aa3b, v106
	v_mul_f32_e32 v113, 0xbfb8aa3b, v107
	v_exp_f32_e32 v112, v112
	v_exp_f32_e32 v113, v113
	v_pk_fma_f32 v[108:109], v[108:109], v[194:195], v[136:137] op_sel_hi:[1,0,1]
	v_pk_mul_f32 v[104:105], v[104:105], v[110:111]
	v_add_f32_e32 v110, 1.0, v112
	v_add_f32_e32 v111, 1.0, v113
	v_mul_f32_e32 v112, 0xbfb8aa3b, v108
	v_mul_f32_e32 v113, 0xbfb8aa3b, v109
	v_exp_f32_e32 v112, v112
	v_exp_f32_e32 v113, v113
	v_rcp_f32_e32 v110, v110
	v_rcp_f32_e32 v111, v111
	v_add_f32_e32 v112, 1.0, v112
	v_add_f32_e32 v113, 1.0, v113
	v_rcp_f32_e32 v112, v112
	v_rcp_f32_e32 v113, v113
	v_pk_mul_f32 v[106:107], v[106:107], v[110:111]
	v_pk_fma_f32 v[98:99], v[98:99], v[194:195], v[130:131] op_sel_hi:[1,0,1]
	v_pk_fma_f32 v[100:101], v[100:101], v[194:195], v[132:133] op_sel_hi:[1,0,1]
	v_pk_mul_f32 v[106:107], v[98:99], v[106:107]
	v_pk_mul_f32 v[98:99], v[108:109], v[112:113]
	v_pk_fma_f32 v[94:95], v[94:95], v[204:205], v[142:143] op_sel_hi:[1,0,1]
	v_pk_mul_f32 v[108:109], v[100:101], v[98:99]
	v_mad_i64_i32 v[98:99], s[18:19], v192, s56, v[166:167]
	v_lshl_add_u64 v[98:99], v[98:99], 0, s[16:17]
	v_lshl_add_u64 v[110:111], v[98:99], 0, v[154:155]
	v_cvt_pk_bf16_f32 v98, v102, v103
	v_cvt_pk_bf16_f32 v99, v104, v105
	v_cvt_pk_bf16_f32 v100, v106, v107
	v_cvt_pk_bf16_f32 v101, v108, v109
	v_mul_f32_e32 v102, 0xbfb8aa3b, v94
	v_mul_f32_e32 v103, 0xbfb8aa3b, v95
	v_pk_fma_f32 v[96:97], v[96:97], v[204:205], v[144:145] op_sel_hi:[1,0,1]
	v_exp_f32_e32 v102, v102
	v_exp_f32_e32 v103, v103
	global_store_dwordx4 v[110:111], v[98:101], off nt
	v_pk_fma_f32 v[86:87], v[86:87], v[204:205], v[138:139] op_sel_hi:[1,0,1]
	v_pk_fma_f32 v[90:91], v[90:91], v[204:205], v[134:135] op_sel_hi:[1,0,1]
	v_mul_f32_e32 v100, 0xbfb8aa3b, v96
	v_mul_f32_e32 v101, 0xbfb8aa3b, v97
	v_exp_f32_e32 v100, v100
	v_exp_f32_e32 v101, v101
	v_add_f32_e32 v98, 1.0, v102
	v_add_f32_e32 v99, 1.0, v103
	v_rcp_f32_e32 v98, v98
	v_rcp_f32_e32 v99, v99
	v_add_f32_e32 v100, 1.0, v100
	v_add_f32_e32 v101, 1.0, v101
	v_rcp_f32_e32 v100, v100
	v_rcp_f32_e32 v101, v101
	v_pk_mul_f32 v[94:95], v[94:95], v[98:99]
	v_pk_fma_f32 v[88:89], v[88:89], v[204:205], v[140:141] op_sel_hi:[1,0,1]
	v_pk_mul_f32 v[86:87], v[86:87], v[94:95]
	v_pk_mul_f32 v[94:95], v[96:97], v[100:101]
	v_mul_f32_e32 v96, 0xbfb8aa3b, v90
	v_mul_f32_e32 v97, 0xbfb8aa3b, v91
	v_exp_f32_e32 v96, v96
	v_exp_f32_e32 v97, v97
	v_pk_fma_f32 v[92:93], v[92:93], v[204:205], v[136:137] op_sel_hi:[1,0,1]
	v_pk_mul_f32 v[88:89], v[88:89], v[94:95]
	v_add_f32_e32 v94, 1.0, v96
	v_add_f32_e32 v95, 1.0, v97
	v_mul_f32_e32 v96, 0xbfb8aa3b, v92
	v_mul_f32_e32 v97, 0xbfb8aa3b, v93
	v_exp_f32_e32 v96, v96
	v_exp_f32_e32 v97, v97
	v_rcp_f32_e32 v94, v94
	v_rcp_f32_e32 v95, v95
	v_add_f32_e32 v96, 1.0, v96
	v_add_f32_e32 v97, 1.0, v97
	v_rcp_f32_e32 v96, v96
	v_rcp_f32_e32 v97, v97
	v_pk_mul_f32 v[90:91], v[90:91], v[94:95]
	v_pk_fma_f32 v[82:83], v[82:83], v[204:205], v[130:131] op_sel_hi:[1,0,1]
	v_pk_fma_f32 v[84:85], v[84:85], v[204:205], v[132:133] op_sel_hi:[1,0,1]
	v_pk_mul_f32 v[90:91], v[82:83], v[90:91]
	v_pk_mul_f32 v[82:83], v[92:93], v[96:97]
	v_pk_fma_f32 v[78:79], v[78:79], v[186:187], v[142:143] op_sel_hi:[1,0,1]
	v_pk_mul_f32 v[92:93], v[84:85], v[82:83]
	v_mad_i64_i32 v[82:83], s[18:19], v188, s56, v[166:167]
	v_lshl_add_u64 v[82:83], v[82:83], 0, s[16:17]
	v_lshl_add_u64 v[94:95], v[82:83], 0, v[154:155]
	v_cvt_pk_bf16_f32 v82, v86, v87
	v_cvt_pk_bf16_f32 v83, v88, v89
	v_cvt_pk_bf16_f32 v84, v90, v91
	v_cvt_pk_bf16_f32 v85, v92, v93
	v_mul_f32_e32 v86, 0xbfb8aa3b, v78
	v_mul_f32_e32 v87, 0xbfb8aa3b, v79
	v_pk_fma_f32 v[80:81], v[80:81], v[186:187], v[144:145] op_sel_hi:[1,0,1]
	v_exp_f32_e32 v86, v86
	v_exp_f32_e32 v87, v87
	global_store_dwordx4 v[94:95], v[82:85], off nt
	v_pk_fma_f32 v[70:71], v[70:71], v[186:187], v[138:139] op_sel_hi:[1,0,1]
	v_pk_fma_f32 v[74:75], v[74:75], v[186:187], v[134:135] op_sel_hi:[1,0,1]
	v_mul_f32_e32 v84, 0xbfb8aa3b, v80
	v_mul_f32_e32 v85, 0xbfb8aa3b, v81
	v_exp_f32_e32 v84, v84
	v_exp_f32_e32 v85, v85
	v_add_f32_e32 v82, 1.0, v86
	v_add_f32_e32 v83, 1.0, v87
	v_rcp_f32_e32 v82, v82
	v_rcp_f32_e32 v83, v83
	v_add_f32_e32 v84, 1.0, v84
	v_add_f32_e32 v85, 1.0, v85
	v_rcp_f32_e32 v84, v84
	v_rcp_f32_e32 v85, v85
	v_pk_mul_f32 v[78:79], v[78:79], v[82:83]
	v_pk_fma_f32 v[72:73], v[72:73], v[186:187], v[140:141] op_sel_hi:[1,0,1]
	v_pk_mul_f32 v[70:71], v[70:71], v[78:79]
	v_pk_mul_f32 v[78:79], v[80:81], v[84:85]
	v_mul_f32_e32 v80, 0xbfb8aa3b, v74
	v_mul_f32_e32 v81, 0xbfb8aa3b, v75
	v_exp_f32_e32 v80, v80
	v_exp_f32_e32 v81, v81
	v_pk_fma_f32 v[76:77], v[76:77], v[186:187], v[136:137] op_sel_hi:[1,0,1]
	v_pk_mul_f32 v[72:73], v[72:73], v[78:79]
	v_add_f32_e32 v78, 1.0, v80
	v_add_f32_e32 v79, 1.0, v81
	v_mul_f32_e32 v80, 0xbfb8aa3b, v76
	v_mul_f32_e32 v81, 0xbfb8aa3b, v77
	v_exp_f32_e32 v80, v80
	v_exp_f32_e32 v81, v81
	v_rcp_f32_e32 v78, v78
	v_rcp_f32_e32 v79, v79
	v_add_f32_e32 v80, 1.0, v80
	v_add_f32_e32 v81, 1.0, v81
	v_rcp_f32_e32 v80, v80
	v_rcp_f32_e32 v81, v81
	v_pk_mul_f32 v[74:75], v[74:75], v[78:79]
	v_pk_fma_f32 v[66:67], v[66:67], v[186:187], v[130:131] op_sel_hi:[1,0,1]
	v_pk_fma_f32 v[68:69], v[68:69], v[186:187], v[132:133] op_sel_hi:[1,0,1]
	v_pk_mul_f32 v[74:75], v[66:67], v[74:75]
	v_pk_mul_f32 v[66:67], v[76:77], v[80:81]
	v_pk_fma_f32 v[62:63], v[62:63], v[182:183], v[142:143] op_sel_hi:[1,0,1]
	v_pk_mul_f32 v[76:77], v[68:69], v[66:67]
	v_mad_i64_i32 v[66:67], s[18:19], v184, s56, v[166:167]
	v_lshl_add_u64 v[66:67], v[66:67], 0, s[16:17]
	v_lshl_add_u64 v[78:79], v[66:67], 0, v[154:155]
	v_cvt_pk_bf16_f32 v66, v70, v71
	v_cvt_pk_bf16_f32 v67, v72, v73
	v_cvt_pk_bf16_f32 v68, v74, v75
	v_cvt_pk_bf16_f32 v69, v76, v77
	v_mul_f32_e32 v70, 0xbfb8aa3b, v62
	v_mul_f32_e32 v71, 0xbfb8aa3b, v63
	v_pk_fma_f32 v[64:65], v[64:65], v[182:183], v[144:145] op_sel_hi:[1,0,1]
	v_exp_f32_e32 v70, v70
	v_exp_f32_e32 v71, v71
	global_store_dwordx4 v[78:79], v[66:69], off nt
	v_pk_fma_f32 v[54:55], v[54:55], v[182:183], v[138:139] op_sel_hi:[1,0,1]
	v_pk_fma_f32 v[58:59], v[58:59], v[182:183], v[134:135] op_sel_hi:[1,0,1]
	v_mul_f32_e32 v68, 0xbfb8aa3b, v64
	v_mul_f32_e32 v69, 0xbfb8aa3b, v65
	v_exp_f32_e32 v68, v68
	v_exp_f32_e32 v69, v69
	v_add_f32_e32 v66, 1.0, v70
	v_add_f32_e32 v67, 1.0, v71
	v_rcp_f32_e32 v66, v66
	v_rcp_f32_e32 v67, v67
	v_add_f32_e32 v68, 1.0, v68
	v_add_f32_e32 v69, 1.0, v69
	v_rcp_f32_e32 v68, v68
	v_rcp_f32_e32 v69, v69
	v_pk_mul_f32 v[62:63], v[62:63], v[66:67]
	v_pk_fma_f32 v[56:57], v[56:57], v[182:183], v[140:141] op_sel_hi:[1,0,1]
	v_pk_mul_f32 v[54:55], v[54:55], v[62:63]
	v_pk_mul_f32 v[62:63], v[64:65], v[68:69]
	v_mul_f32_e32 v64, 0xbfb8aa3b, v58
	v_mul_f32_e32 v65, 0xbfb8aa3b, v59
	v_exp_f32_e32 v64, v64
	v_exp_f32_e32 v65, v65
	v_pk_fma_f32 v[60:61], v[60:61], v[182:183], v[136:137] op_sel_hi:[1,0,1]
	v_pk_mul_f32 v[56:57], v[56:57], v[62:63]
	v_add_f32_e32 v62, 1.0, v64
	v_add_f32_e32 v63, 1.0, v65
	v_mul_f32_e32 v64, 0xbfb8aa3b, v60
	v_mul_f32_e32 v65, 0xbfb8aa3b, v61
	v_exp_f32_e32 v64, v64
	v_exp_f32_e32 v65, v65
	v_rcp_f32_e32 v62, v62
	v_rcp_f32_e32 v63, v63
	v_add_f32_e32 v64, 1.0, v64
	v_add_f32_e32 v65, 1.0, v65
	v_rcp_f32_e32 v64, v64
	v_rcp_f32_e32 v65, v65
	v_pk_mul_f32 v[58:59], v[58:59], v[62:63]
	v_pk_fma_f32 v[50:51], v[50:51], v[182:183], v[130:131] op_sel_hi:[1,0,1]
	v_pk_fma_f32 v[52:53], v[52:53], v[182:183], v[132:133] op_sel_hi:[1,0,1]
	v_pk_mul_f32 v[58:59], v[50:51], v[58:59]
	v_pk_mul_f32 v[50:51], v[60:61], v[64:65]
	v_pk_fma_f32 v[46:47], v[46:47], v[180:181], v[142:143] op_sel_hi:[1,0,1]
	v_pk_mul_f32 v[60:61], v[52:53], v[50:51]
	v_mad_i64_i32 v[50:51], s[18:19], v193, s56, v[166:167]
	v_lshl_add_u64 v[50:51], v[50:51], 0, s[16:17]
	v_lshl_add_u64 v[62:63], v[50:51], 0, v[154:155]
	v_cvt_pk_bf16_f32 v50, v54, v55
	v_cvt_pk_bf16_f32 v51, v56, v57
	v_cvt_pk_bf16_f32 v52, v58, v59
	v_cvt_pk_bf16_f32 v53, v60, v61
	v_mul_f32_e32 v54, 0xbfb8aa3b, v46
	v_mul_f32_e32 v55, 0xbfb8aa3b, v47
	v_pk_fma_f32 v[48:49], v[48:49], v[180:181], v[144:145] op_sel_hi:[1,0,1]
	v_exp_f32_e32 v54, v54
	v_exp_f32_e32 v55, v55
	global_store_dwordx4 v[62:63], v[50:53], off nt
	v_pk_fma_f32 v[38:39], v[38:39], v[180:181], v[138:139] op_sel_hi:[1,0,1]
	v_pk_fma_f32 v[42:43], v[42:43], v[180:181], v[134:135] op_sel_hi:[1,0,1]
	v_mul_f32_e32 v52, 0xbfb8aa3b, v48
	v_mul_f32_e32 v53, 0xbfb8aa3b, v49
	v_exp_f32_e32 v52, v52
	v_exp_f32_e32 v53, v53
	v_add_f32_e32 v50, 1.0, v54
	v_add_f32_e32 v51, 1.0, v55
	v_rcp_f32_e32 v50, v50
	v_rcp_f32_e32 v51, v51
	v_add_f32_e32 v52, 1.0, v52
	v_add_f32_e32 v53, 1.0, v53
	v_rcp_f32_e32 v52, v52
	v_rcp_f32_e32 v53, v53
	v_pk_mul_f32 v[46:47], v[46:47], v[50:51]
	v_pk_fma_f32 v[40:41], v[40:41], v[180:181], v[140:141] op_sel_hi:[1,0,1]
	v_pk_mul_f32 v[38:39], v[38:39], v[46:47]
	v_pk_mul_f32 v[46:47], v[48:49], v[52:53]
	v_mul_f32_e32 v48, 0xbfb8aa3b, v42
	v_mul_f32_e32 v49, 0xbfb8aa3b, v43
	v_exp_f32_e32 v48, v48
	v_exp_f32_e32 v49, v49
	v_pk_fma_f32 v[44:45], v[44:45], v[180:181], v[136:137] op_sel_hi:[1,0,1]
	v_pk_mul_f32 v[40:41], v[40:41], v[46:47]
	v_add_f32_e32 v46, 1.0, v48
	v_add_f32_e32 v47, 1.0, v49
	v_mul_f32_e32 v48, 0xbfb8aa3b, v44
	v_mul_f32_e32 v49, 0xbfb8aa3b, v45
	v_exp_f32_e32 v48, v48
	v_exp_f32_e32 v49, v49
	v_rcp_f32_e32 v46, v46
	v_rcp_f32_e32 v47, v47
	v_add_f32_e32 v48, 1.0, v48
	v_add_f32_e32 v49, 1.0, v49
	v_rcp_f32_e32 v48, v48
	v_rcp_f32_e32 v49, v49
	v_pk_mul_f32 v[42:43], v[42:43], v[46:47]
	v_pk_fma_f32 v[34:35], v[34:35], v[180:181], v[130:131] op_sel_hi:[1,0,1]
	v_pk_fma_f32 v[36:37], v[36:37], v[180:181], v[132:133] op_sel_hi:[1,0,1]
	v_pk_mul_f32 v[42:43], v[34:35], v[42:43]
	v_pk_mul_f32 v[34:35], v[44:45], v[48:49]
	v_pk_fma_f32 v[30:31], v[30:31], v[176:177], v[142:143] op_sel_hi:[1,0,1]
	v_pk_mul_f32 v[44:45], v[36:37], v[34:35]
	v_mad_i64_i32 v[34:35], s[18:19], v178, s56, v[166:167]
	v_lshl_add_u64 v[34:35], v[34:35], 0, s[16:17]
	v_lshl_add_u64 v[46:47], v[34:35], 0, v[154:155]
	v_cvt_pk_bf16_f32 v34, v38, v39
	v_cvt_pk_bf16_f32 v35, v40, v41
	v_cvt_pk_bf16_f32 v36, v42, v43
	v_cvt_pk_bf16_f32 v37, v44, v45
	v_mul_f32_e32 v38, 0xbfb8aa3b, v30
	v_mul_f32_e32 v39, 0xbfb8aa3b, v31
	v_pk_fma_f32 v[32:33], v[32:33], v[176:177], v[144:145] op_sel_hi:[1,0,1]
	v_exp_f32_e32 v38, v38
	v_exp_f32_e32 v39, v39
	global_store_dwordx4 v[46:47], v[34:37], off nt
	v_pk_fma_f32 v[22:23], v[22:23], v[176:177], v[138:139] op_sel_hi:[1,0,1]
	v_pk_fma_f32 v[26:27], v[26:27], v[176:177], v[134:135] op_sel_hi:[1,0,1]
	v_mul_f32_e32 v36, 0xbfb8aa3b, v32
	v_mul_f32_e32 v37, 0xbfb8aa3b, v33
	v_exp_f32_e32 v36, v36
	v_exp_f32_e32 v37, v37
	v_add_f32_e32 v34, 1.0, v38
	v_add_f32_e32 v35, 1.0, v39
	v_rcp_f32_e32 v34, v34
	v_rcp_f32_e32 v35, v35
	v_add_f32_e32 v36, 1.0, v36
	v_add_f32_e32 v37, 1.0, v37
	v_rcp_f32_e32 v36, v36
	v_rcp_f32_e32 v37, v37
	v_pk_mul_f32 v[30:31], v[30:31], v[34:35]
	v_pk_fma_f32 v[24:25], v[24:25], v[176:177], v[140:141] op_sel_hi:[1,0,1]
	v_pk_mul_f32 v[22:23], v[22:23], v[30:31]
	v_pk_mul_f32 v[30:31], v[32:33], v[36:37]
	v_mul_f32_e32 v32, 0xbfb8aa3b, v26
	v_mul_f32_e32 v33, 0xbfb8aa3b, v27
	v_exp_f32_e32 v32, v32
	v_exp_f32_e32 v33, v33
	v_pk_fma_f32 v[28:29], v[28:29], v[176:177], v[136:137] op_sel_hi:[1,0,1]
	v_pk_mul_f32 v[24:25], v[24:25], v[30:31]
	v_add_f32_e32 v30, 1.0, v32
	v_add_f32_e32 v31, 1.0, v33
	v_mul_f32_e32 v32, 0xbfb8aa3b, v28
	v_mul_f32_e32 v33, 0xbfb8aa3b, v29
	v_exp_f32_e32 v32, v32
	v_exp_f32_e32 v33, v33
	v_rcp_f32_e32 v30, v30
	v_rcp_f32_e32 v31, v31
	v_add_f32_e32 v32, 1.0, v32
	v_add_f32_e32 v33, 1.0, v33
	v_rcp_f32_e32 v32, v32
	v_rcp_f32_e32 v33, v33
	v_pk_mul_f32 v[26:27], v[26:27], v[30:31]
	v_pk_fma_f32 v[18:19], v[18:19], v[176:177], v[130:131] op_sel_hi:[1,0,1]
	v_pk_fma_f32 v[20:21], v[20:21], v[176:177], v[132:133] op_sel_hi:[1,0,1]
	v_pk_mul_f32 v[26:27], v[18:19], v[26:27]
	v_pk_mul_f32 v[18:19], v[28:29], v[32:33]
	v_pk_fma_f32 v[14:15], v[14:15], v[172:173], v[142:143] op_sel_hi:[1,0,1]
	v_pk_mul_f32 v[28:29], v[20:21], v[18:19]
	v_mad_i64_i32 v[18:19], s[18:19], v174, s56, v[166:167]
	v_lshl_add_u64 v[18:19], v[18:19], 0, s[16:17]
	v_lshl_add_u64 v[30:31], v[18:19], 0, v[154:155]
	v_cvt_pk_bf16_f32 v18, v22, v23
	v_cvt_pk_bf16_f32 v19, v24, v25
	v_cvt_pk_bf16_f32 v20, v26, v27
	v_cvt_pk_bf16_f32 v21, v28, v29
	v_mul_f32_e32 v22, 0xbfb8aa3b, v14
	v_mul_f32_e32 v23, 0xbfb8aa3b, v15
	v_pk_fma_f32 v[16:17], v[16:17], v[172:173], v[144:145] op_sel_hi:[1,0,1]
	v_exp_f32_e32 v22, v22
	v_exp_f32_e32 v23, v23
	global_store_dwordx4 v[30:31], v[18:21], off nt
	v_pk_fma_f32 v[6:7], v[6:7], v[172:173], v[138:139] op_sel_hi:[1,0,1]
	v_pk_fma_f32 v[10:11], v[10:11], v[172:173], v[134:135] op_sel_hi:[1,0,1]
	v_mul_f32_e32 v20, 0xbfb8aa3b, v16
	v_mul_f32_e32 v21, 0xbfb8aa3b, v17
	v_exp_f32_e32 v20, v20
	v_exp_f32_e32 v21, v21
	v_add_f32_e32 v18, 1.0, v22
	v_add_f32_e32 v19, 1.0, v23
	v_rcp_f32_e32 v18, v18
	v_rcp_f32_e32 v19, v19
	v_add_f32_e32 v20, 1.0, v20
	v_add_f32_e32 v21, 1.0, v21
	v_rcp_f32_e32 v20, v20
	v_rcp_f32_e32 v21, v21
	v_pk_mul_f32 v[14:15], v[14:15], v[18:19]
	v_pk_fma_f32 v[8:9], v[8:9], v[172:173], v[140:141] op_sel_hi:[1,0,1]
	v_pk_mul_f32 v[6:7], v[6:7], v[14:15]
	v_pk_mul_f32 v[14:15], v[16:17], v[20:21]
	v_mul_f32_e32 v16, 0xbfb8aa3b, v10
	v_mul_f32_e32 v17, 0xbfb8aa3b, v11
	v_exp_f32_e32 v16, v16
	v_exp_f32_e32 v17, v17
	v_pk_fma_f32 v[12:13], v[12:13], v[172:173], v[136:137] op_sel_hi:[1,0,1]
	v_pk_mul_f32 v[8:9], v[8:9], v[14:15]
	v_add_f32_e32 v14, 1.0, v16
	v_add_f32_e32 v15, 1.0, v17
	v_mul_f32_e32 v16, 0xbfb8aa3b, v12
	v_mul_f32_e32 v17, 0xbfb8aa3b, v13
	v_exp_f32_e32 v16, v16
	v_exp_f32_e32 v17, v17
	v_rcp_f32_e32 v14, v14
	v_rcp_f32_e32 v15, v15
	v_add_f32_e32 v16, 1.0, v16
	v_add_f32_e32 v17, 1.0, v17
	v_rcp_f32_e32 v16, v16
	v_rcp_f32_e32 v17, v17
	v_pk_mul_f32 v[10:11], v[10:11], v[14:15]
	v_pk_fma_f32 v[2:3], v[2:3], v[172:173], v[130:131] op_sel_hi:[1,0,1]
	v_pk_fma_f32 v[4:5], v[4:5], v[172:173], v[132:133] op_sel_hi:[1,0,1]
	v_pk_mul_f32 v[10:11], v[2:3], v[10:11]
	v_pk_mul_f32 v[2:3], v[12:13], v[16:17]
	s_nop 0
	v_pk_mul_f32 v[12:13], v[4:5], v[2:3]
	v_mad_i64_i32 v[2:3], s[18:19], v168, s56, v[166:167]
	v_lshl_add_u64 v[2:3], v[2:3], 0, s[16:17]
	v_lshl_add_u64 v[14:15], v[2:3], 0, v[154:155]
	v_cvt_pk_bf16_f32 v2, v6, v7
	v_cvt_pk_bf16_f32 v3, v8, v9
	v_cvt_pk_bf16_f32 v4, v10, v11
	v_cvt_pk_bf16_f32 v5, v12, v13
	s_mov_b32 s17, s8
	s_mov_b32 s16, s10
	global_store_dwordx4 v[14:15], v[2:5], off nt
	s_cbranch_vccz .LBB0_3262
	s_waitcnt vmcnt(0)
	s_cmpk_gt_u32 s33, 0xff
	s_cbranch_scc1 .LBB0_3269
	s_barrier
